# GEMM K-loops: counted lgkmcnt waits so each MFMA block starts as soon as its first fragments have landed
# speedup vs baseline: 1.0211x; 1.0105x over previous
; #define PG8_STAGE(bufoff, gbase, voff) do { _Pragma("unroll") for (int _i = 0; _i < 2; ++_i) \
;         __builtin_amdgcn_global_load_lds((const unsigned*)((const char*)(gbase) + (voff)[_i]), (LAS unsigned*)(lds + (bufoff) + ldsw + _i * 8192), 16, 0, 0); } while (0)
; #define PG8_LDA(dst, b, h) do { _Pragma("unroll") for (int m = 0; m < 4; ++m) _Pragma("unroll") for (int k = 0; k < 2; ++k) dst[m][k] = *(const LAS bf16x8*)(lds + PG8_SA(b, h) + aoff + m * 2048 + k * 1024); } while (0)
; #define PG8_LDB(dst, b, h) do { _Pragma("unroll") for (int n = 0; n < 2; ++n) _Pragma("unroll") for (int k = 0; k < 2; ++k) dst[n][k] = *(const LAS bf16x8*)(lds + PG8_SB(b, h) + boff + n * 2048 + k * 1024); } while (0)
; #define PG8_MMA(ai, bj, At, Bt) do { __builtin_amdgcn_s_setprio(1); _Pragma("unroll") for (int m = 0; m < 4; ++m) _Pragma("unroll") for (int n = 0; n < 2; ++n) _Pragma("unroll") for (int k = 0; k < 2; ++k) \
;         acc[ai][bj][m][n] = __builtin_amdgcn_mfma_f32_16x16x32_bf16(Bt[n][k], At[m][k], acc[ai][bj][m][n], 0, 0, 0); __builtin_amdgcn_s_setprio(0); } while (0)
; #define PG8_WAIT_L(n) asm volatile("s_waitcnt lgkmcnt(" #n ")" ::: "memory")
; #define PG8_BAR __builtin_amdgcn_s_barrier()
; #define PG8_SCHED __builtin_amdgcn_sched_barrier(0)
; template <class Epi, class Sched>
; DI void gemm_phase(LAS unsigned char* lds, const Gemm g, const Sched& S, const Epi& E) {
;     ...
;             PG8_LDB(B0, 0, 0); PG8_SCHED; PG8_LDA(At, 0, 0); PG8_STAGE(PG8_SA(1, 1), a1 + hstepA, voffA);
;             PG8_WAIT_L(8); PG8_BAR; PG8_WAIT_L(0); PG8_MMA(0, 0, At, B0); PG8_BAR; PG8_SCHED;
;             PG8_LDB(B1, 0, 1); PG8_STAGE(PG8_SB(0, 0), b2, voffB);
;             PG8_BAR; PG8_WAIT_L(0); PG8_MMA(0, 1, At, B1); PG8_BAR;
;             PG8_LDA(At, 0, 1); PG8_STAGE(PG8_SA(0, 0), a2, voffA);
;             PG8_BAR; PG8_WAIT_L(0); PG8_MMA(1, 0, At, B0); PG8_BAR; PG8_SCHED;
.LBB0_54:
	s_add_i32 s90, s6, 2
	s_add_u32 s56, s54, 0x100
	s_addc_u32 s57, s55, 0
	s_add_i32 s91, 0, 0x10000
	v_add_u32_e32 v142, s91, v156
	ds_read_b128 v[130:133], v142
	ds_read_b128 v[134:137], v142 offset:1024
	ds_read_b128 v[138:141], v142 offset:2048
	ds_read_b128 v[142:145], v142 offset:3072
	s_cmp_eq_u32 s80, s6
	s_cselect_b32 s6, s46, s88
	s_cselect_b32 s9, s45, s57
	s_cselect_b32 s8, s44, s56
	s_cselect_b32 s7, s47, s89
	v_lshl_add_u64 v[152:153], s[54:55], 0, v[150:151]
	s_add_i32 m0, s60, 0xc000
	ds_read_b128 v[158:161], v157
	ds_read_b128 v[162:165], v157 offset:1024
	ds_read_b128 v[168:171], v157 offset:2048
	ds_read_b128 v[172:175], v157 offset:3072
	ds_read_b128 v[176:179], v157 offset:4096
	ds_read_b128 v[196:199], v157 offset:5120
	ds_read_b128 v[200:203], v157 offset:6144
	ds_read_b128 v[204:207], v157 offset:7168
	global_load_lds_dwordx4 v[152:153], off
	v_lshl_add_u64 v[152:153], s[54:55], 0, v[148:149]
	s_add_i32 m0, s60, 0xe000
	s_nop 0
	global_load_lds_dwordx4 v[152:153], off
	s_waitcnt lgkmcnt(8)
	s_barrier
	s_setprio 1
	s_waitcnt lgkmcnt(7)
	v_mfma_f32_16x16x32_bf16 v[126:129], v[130:133], v[158:161], v[126:129]
	v_mfma_f32_16x16x32_bf16 v[122:125], v[138:141], v[158:161], v[122:125]
	s_waitcnt lgkmcnt(5)
	v_mfma_f32_16x16x32_bf16 v[110:113], v[130:133], v[168:171], v[110:113]
	v_mfma_f32_16x16x32_bf16 v[106:109], v[138:141], v[168:171], v[106:109]
	s_waitcnt lgkmcnt(3)
	v_mfma_f32_16x16x32_bf16 v[92:95], v[130:133], v[176:179], v[92:95]
	v_mfma_f32_16x16x32_bf16 v[88:91], v[138:141], v[176:179], v[88:91]
	s_waitcnt lgkmcnt(1)
	v_mfma_f32_16x16x32_bf16 v[76:79], v[130:133], v[200:203], v[76:79]
	v_mfma_f32_16x16x32_bf16 v[72:75], v[138:141], v[200:203], v[72:75]
	v_mfma_f32_16x16x32_bf16 v[126:129], v[134:137], v[162:165], v[126:129]
	v_mfma_f32_16x16x32_bf16 v[122:125], v[142:145], v[162:165], v[122:125]
	v_mfma_f32_16x16x32_bf16 v[110:113], v[134:137], v[172:175], v[110:113]
	v_mfma_f32_16x16x32_bf16 v[106:109], v[142:145], v[172:175], v[106:109]
	v_mfma_f32_16x16x32_bf16 v[92:95], v[134:137], v[196:199], v[92:95]
	v_mfma_f32_16x16x32_bf16 v[88:91], v[142:145], v[196:199], v[88:91]
	s_waitcnt lgkmcnt(0)
	v_mfma_f32_16x16x32_bf16 v[76:79], v[134:137], v[204:207], v[76:79]
	v_mfma_f32_16x16x32_bf16 v[72:75], v[142:145], v[204:207], v[72:75]
	s_setprio 0
	s_barrier
	s_add_i32 s92, 0, 0x14000
	v_add_u32_e32 v152, s92, v156
	s_add_i32 s54, s91, s76
	ds_read_b128 v[208:211], v152
	ds_read_b128 v[212:215], v152 offset:1024
	ds_read_b128 v[216:219], v152 offset:2048
	ds_read_b128 v[220:223], v152 offset:3072
	v_lshl_add_u64 v[152:153], s[6:7], 0, v[96:97]
	s_mov_b32 m0, s54
	v_lshl_add_u64 v[180:181], s[6:7], 0, v[146:147]
	global_load_lds_dwordx4 v[152:153], off
	s_add_i32 m0, s54, 0x2000
	s_nop 0
	global_load_lds_dwordx4 v[180:181], off
	s_barrier
	s_setprio 1
	s_waitcnt lgkmcnt(3)
	v_mfma_f32_16x16x32_bf16 v[118:121], v[208:211], v[158:161], v[118:121]
	s_waitcnt lgkmcnt(1)
	v_mfma_f32_16x16x32_bf16 v[114:117], v[216:219], v[158:161], v[114:117]
	v_mfma_f32_16x16x32_bf16 v[102:105], v[208:211], v[168:171], v[102:105]
	v_mfma_f32_16x16x32_bf16 v[98:101], v[216:219], v[168:171], v[98:101]
	v_mfma_f32_16x16x32_bf16 v[84:87], v[208:211], v[176:179], v[84:87]
	v_mfma_f32_16x16x32_bf16 v[80:83], v[216:219], v[176:179], v[80:83]
	v_mfma_f32_16x16x32_bf16 v[68:71], v[208:211], v[200:203], v[68:71]
	v_mfma_f32_16x16x32_bf16 v[64:67], v[216:219], v[200:203], v[64:67]
	v_mfma_f32_16x16x32_bf16 v[118:121], v[212:215], v[162:165], v[118:121]
	s_waitcnt lgkmcnt(0)
	v_mfma_f32_16x16x32_bf16 v[114:117], v[220:223], v[162:165], v[114:117]
	v_mfma_f32_16x16x32_bf16 v[102:105], v[212:215], v[172:175], v[102:105]
	v_mfma_f32_16x16x32_bf16 v[98:101], v[220:223], v[172:175], v[98:101]
	v_mfma_f32_16x16x32_bf16 v[84:87], v[212:215], v[196:199], v[84:87]
	v_mfma_f32_16x16x32_bf16 v[80:83], v[220:223], v[196:199], v[80:83]
	v_mfma_f32_16x16x32_bf16 v[68:71], v[212:215], v[204:207], v[68:71]
	v_mfma_f32_16x16x32_bf16 v[64:67], v[220:223], v[204:207], v[64:67]
	s_setprio 0
	s_mov_b32 m0, s60
	v_lshl_add_u64 v[224:225], s[8:9], 0, v[96:97]
	s_barrier
	ds_read_b128 v[158:161], v157 offset:16384
	ds_read_b128 v[162:165], v157 offset:17408
	ds_read_b128 v[168:171], v157 offset:18432
	ds_read_b128 v[172:175], v157 offset:19456
	ds_read_b128 v[176:179], v157 offset:20480
	ds_read_b128 v[196:199], v157 offset:21504
	ds_read_b128 v[200:203], v157 offset:22528
	ds_read_b128 v[204:207], v157 offset:23552
	global_load_lds_dwordx4 v[224:225], off
	v_lshl_add_u64 v[226:227], s[8:9], 0, v[146:147]
	s_mov_b32 m0, s61
	s_nop 0
	global_load_lds_dwordx4 v[226:227], off
	s_barrier
	s_setprio 1
	s_waitcnt lgkmcnt(7)
	v_mfma_f32_16x16x32_bf16 v[60:63], v[130:133], v[158:161], v[60:63]
	v_mfma_f32_16x16x32_bf16 v[56:59], v[138:141], v[158:161], v[56:59]
	s_waitcnt lgkmcnt(5)
	v_mfma_f32_16x16x32_bf16 v[44:47], v[130:133], v[168:171], v[44:47]
	v_mfma_f32_16x16x32_bf16 v[40:43], v[138:141], v[168:171], v[40:43]
	s_waitcnt lgkmcnt(3)
	v_mfma_f32_16x16x32_bf16 v[28:31], v[130:133], v[176:179], v[28:31]
	v_mfma_f32_16x16x32_bf16 v[24:27], v[138:141], v[176:179], v[24:27]
	s_waitcnt lgkmcnt(1)
	v_mfma_f32_16x16x32_bf16 v[12:15], v[130:133], v[200:203], v[12:15]
	v_mfma_f32_16x16x32_bf16 v[8:11], v[138:141], v[200:203], v[8:11]
	v_mfma_f32_16x16x32_bf16 v[60:63], v[134:137], v[162:165], v[60:63]
	v_mfma_f32_16x16x32_bf16 v[56:59], v[142:145], v[162:165], v[56:59]
	v_mfma_f32_16x16x32_bf16 v[44:47], v[134:137], v[172:175], v[44:47]
	v_mfma_f32_16x16x32_bf16 v[40:43], v[142:145], v[172:175], v[40:43]
	v_mfma_f32_16x16x32_bf16 v[28:31], v[134:137], v[196:199], v[28:31]
	v_mfma_f32_16x16x32_bf16 v[24:27], v[142:145], v[196:199], v[24:27]
	s_waitcnt lgkmcnt(0)
	v_mfma_f32_16x16x32_bf16 v[12:15], v[134:137], v[204:207], v[12:15]
	v_mfma_f32_16x16x32_bf16 v[8:11], v[142:145], v[204:207], v[8:11]
	s_setprio 0
	s_barrier
; #define PG8_STAGE(bufoff, gbase, voff) do { _Pragma("unroll") for (int _i = 0; _i < 2; ++_i) \
;         __builtin_amdgcn_global_load_lds((const unsigned*)((const char*)(gbase) + (voff)[_i]), (LAS unsigned*)(lds + (bufoff) + ldsw + _i * 8192), 16, 0, 0); } while (0)
; #define PG8_LDA(dst, b, h) do { _Pragma("unroll") for (int m = 0; m < 4; ++m) _Pragma("unroll") for (int k = 0; k < 2; ++k) dst[m][k] = *(const LAS bf16x8*)(lds + PG8_SA(b, h) + aoff + m * 2048 + k * 1024); } while (0)
; #define PG8_LDB(dst, b, h) do { _Pragma("unroll") for (int n = 0; n < 2; ++n) _Pragma("unroll") for (int k = 0; k < 2; ++k) dst[n][k] = *(const LAS bf16x8*)(lds + PG8_SB(b, h) + boff + n * 2048 + k * 1024); } while (0)
; #define PG8_MMA(ai, bj, At, Bt) do { __builtin_amdgcn_s_setprio(1); _Pragma("unroll") for (int m = 0; m < 4; ++m) _Pragma("unroll") for (int n = 0; n < 2; ++n) _Pragma("unroll") for (int k = 0; k < 2; ++k) \
;         acc[ai][bj][m][n] = __builtin_amdgcn_mfma_f32_16x16x32_bf16(Bt[n][k], At[m][k], acc[ai][bj][m][n], 0, 0, 0); __builtin_amdgcn_s_setprio(0); } while (0)
; #define PG8_WAIT_V(n) asm volatile("s_waitcnt vmcnt(" #n ")" ::: "memory")
; #define PG8_WAIT_L(n) asm volatile("s_waitcnt lgkmcnt(" #n ")" ::: "memory")
; #define PG8_BAR __builtin_amdgcn_s_barrier()
; #define PG8_SCHED __builtin_amdgcn_sched_barrier(0)
; template <class Epi, class Sched>
; DI void gemm_phase(LAS unsigned char* lds, const Gemm g, const Sched& S, const Epi& E) {
;     ...
;             PG8_STAGE(PG8_SB(0, 1), b2 + hstepB, voffB);
;             PG8_WAIT_V(6); PG8_BAR; PG8_MMA(1, 1, At, B1); PG8_BAR;
;             PG8_LDB(B0, 1, 0); PG8_SCHED; PG8_LDA(At, 1, 0); PG8_STAGE(PG8_SA(0, 1), a2 + hstepA, voffA);
;             PG8_WAIT_L(8); PG8_BAR; PG8_WAIT_L(0); PG8_MMA(0, 0, At, B0); PG8_BAR; PG8_SCHED;
;             PG8_LDB(B1, 1, 1); PG8_STAGE(PG8_SB(1, 0), b3, voffB);
	s_add_u32 s54, s6, 0x204000
	s_addc_u32 s55, s7, 0
	s_add_i32 s91, s92, s76
	v_lshl_add_u64 v[130:131], s[54:55], 0, v[96:97]
	s_mov_b32 m0, s91
	s_nop 0
	global_load_lds_dwordx4 v[130:131], off
	v_lshl_add_u64 v[130:131], s[54:55], 0, v[146:147]
	s_add_i32 m0, s91, 0x2000
	s_nop 0
	global_load_lds_dwordx4 v[130:131], off
	s_waitcnt vmcnt(6)
	s_barrier
	s_setprio 1
	v_mfma_f32_16x16x32_bf16 v[52:55], v[208:211], v[158:161], v[52:55]
	v_mfma_f32_16x16x32_bf16 v[48:51], v[216:219], v[158:161], v[48:51]
	v_mfma_f32_16x16x32_bf16 v[36:39], v[208:211], v[168:171], v[36:39]
	v_mfma_f32_16x16x32_bf16 v[32:35], v[216:219], v[168:171], v[32:35]
	v_mfma_f32_16x16x32_bf16 v[20:23], v[208:211], v[176:179], v[20:23]
	v_mfma_f32_16x16x32_bf16 v[16:19], v[216:219], v[176:179], v[16:19]
	v_mfma_f32_16x16x32_bf16 v[4:7], v[208:211], v[200:203], v[4:7]
	v_mfma_f32_16x16x32_bf16 v[0:3], v[216:219], v[200:203], v[0:3]
	v_mfma_f32_16x16x32_bf16 v[52:55], v[212:215], v[162:165], v[52:55]
	v_mfma_f32_16x16x32_bf16 v[48:51], v[220:223], v[162:165], v[48:51]
	v_mfma_f32_16x16x32_bf16 v[36:39], v[212:215], v[172:175], v[36:39]
	v_mfma_f32_16x16x32_bf16 v[32:35], v[220:223], v[172:175], v[32:35]
	v_mfma_f32_16x16x32_bf16 v[20:23], v[212:215], v[196:199], v[20:23]
	v_mfma_f32_16x16x32_bf16 v[16:19], v[220:223], v[196:199], v[16:19]
	v_mfma_f32_16x16x32_bf16 v[4:7], v[212:215], v[204:207], v[4:7]
	v_mfma_f32_16x16x32_bf16 v[0:3], v[220:223], v[204:207], v[0:3]
	s_setprio 0
	s_add_i32 s54, 0, 0x18000
	v_add_u32_e32 v142, s54, v156
	s_barrier
	ds_read_b128 v[130:133], v142
	ds_read_b128 v[134:137], v142 offset:1024
	ds_read_b128 v[138:141], v142 offset:2048
	ds_read_b128 v[142:145], v142 offset:3072
	s_add_u32 s8, s8, 0x204000
	s_addc_u32 s9, s9, 0
	s_mov_b32 m0, s82
	v_lshl_add_u64 v[208:209], s[8:9], 0, v[96:97]
	ds_read_b128 v[158:161], v157 offset:32768
	ds_read_b128 v[162:165], v157 offset:33792
	ds_read_b128 v[168:171], v157 offset:34816
	ds_read_b128 v[172:175], v157 offset:35840
	ds_read_b128 v[176:179], v157 offset:36864
	ds_read_b128 v[196:199], v157 offset:37888
	ds_read_b128 v[200:203], v157 offset:38912
	ds_read_b128 v[204:207], v157 offset:39936
	global_load_lds_dwordx4 v[208:209], off
	v_lshl_add_u64 v[208:209], s[8:9], 0, v[146:147]
	s_mov_b32 m0, s27
	s_nop 0
	global_load_lds_dwordx4 v[208:209], off
	s_waitcnt lgkmcnt(8)
	s_barrier
	s_setprio 1
	s_waitcnt lgkmcnt(7)
	v_mfma_f32_16x16x32_bf16 v[126:129], v[130:133], v[158:161], v[126:129]
	v_mfma_f32_16x16x32_bf16 v[122:125], v[138:141], v[158:161], v[122:125]
	s_waitcnt lgkmcnt(5)
	v_mfma_f32_16x16x32_bf16 v[110:113], v[130:133], v[168:171], v[110:113]
	v_mfma_f32_16x16x32_bf16 v[106:109], v[138:141], v[168:171], v[106:109]
	s_waitcnt lgkmcnt(3)
	v_mfma_f32_16x16x32_bf16 v[92:95], v[130:133], v[176:179], v[92:95]
	v_mfma_f32_16x16x32_bf16 v[88:91], v[138:141], v[176:179], v[88:91]
	s_waitcnt lgkmcnt(1)
	v_mfma_f32_16x16x32_bf16 v[76:79], v[130:133], v[200:203], v[76:79]
	v_mfma_f32_16x16x32_bf16 v[72:75], v[138:141], v[200:203], v[72:75]
	v_mfma_f32_16x16x32_bf16 v[126:129], v[134:137], v[162:165], v[126:129]
	v_mfma_f32_16x16x32_bf16 v[122:125], v[142:145], v[162:165], v[122:125]
	v_mfma_f32_16x16x32_bf16 v[110:113], v[134:137], v[172:175], v[110:113]
	v_mfma_f32_16x16x32_bf16 v[106:109], v[142:145], v[172:175], v[106:109]
	v_mfma_f32_16x16x32_bf16 v[92:95], v[134:137], v[196:199], v[92:95]
	v_mfma_f32_16x16x32_bf16 v[88:91], v[142:145], v[196:199], v[88:91]
	s_waitcnt lgkmcnt(0)
	v_mfma_f32_16x16x32_bf16 v[76:79], v[134:137], v[204:207], v[76:79]
	v_mfma_f32_16x16x32_bf16 v[72:75], v[142:145], v[204:207], v[72:75]
	s_setprio 0
	s_barrier
	s_add_i32 s8, 0, 0x1c000
	s_add_i32 s9, s54, s76
	v_add_u32_e32 v182, s8, v156
	v_lshl_add_u64 v[152:153], v[152:153], 0, s[28:29]
	s_mov_b32 m0, s9
	ds_read_b128 v[208:211], v182
	ds_read_b128 v[212:215], v182 offset:1024
	ds_read_b128 v[216:219], v182 offset:2048
	ds_read_b128 v[220:223], v182 offset:3072
	global_load_lds_dwordx4 v[152:153], off
	v_lshl_add_u64 v[152:153], v[180:181], 0, s[28:29]
	s_add_i32 m0, s9, 0x2000
	s_nop 0
	global_load_lds_dwordx4 v[152:153], off
	s_barrier
; #define PG8_STAGE(bufoff, gbase, voff) do { _Pragma("unroll") for (int _i = 0; _i < 2; ++_i) \
;         __builtin_amdgcn_global_load_lds((const unsigned*)((const char*)(gbase) + (voff)[_i]), (LAS unsigned*)(lds + (bufoff) + ldsw + _i * 8192), 16, 0, 0); } while (0)
; #define PG8_LDA(dst, b, h) do { _Pragma("unroll") for (int m = 0; m < 4; ++m) _Pragma("unroll") for (int k = 0; k < 2; ++k) dst[m][k] = *(const LAS bf16x8*)(lds + PG8_SA(b, h) + aoff + m * 2048 + k * 1024); } while (0)
; #define PG8_MMA(ai, bj, At, Bt) do { __builtin_amdgcn_s_setprio(1); _Pragma("unroll") for (int m = 0; m < 4; ++m) _Pragma("unroll") for (int n = 0; n < 2; ++n) _Pragma("unroll") for (int k = 0; k < 2; ++k) \
;         acc[ai][bj][m][n] = __builtin_amdgcn_mfma_f32_16x16x32_bf16(Bt[n][k], At[m][k], acc[ai][bj][m][n], 0, 0, 0); __builtin_amdgcn_s_setprio(0); } while (0)
; #define PG8_WAIT_V(n) asm volatile("s_waitcnt vmcnt(" #n ")" ::: "memory")
; #define PG8_WAIT_L(n) asm volatile("s_waitcnt lgkmcnt(" #n ")" ::: "memory")
; #define PG8_BAR __builtin_amdgcn_s_barrier()
; #define PG8_SCHED __builtin_amdgcn_sched_barrier(0)
; template <class Epi, class Sched>
; DI void gemm_phase(LAS unsigned char* lds, const Gemm g, const Sched& S, const Epi& E) {
;     ...
;             PG8_BAR; PG8_WAIT_L(0); PG8_MMA(0, 1, At, B1); PG8_BAR;
;             PG8_LDA(At, 1, 1); PG8_STAGE(PG8_SA(1, 0), a3, voffA);
;             PG8_BAR; PG8_WAIT_L(0); PG8_MMA(1, 0, At, B0); PG8_BAR; PG8_SCHED;
;             PG8_STAGE(PG8_SB(1, 1), b3 + hstepB, voffB);
;             PG8_WAIT_V(6); PG8_BAR; PG8_MMA(1, 1, At, B1); PG8_BAR;
;         }
	s_setprio 1
	s_waitcnt lgkmcnt(3)
	v_mfma_f32_16x16x32_bf16 v[118:121], v[208:211], v[158:161], v[118:121]
	s_waitcnt lgkmcnt(1)
	v_mfma_f32_16x16x32_bf16 v[114:117], v[216:219], v[158:161], v[114:117]
	v_mfma_f32_16x16x32_bf16 v[102:105], v[208:211], v[168:171], v[102:105]
	v_mfma_f32_16x16x32_bf16 v[98:101], v[216:219], v[168:171], v[98:101]
	v_mfma_f32_16x16x32_bf16 v[84:87], v[208:211], v[176:179], v[84:87]
	v_mfma_f32_16x16x32_bf16 v[80:83], v[216:219], v[176:179], v[80:83]
	v_mfma_f32_16x16x32_bf16 v[68:71], v[208:211], v[200:203], v[68:71]
	v_mfma_f32_16x16x32_bf16 v[64:67], v[216:219], v[200:203], v[64:67]
	v_mfma_f32_16x16x32_bf16 v[118:121], v[212:215], v[162:165], v[118:121]
	s_waitcnt lgkmcnt(0)
	v_mfma_f32_16x16x32_bf16 v[114:117], v[220:223], v[162:165], v[114:117]
	v_mfma_f32_16x16x32_bf16 v[102:105], v[212:215], v[172:175], v[102:105]
	v_mfma_f32_16x16x32_bf16 v[98:101], v[220:223], v[172:175], v[98:101]
	v_mfma_f32_16x16x32_bf16 v[84:87], v[212:215], v[196:199], v[84:87]
	v_mfma_f32_16x16x32_bf16 v[80:83], v[220:223], v[196:199], v[80:83]
	v_mfma_f32_16x16x32_bf16 v[68:71], v[212:215], v[204:207], v[68:71]
	v_mfma_f32_16x16x32_bf16 v[64:67], v[220:223], v[204:207], v[64:67]
	s_setprio 0
	s_mov_b32 m0, s84
	v_lshl_add_u64 v[152:153], v[224:225], 0, s[28:29]
	s_barrier
	ds_read_b128 v[158:161], v157 offset:49152
	ds_read_b128 v[162:165], v157 offset:50176
	ds_read_b128 v[168:171], v157 offset:51200
	ds_read_b128 v[172:175], v157 offset:52224
	ds_read_b128 v[176:179], v157 offset:53248
	ds_read_b128 v[196:199], v157 offset:54272
	ds_read_b128 v[200:203], v157 offset:55296
	ds_read_b128 v[204:207], v157 offset:56320
	global_load_lds_dwordx4 v[152:153], off
	v_lshl_add_u64 v[152:153], v[226:227], 0, s[28:29]
	s_mov_b32 m0, s85
	s_nop 0
	global_load_lds_dwordx4 v[152:153], off
	s_barrier
	s_setprio 1
	s_waitcnt lgkmcnt(7)
	v_mfma_f32_16x16x32_bf16 v[60:63], v[130:133], v[158:161], v[60:63]
	v_mfma_f32_16x16x32_bf16 v[56:59], v[138:141], v[158:161], v[56:59]
	s_waitcnt lgkmcnt(5)
	v_mfma_f32_16x16x32_bf16 v[44:47], v[130:133], v[168:171], v[44:47]
	v_mfma_f32_16x16x32_bf16 v[40:43], v[138:141], v[168:171], v[40:43]
	s_waitcnt lgkmcnt(3)
	v_mfma_f32_16x16x32_bf16 v[28:31], v[130:133], v[176:179], v[28:31]
	v_mfma_f32_16x16x32_bf16 v[24:27], v[138:141], v[176:179], v[24:27]
	s_waitcnt lgkmcnt(1)
	v_mfma_f32_16x16x32_bf16 v[12:15], v[130:133], v[200:203], v[12:15]
	v_mfma_f32_16x16x32_bf16 v[8:11], v[138:141], v[200:203], v[8:11]
	v_mfma_f32_16x16x32_bf16 v[60:63], v[134:137], v[162:165], v[60:63]
	v_mfma_f32_16x16x32_bf16 v[56:59], v[142:145], v[162:165], v[56:59]
	v_mfma_f32_16x16x32_bf16 v[44:47], v[134:137], v[172:175], v[44:47]
	v_mfma_f32_16x16x32_bf16 v[40:43], v[142:145], v[172:175], v[40:43]
	v_mfma_f32_16x16x32_bf16 v[28:31], v[134:137], v[196:199], v[28:31]
	v_mfma_f32_16x16x32_bf16 v[24:27], v[142:145], v[196:199], v[24:27]
	s_waitcnt lgkmcnt(0)
	v_mfma_f32_16x16x32_bf16 v[12:15], v[134:137], v[204:207], v[12:15]
	v_mfma_f32_16x16x32_bf16 v[8:11], v[142:145], v[204:207], v[8:11]
	s_setprio 0
	s_barrier
	s_add_u32 s6, s6, 0x204080
	s_addc_u32 s7, s7, 0
	s_add_i32 s8, s8, s76
	v_lshl_add_u64 v[130:131], s[6:7], 0, v[96:97]
	s_mov_b32 m0, s8
	s_nop 0
	global_load_lds_dwordx4 v[130:131], off
	v_lshl_add_u64 v[130:131], s[6:7], 0, v[146:147]
	s_add_i32 m0, s8, 0x2000
	s_nop 0
	global_load_lds_dwordx4 v[130:131], off
	s_waitcnt vmcnt(6)
	s_barrier
	s_setprio 1
	v_mfma_f32_16x16x32_bf16 v[52:55], v[208:211], v[158:161], v[52:55]
	v_mfma_f32_16x16x32_bf16 v[48:51], v[216:219], v[158:161], v[48:51]
	v_mfma_f32_16x16x32_bf16 v[36:39], v[208:211], v[168:171], v[36:39]
	v_mfma_f32_16x16x32_bf16 v[32:35], v[216:219], v[168:171], v[32:35]
	v_mfma_f32_16x16x32_bf16 v[20:23], v[208:211], v[176:179], v[20:23]
	v_mfma_f32_16x16x32_bf16 v[16:19], v[216:219], v[176:179], v[16:19]
	v_mfma_f32_16x16x32_bf16 v[4:7], v[208:211], v[200:203], v[4:7]
	v_mfma_f32_16x16x32_bf16 v[0:3], v[216:219], v[200:203], v[0:3]
	v_mfma_f32_16x16x32_bf16 v[52:55], v[212:215], v[162:165], v[52:55]
	v_mfma_f32_16x16x32_bf16 v[48:51], v[220:223], v[162:165], v[48:51]
	v_mfma_f32_16x16x32_bf16 v[36:39], v[212:215], v[172:175], v[36:39]
	v_mfma_f32_16x16x32_bf16 v[32:35], v[220:223], v[172:175], v[32:35]
	v_mfma_f32_16x16x32_bf16 v[20:23], v[212:215], v[196:199], v[20:23]
	v_mfma_f32_16x16x32_bf16 v[16:19], v[220:223], v[196:199], v[16:19]
	v_mfma_f32_16x16x32_bf16 v[4:7], v[212:215], v[204:207], v[4:7]
	v_mfma_f32_16x16x32_bf16 v[0:3], v[220:223], v[204:207], v[0:3]
	s_setprio 0
	s_add_u32 s88, s88, 0x100
	s_addc_u32 s89, s89, 0
	s_cmp_ge_i32 s90, s24
	s_mov_b64 s[54:55], s[56:57]
	s_mov_b32 s6, s90
	s_barrier
	s_cbranch_scc0 .LBB0_54
	s_branch .LBB0_41

; #define PG8_STAGE(bufoff, gbase, voff) do { _Pragma("unroll") for (int _i = 0; _i < 2; ++_i) \
;         __builtin_amdgcn_global_load_lds((const unsigned*)((const char*)(gbase) + (voff)[_i]), (LAS unsigned*)(lds + (bufoff) + ldsw + _i * 8192), 16, 0, 0); } while (0)
; #define PG8_LDA(dst, b, h) do { _Pragma("unroll") for (int m = 0; m < 4; ++m) _Pragma("unroll") for (int k = 0; k < 2; ++k) dst[m][k] = *(const LAS bf16x8*)(lds + PG8_SA(b, h) + aoff + m * 2048 + k * 1024); } while (0)
; #define PG8_LDB(dst, b, h) do { _Pragma("unroll") for (int n = 0; n < 2; ++n) _Pragma("unroll") for (int k = 0; k < 2; ++k) dst[n][k] = *(const LAS bf16x8*)(lds + PG8_SB(b, h) + boff + n * 2048 + k * 1024); } while (0)
; #define PG8_MMA(ai, bj, At, Bt) do { __builtin_amdgcn_s_setprio(1); _Pragma("unroll") for (int m = 0; m < 4; ++m) _Pragma("unroll") for (int n = 0; n < 2; ++n) _Pragma("unroll") for (int k = 0; k < 2; ++k) \
;         acc[ai][bj][m][n] = __builtin_amdgcn_mfma_f32_16x16x32_bf16(Bt[n][k], At[m][k], acc[ai][bj][m][n], 0, 0, 0); __builtin_amdgcn_s_setprio(0); } while (0)
; #define PG8_WAIT_L(n) asm volatile("s_waitcnt lgkmcnt(" #n ")" ::: "memory")
; #define PG8_BAR __builtin_amdgcn_s_barrier()
; #define PG8_SCHED __builtin_amdgcn_sched_barrier(0)
; template <class Epi, class Sched>
; DI void gemm_phase(LAS unsigned char* lds, const Gemm g, const Sched& S, const Epi& E) {
;     ...
;             PG8_LDB(B0, 0, 0); PG8_SCHED; PG8_LDA(At, 0, 0); PG8_STAGE(PG8_SA(1, 1), a1 + hstepA, voffA);
;             PG8_WAIT_L(8); PG8_BAR; PG8_WAIT_L(0); PG8_MMA(0, 0, At, B0); PG8_BAR; PG8_SCHED;
;             PG8_LDB(B1, 0, 1); PG8_STAGE(PG8_SB(0, 0), b2, voffB);
;             PG8_BAR; PG8_WAIT_L(0); PG8_MMA(0, 1, At, B1); PG8_BAR;
;             PG8_LDA(At, 0, 1); PG8_STAGE(PG8_SA(0, 0), a2, voffA);
;             PG8_BAR; PG8_WAIT_L(0); PG8_MMA(1, 0, At, B0); PG8_BAR; PG8_SCHED;
.LBB0_79:
	s_add_i32 s74, s6, 2
	s_add_u32 s68, s56, 0x100
	s_addc_u32 s69, s57, 0
	s_add_i32 s75, 0, 0x10000
	v_add_u32_e32 v142, s75, v160
	ds_read_b128 v[130:133], v142
	ds_read_b128 v[134:137], v142 offset:1024
	ds_read_b128 v[138:141], v142 offset:2048
	ds_read_b128 v[142:145], v142 offset:3072
	s_cmp_eq_u32 s96, s6
	s_cselect_b32 s6, s46, s11
	s_cselect_b32 s9, s45, s69
	s_cselect_b32 s8, s44, s68
	s_cselect_b32 s7, s47, s31
	v_lshl_add_u64 v[156:157], s[56:57], 0, v[150:151]
	s_add_i32 m0, s92, 0xc000
	ds_read_b128 v[152:155], v161
	ds_read_b128 v[162:165], v161 offset:1024
	ds_read_b128 v[168:171], v161 offset:2048
	ds_read_b128 v[172:175], v161 offset:3072
	ds_read_b128 v[176:179], v161 offset:4096
	ds_read_b128 v[196:199], v161 offset:5120
	ds_read_b128 v[200:203], v161 offset:6144
	ds_read_b128 v[204:207], v161 offset:7168
	global_load_lds_dwordx4 v[156:157], off
	v_lshl_add_u64 v[156:157], s[56:57], 0, v[148:149]
	s_add_i32 m0, s92, 0xe000
	s_nop 0
	global_load_lds_dwordx4 v[156:157], off
	s_waitcnt lgkmcnt(8)
	s_barrier
	s_setprio 1
	s_waitcnt lgkmcnt(7)
	v_mfma_f32_16x16x32_bf16 v[126:129], v[130:133], v[152:155], v[126:129]
	v_mfma_f32_16x16x32_bf16 v[122:125], v[138:141], v[152:155], v[122:125]
	s_waitcnt lgkmcnt(5)
	v_mfma_f32_16x16x32_bf16 v[110:113], v[130:133], v[168:171], v[110:113]
	v_mfma_f32_16x16x32_bf16 v[106:109], v[138:141], v[168:171], v[106:109]
	s_waitcnt lgkmcnt(3)
	v_mfma_f32_16x16x32_bf16 v[92:95], v[130:133], v[176:179], v[92:95]
	v_mfma_f32_16x16x32_bf16 v[88:91], v[138:141], v[176:179], v[88:91]
	s_waitcnt lgkmcnt(1)
	v_mfma_f32_16x16x32_bf16 v[76:79], v[130:133], v[200:203], v[76:79]
	v_mfma_f32_16x16x32_bf16 v[72:75], v[138:141], v[200:203], v[72:75]
	v_mfma_f32_16x16x32_bf16 v[126:129], v[134:137], v[162:165], v[126:129]
	v_mfma_f32_16x16x32_bf16 v[122:125], v[142:145], v[162:165], v[122:125]
	v_mfma_f32_16x16x32_bf16 v[110:113], v[134:137], v[172:175], v[110:113]
	v_mfma_f32_16x16x32_bf16 v[106:109], v[142:145], v[172:175], v[106:109]
	v_mfma_f32_16x16x32_bf16 v[92:95], v[134:137], v[196:199], v[92:95]
	v_mfma_f32_16x16x32_bf16 v[88:91], v[142:145], v[196:199], v[88:91]
	s_waitcnt lgkmcnt(0)
	v_mfma_f32_16x16x32_bf16 v[76:79], v[134:137], v[204:207], v[76:79]
	v_mfma_f32_16x16x32_bf16 v[72:75], v[142:145], v[204:207], v[72:75]
	s_setprio 0
	s_barrier
	s_add_i32 s81, 0, 0x14000
	v_add_u32_e32 v156, s81, v160
	s_add_i32 s56, s75, s89
	ds_read_b128 v[208:211], v156
	ds_read_b128 v[212:215], v156 offset:1024
	ds_read_b128 v[216:219], v156 offset:2048
	ds_read_b128 v[220:223], v156 offset:3072
	v_lshl_add_u64 v[156:157], s[6:7], 0, v[96:97]
	s_mov_b32 m0, s56
	v_lshl_add_u64 v[180:181], s[6:7], 0, v[146:147]
	global_load_lds_dwordx4 v[156:157], off
	s_add_i32 m0, s56, 0x2000
	s_nop 0
	global_load_lds_dwordx4 v[180:181], off
	s_barrier
	s_setprio 1
	s_waitcnt lgkmcnt(3)
	v_mfma_f32_16x16x32_bf16 v[118:121], v[208:211], v[152:155], v[118:121]
	s_waitcnt lgkmcnt(1)
	v_mfma_f32_16x16x32_bf16 v[114:117], v[216:219], v[152:155], v[114:117]
	v_mfma_f32_16x16x32_bf16 v[102:105], v[208:211], v[168:171], v[102:105]
	v_mfma_f32_16x16x32_bf16 v[98:101], v[216:219], v[168:171], v[98:101]
	v_mfma_f32_16x16x32_bf16 v[84:87], v[208:211], v[176:179], v[84:87]
	v_mfma_f32_16x16x32_bf16 v[80:83], v[216:219], v[176:179], v[80:83]
	v_mfma_f32_16x16x32_bf16 v[68:71], v[208:211], v[200:203], v[68:71]
	v_mfma_f32_16x16x32_bf16 v[64:67], v[216:219], v[200:203], v[64:67]
	v_mfma_f32_16x16x32_bf16 v[118:121], v[212:215], v[162:165], v[118:121]
	s_waitcnt lgkmcnt(0)
	v_mfma_f32_16x16x32_bf16 v[114:117], v[220:223], v[162:165], v[114:117]
	v_mfma_f32_16x16x32_bf16 v[102:105], v[212:215], v[172:175], v[102:105]
	v_mfma_f32_16x16x32_bf16 v[98:101], v[220:223], v[172:175], v[98:101]
	v_mfma_f32_16x16x32_bf16 v[84:87], v[212:215], v[196:199], v[84:87]
	v_mfma_f32_16x16x32_bf16 v[80:83], v[220:223], v[196:199], v[80:83]
	v_mfma_f32_16x16x32_bf16 v[68:71], v[212:215], v[204:207], v[68:71]
	v_mfma_f32_16x16x32_bf16 v[64:67], v[220:223], v[204:207], v[64:67]
	s_setprio 0
	s_mov_b32 m0, s92
	v_lshl_add_u64 v[224:225], s[8:9], 0, v[96:97]
	s_barrier
	ds_read_b128 v[152:155], v161 offset:16384
	ds_read_b128 v[162:165], v161 offset:17408
	ds_read_b128 v[168:171], v161 offset:18432
	ds_read_b128 v[172:175], v161 offset:19456
	ds_read_b128 v[176:179], v161 offset:20480
	ds_read_b128 v[196:199], v161 offset:21504
	ds_read_b128 v[200:203], v161 offset:22528
	ds_read_b128 v[204:207], v161 offset:23552
	global_load_lds_dwordx4 v[224:225], off
	v_lshl_add_u64 v[226:227], s[8:9], 0, v[146:147]
	s_mov_b32 m0, s73
	s_nop 0
	global_load_lds_dwordx4 v[226:227], off
	s_barrier
	s_setprio 1
	s_waitcnt lgkmcnt(7)
	v_mfma_f32_16x16x32_bf16 v[60:63], v[130:133], v[152:155], v[60:63]
	v_mfma_f32_16x16x32_bf16 v[56:59], v[138:141], v[152:155], v[56:59]
	s_waitcnt lgkmcnt(5)
	v_mfma_f32_16x16x32_bf16 v[44:47], v[130:133], v[168:171], v[44:47]
	v_mfma_f32_16x16x32_bf16 v[40:43], v[138:141], v[168:171], v[40:43]
	s_waitcnt lgkmcnt(3)
	v_mfma_f32_16x16x32_bf16 v[28:31], v[130:133], v[176:179], v[28:31]
	v_mfma_f32_16x16x32_bf16 v[24:27], v[138:141], v[176:179], v[24:27]
	s_waitcnt lgkmcnt(1)
	v_mfma_f32_16x16x32_bf16 v[12:15], v[130:133], v[200:203], v[12:15]
	v_mfma_f32_16x16x32_bf16 v[8:11], v[138:141], v[200:203], v[8:11]
	v_mfma_f32_16x16x32_bf16 v[60:63], v[134:137], v[162:165], v[60:63]
	v_mfma_f32_16x16x32_bf16 v[56:59], v[142:145], v[162:165], v[56:59]
	v_mfma_f32_16x16x32_bf16 v[44:47], v[134:137], v[172:175], v[44:47]
	v_mfma_f32_16x16x32_bf16 v[40:43], v[142:145], v[172:175], v[40:43]
	v_mfma_f32_16x16x32_bf16 v[28:31], v[134:137], v[196:199], v[28:31]
	v_mfma_f32_16x16x32_bf16 v[24:27], v[142:145], v[196:199], v[24:27]
	s_waitcnt lgkmcnt(0)
	v_mfma_f32_16x16x32_bf16 v[12:15], v[134:137], v[204:207], v[12:15]
	v_mfma_f32_16x16x32_bf16 v[8:11], v[142:145], v[204:207], v[8:11]
	s_setprio 0
	s_barrier
; #define PG8_STAGE(bufoff, gbase, voff) do { _Pragma("unroll") for (int _i = 0; _i < 2; ++_i) \
;         __builtin_amdgcn_global_load_lds((const unsigned*)((const char*)(gbase) + (voff)[_i]), (LAS unsigned*)(lds + (bufoff) + ldsw + _i * 8192), 16, 0, 0); } while (0)
; #define PG8_LDA(dst, b, h) do { _Pragma("unroll") for (int m = 0; m < 4; ++m) _Pragma("unroll") for (int k = 0; k < 2; ++k) dst[m][k] = *(const LAS bf16x8*)(lds + PG8_SA(b, h) + aoff + m * 2048 + k * 1024); } while (0)
; #define PG8_LDB(dst, b, h) do { _Pragma("unroll") for (int n = 0; n < 2; ++n) _Pragma("unroll") for (int k = 0; k < 2; ++k) dst[n][k] = *(const LAS bf16x8*)(lds + PG8_SB(b, h) + boff + n * 2048 + k * 1024); } while (0)
; #define PG8_MMA(ai, bj, At, Bt) do { __builtin_amdgcn_s_setprio(1); _Pragma("unroll") for (int m = 0; m < 4; ++m) _Pragma("unroll") for (int n = 0; n < 2; ++n) _Pragma("unroll") for (int k = 0; k < 2; ++k) \
;         acc[ai][bj][m][n] = __builtin_amdgcn_mfma_f32_16x16x32_bf16(Bt[n][k], At[m][k], acc[ai][bj][m][n], 0, 0, 0); __builtin_amdgcn_s_setprio(0); } while (0)
; #define PG8_WAIT_V(n) asm volatile("s_waitcnt vmcnt(" #n ")" ::: "memory")
; #define PG8_WAIT_L(n) asm volatile("s_waitcnt lgkmcnt(" #n ")" ::: "memory")
; #define PG8_BAR __builtin_amdgcn_s_barrier()
; #define PG8_SCHED __builtin_amdgcn_sched_barrier(0)
; template <class Epi, class Sched>
; DI void gemm_phase(LAS unsigned char* lds, const Gemm g, const Sched& S, const Epi& E) {
;     ...
;             PG8_STAGE(PG8_SB(0, 1), b2 + hstepB, voffB);
;             PG8_WAIT_V(6); PG8_BAR; PG8_MMA(1, 1, At, B1); PG8_BAR;
;             PG8_LDB(B0, 1, 0); PG8_SCHED; PG8_LDA(At, 1, 0); PG8_STAGE(PG8_SA(0, 1), a2 + hstepA, voffA);
;             PG8_WAIT_L(8); PG8_BAR; PG8_WAIT_L(0); PG8_MMA(0, 0, At, B0); PG8_BAR; PG8_SCHED;
;             PG8_LDB(B1, 1, 1); PG8_STAGE(PG8_SB(1, 0), b3, voffB);
	s_add_u32 s56, s6, 0x204000
	s_addc_u32 s57, s7, 0
	s_add_i32 s75, s81, s89
	v_lshl_add_u64 v[130:131], s[56:57], 0, v[96:97]
	s_mov_b32 m0, s75
	s_nop 0
	global_load_lds_dwordx4 v[130:131], off
	v_lshl_add_u64 v[130:131], s[56:57], 0, v[146:147]
	s_add_i32 m0, s75, 0x2000
	s_nop 0
	global_load_lds_dwordx4 v[130:131], off
	s_waitcnt vmcnt(6)
	s_barrier
	s_setprio 1
	v_mfma_f32_16x16x32_bf16 v[52:55], v[208:211], v[152:155], v[52:55]
	v_mfma_f32_16x16x32_bf16 v[48:51], v[216:219], v[152:155], v[48:51]
	v_mfma_f32_16x16x32_bf16 v[36:39], v[208:211], v[168:171], v[36:39]
	v_mfma_f32_16x16x32_bf16 v[32:35], v[216:219], v[168:171], v[32:35]
	v_mfma_f32_16x16x32_bf16 v[20:23], v[208:211], v[176:179], v[20:23]
	v_mfma_f32_16x16x32_bf16 v[16:19], v[216:219], v[176:179], v[16:19]
	v_mfma_f32_16x16x32_bf16 v[4:7], v[208:211], v[200:203], v[4:7]
	v_mfma_f32_16x16x32_bf16 v[0:3], v[216:219], v[200:203], v[0:3]
	v_mfma_f32_16x16x32_bf16 v[52:55], v[212:215], v[162:165], v[52:55]
	v_mfma_f32_16x16x32_bf16 v[48:51], v[220:223], v[162:165], v[48:51]
	v_mfma_f32_16x16x32_bf16 v[36:39], v[212:215], v[172:175], v[36:39]
	v_mfma_f32_16x16x32_bf16 v[32:35], v[220:223], v[172:175], v[32:35]
	v_mfma_f32_16x16x32_bf16 v[20:23], v[212:215], v[196:199], v[20:23]
	v_mfma_f32_16x16x32_bf16 v[16:19], v[220:223], v[196:199], v[16:19]
	v_mfma_f32_16x16x32_bf16 v[4:7], v[212:215], v[204:207], v[4:7]
	v_mfma_f32_16x16x32_bf16 v[0:3], v[220:223], v[204:207], v[0:3]
	s_setprio 0
	s_add_i32 s56, 0, 0x18000
	v_add_u32_e32 v142, s56, v160
	s_barrier
	ds_read_b128 v[130:133], v142
	ds_read_b128 v[134:137], v142 offset:1024
	ds_read_b128 v[138:141], v142 offset:2048
	ds_read_b128 v[142:145], v142 offset:3072
	s_add_u32 s8, s8, 0x204000
	s_addc_u32 s9, s9, 0
	s_mov_b32 m0, s78
	v_lshl_add_u64 v[208:209], s[8:9], 0, v[96:97]
	ds_read_b128 v[152:155], v161 offset:32768
	ds_read_b128 v[162:165], v161 offset:33792
	ds_read_b128 v[168:171], v161 offset:34816
	ds_read_b128 v[172:175], v161 offset:35840
	ds_read_b128 v[176:179], v161 offset:36864
	ds_read_b128 v[196:199], v161 offset:37888
	ds_read_b128 v[200:203], v161 offset:38912
	ds_read_b128 v[204:207], v161 offset:39936
	global_load_lds_dwordx4 v[208:209], off
	v_lshl_add_u64 v[208:209], s[8:9], 0, v[146:147]
	s_mov_b32 m0, s93
	s_nop 0
	global_load_lds_dwordx4 v[208:209], off
	s_waitcnt lgkmcnt(8)
	s_barrier
	s_setprio 1
	s_waitcnt lgkmcnt(7)
	v_mfma_f32_16x16x32_bf16 v[126:129], v[130:133], v[152:155], v[126:129]
	v_mfma_f32_16x16x32_bf16 v[122:125], v[138:141], v[152:155], v[122:125]
	s_waitcnt lgkmcnt(5)
	v_mfma_f32_16x16x32_bf16 v[110:113], v[130:133], v[168:171], v[110:113]
	v_mfma_f32_16x16x32_bf16 v[106:109], v[138:141], v[168:171], v[106:109]
	s_waitcnt lgkmcnt(3)
	v_mfma_f32_16x16x32_bf16 v[92:95], v[130:133], v[176:179], v[92:95]
	v_mfma_f32_16x16x32_bf16 v[88:91], v[138:141], v[176:179], v[88:91]
	s_waitcnt lgkmcnt(1)
	v_mfma_f32_16x16x32_bf16 v[76:79], v[130:133], v[200:203], v[76:79]
	v_mfma_f32_16x16x32_bf16 v[72:75], v[138:141], v[200:203], v[72:75]
	v_mfma_f32_16x16x32_bf16 v[126:129], v[134:137], v[162:165], v[126:129]
	v_mfma_f32_16x16x32_bf16 v[122:125], v[142:145], v[162:165], v[122:125]
	v_mfma_f32_16x16x32_bf16 v[110:113], v[134:137], v[172:175], v[110:113]
	v_mfma_f32_16x16x32_bf16 v[106:109], v[142:145], v[172:175], v[106:109]
	v_mfma_f32_16x16x32_bf16 v[92:95], v[134:137], v[196:199], v[92:95]
	v_mfma_f32_16x16x32_bf16 v[88:91], v[142:145], v[196:199], v[88:91]
	s_waitcnt lgkmcnt(0)
	v_mfma_f32_16x16x32_bf16 v[76:79], v[134:137], v[204:207], v[76:79]
	v_mfma_f32_16x16x32_bf16 v[72:75], v[142:145], v[204:207], v[72:75]
	s_setprio 0
	s_barrier
	s_add_i32 s8, 0, 0x1c000
	s_add_i32 s9, s56, s89
	v_add_u32_e32 v182, s8, v160
	v_lshl_add_u64 v[156:157], v[156:157], 0, s[28:29]
	s_mov_b32 m0, s9
	ds_read_b128 v[208:211], v182
	ds_read_b128 v[212:215], v182 offset:1024
	ds_read_b128 v[216:219], v182 offset:2048
	ds_read_b128 v[220:223], v182 offset:3072
	global_load_lds_dwordx4 v[156:157], off
	v_lshl_add_u64 v[156:157], v[180:181], 0, s[28:29]
	s_add_i32 m0, s9, 0x2000
	s_nop 0
	global_load_lds_dwordx4 v[156:157], off
	s_barrier
; #define PG8_STAGE(bufoff, gbase, voff) do { _Pragma("unroll") for (int _i = 0; _i < 2; ++_i) \
;         __builtin_amdgcn_global_load_lds((const unsigned*)((const char*)(gbase) + (voff)[_i]), (LAS unsigned*)(lds + (bufoff) + ldsw + _i * 8192), 16, 0, 0); } while (0)
; #define PG8_LDA(dst, b, h) do { _Pragma("unroll") for (int m = 0; m < 4; ++m) _Pragma("unroll") for (int k = 0; k < 2; ++k) dst[m][k] = *(const LAS bf16x8*)(lds + PG8_SA(b, h) + aoff + m * 2048 + k * 1024); } while (0)
; #define PG8_MMA(ai, bj, At, Bt) do { __builtin_amdgcn_s_setprio(1); _Pragma("unroll") for (int m = 0; m < 4; ++m) _Pragma("unroll") for (int n = 0; n < 2; ++n) _Pragma("unroll") for (int k = 0; k < 2; ++k) \
;         acc[ai][bj][m][n] = __builtin_amdgcn_mfma_f32_16x16x32_bf16(Bt[n][k], At[m][k], acc[ai][bj][m][n], 0, 0, 0); __builtin_amdgcn_s_setprio(0); } while (0)
; #define PG8_WAIT_V(n) asm volatile("s_waitcnt vmcnt(" #n ")" ::: "memory")
; #define PG8_WAIT_L(n) asm volatile("s_waitcnt lgkmcnt(" #n ")" ::: "memory")
; #define PG8_BAR __builtin_amdgcn_s_barrier()
; #define PG8_SCHED __builtin_amdgcn_sched_barrier(0)
; template <class Epi, class Sched>
; DI void gemm_phase(LAS unsigned char* lds, const Gemm g, const Sched& S, const Epi& E) {
;     ...
;             PG8_BAR; PG8_WAIT_L(0); PG8_MMA(0, 1, At, B1); PG8_BAR;
;             PG8_LDA(At, 1, 1); PG8_STAGE(PG8_SA(1, 0), a3, voffA);
;             PG8_BAR; PG8_WAIT_L(0); PG8_MMA(1, 0, At, B0); PG8_BAR; PG8_SCHED;
;             PG8_STAGE(PG8_SB(1, 1), b3 + hstepB, voffB);
;             PG8_WAIT_V(6); PG8_BAR; PG8_MMA(1, 1, At, B1); PG8_BAR;
;         }
	s_setprio 1
	s_waitcnt lgkmcnt(3)
	v_mfma_f32_16x16x32_bf16 v[118:121], v[208:211], v[152:155], v[118:121]
	s_waitcnt lgkmcnt(1)
	v_mfma_f32_16x16x32_bf16 v[114:117], v[216:219], v[152:155], v[114:117]
	v_mfma_f32_16x16x32_bf16 v[102:105], v[208:211], v[168:171], v[102:105]
	v_mfma_f32_16x16x32_bf16 v[98:101], v[216:219], v[168:171], v[98:101]
	v_mfma_f32_16x16x32_bf16 v[84:87], v[208:211], v[176:179], v[84:87]
	v_mfma_f32_16x16x32_bf16 v[80:83], v[216:219], v[176:179], v[80:83]
	v_mfma_f32_16x16x32_bf16 v[68:71], v[208:211], v[200:203], v[68:71]
	v_mfma_f32_16x16x32_bf16 v[64:67], v[216:219], v[200:203], v[64:67]
	v_mfma_f32_16x16x32_bf16 v[118:121], v[212:215], v[162:165], v[118:121]
	s_waitcnt lgkmcnt(0)
	v_mfma_f32_16x16x32_bf16 v[114:117], v[220:223], v[162:165], v[114:117]
	v_mfma_f32_16x16x32_bf16 v[102:105], v[212:215], v[172:175], v[102:105]
	v_mfma_f32_16x16x32_bf16 v[98:101], v[220:223], v[172:175], v[98:101]
	v_mfma_f32_16x16x32_bf16 v[84:87], v[212:215], v[196:199], v[84:87]
	v_mfma_f32_16x16x32_bf16 v[80:83], v[220:223], v[196:199], v[80:83]
	v_mfma_f32_16x16x32_bf16 v[68:71], v[212:215], v[204:207], v[68:71]
	v_mfma_f32_16x16x32_bf16 v[64:67], v[220:223], v[204:207], v[64:67]
	s_setprio 0
	s_mov_b32 m0, s60
	v_lshl_add_u64 v[156:157], v[224:225], 0, s[28:29]
	s_barrier
	ds_read_b128 v[152:155], v161 offset:49152
	ds_read_b128 v[162:165], v161 offset:50176
	ds_read_b128 v[168:171], v161 offset:51200
	ds_read_b128 v[172:175], v161 offset:52224
	ds_read_b128 v[176:179], v161 offset:53248
	ds_read_b128 v[196:199], v161 offset:54272
	ds_read_b128 v[200:203], v161 offset:55296
	ds_read_b128 v[204:207], v161 offset:56320
	global_load_lds_dwordx4 v[156:157], off
	v_lshl_add_u64 v[156:157], v[226:227], 0, s[28:29]
	s_mov_b32 m0, s61
	s_nop 0
	global_load_lds_dwordx4 v[156:157], off
	s_barrier
	s_setprio 1
	s_waitcnt lgkmcnt(7)
	v_mfma_f32_16x16x32_bf16 v[60:63], v[130:133], v[152:155], v[60:63]
	v_mfma_f32_16x16x32_bf16 v[56:59], v[138:141], v[152:155], v[56:59]
	s_waitcnt lgkmcnt(5)
	v_mfma_f32_16x16x32_bf16 v[44:47], v[130:133], v[168:171], v[44:47]
	v_mfma_f32_16x16x32_bf16 v[40:43], v[138:141], v[168:171], v[40:43]
	s_waitcnt lgkmcnt(3)
	v_mfma_f32_16x16x32_bf16 v[28:31], v[130:133], v[176:179], v[28:31]
	v_mfma_f32_16x16x32_bf16 v[24:27], v[138:141], v[176:179], v[24:27]
	s_waitcnt lgkmcnt(1)
	v_mfma_f32_16x16x32_bf16 v[12:15], v[130:133], v[200:203], v[12:15]
	v_mfma_f32_16x16x32_bf16 v[8:11], v[138:141], v[200:203], v[8:11]
	v_mfma_f32_16x16x32_bf16 v[60:63], v[134:137], v[162:165], v[60:63]
	v_mfma_f32_16x16x32_bf16 v[56:59], v[142:145], v[162:165], v[56:59]
	v_mfma_f32_16x16x32_bf16 v[44:47], v[134:137], v[172:175], v[44:47]
	v_mfma_f32_16x16x32_bf16 v[40:43], v[142:145], v[172:175], v[40:43]
	v_mfma_f32_16x16x32_bf16 v[28:31], v[134:137], v[196:199], v[28:31]
	v_mfma_f32_16x16x32_bf16 v[24:27], v[142:145], v[196:199], v[24:27]
	s_waitcnt lgkmcnt(0)
	v_mfma_f32_16x16x32_bf16 v[12:15], v[134:137], v[204:207], v[12:15]
	v_mfma_f32_16x16x32_bf16 v[8:11], v[142:145], v[204:207], v[8:11]
	s_setprio 0
	s_barrier
	s_add_u32 s6, s6, 0x204080
	s_addc_u32 s7, s7, 0
	s_add_i32 s8, s8, s89
	v_lshl_add_u64 v[130:131], s[6:7], 0, v[96:97]
	s_mov_b32 m0, s8
	s_nop 0
	global_load_lds_dwordx4 v[130:131], off
	v_lshl_add_u64 v[130:131], s[6:7], 0, v[146:147]
	s_add_i32 m0, s8, 0x2000
	s_nop 0
	global_load_lds_dwordx4 v[130:131], off
	s_waitcnt vmcnt(6)
	s_barrier
	s_setprio 1
	v_mfma_f32_16x16x32_bf16 v[52:55], v[208:211], v[152:155], v[52:55]
	v_mfma_f32_16x16x32_bf16 v[48:51], v[216:219], v[152:155], v[48:51]
	v_mfma_f32_16x16x32_bf16 v[36:39], v[208:211], v[168:171], v[36:39]
	v_mfma_f32_16x16x32_bf16 v[32:35], v[216:219], v[168:171], v[32:35]
	v_mfma_f32_16x16x32_bf16 v[20:23], v[208:211], v[176:179], v[20:23]
	v_mfma_f32_16x16x32_bf16 v[16:19], v[216:219], v[176:179], v[16:19]
	v_mfma_f32_16x16x32_bf16 v[4:7], v[208:211], v[200:203], v[4:7]
	v_mfma_f32_16x16x32_bf16 v[0:3], v[216:219], v[200:203], v[0:3]
	v_mfma_f32_16x16x32_bf16 v[52:55], v[212:215], v[162:165], v[52:55]
	v_mfma_f32_16x16x32_bf16 v[48:51], v[220:223], v[162:165], v[48:51]
	v_mfma_f32_16x16x32_bf16 v[36:39], v[212:215], v[172:175], v[36:39]
	v_mfma_f32_16x16x32_bf16 v[32:35], v[220:223], v[172:175], v[32:35]
	v_mfma_f32_16x16x32_bf16 v[20:23], v[212:215], v[196:199], v[20:23]
	v_mfma_f32_16x16x32_bf16 v[16:19], v[220:223], v[196:199], v[16:19]
	v_mfma_f32_16x16x32_bf16 v[4:7], v[212:215], v[204:207], v[4:7]
	v_mfma_f32_16x16x32_bf16 v[0:3], v[220:223], v[204:207], v[0:3]
	s_setprio 0
	s_add_u32 s11, s11, 0x100
	s_addc_u32 s31, s31, 0
	s_cmp_ge_i32 s74, s58
	s_mov_b64 s[56:57], s[68:69]
	s_mov_b32 s6, s74
	s_barrier
	s_cbranch_scc0 .LBB0_79

; #define PG8_STAGE(bufoff, gbase, voff) do { _Pragma("unroll") for (int _i = 0; _i < 2; ++_i) \
;         __builtin_amdgcn_global_load_lds((const unsigned*)((const char*)(gbase) + (voff)[_i]), (LAS unsigned*)(lds + (bufoff) + ldsw + _i * 8192), 16, 0, 0); } while (0)
; #define PG8_LDA(dst, b, h) do { _Pragma("unroll") for (int m = 0; m < 4; ++m) _Pragma("unroll") for (int k = 0; k < 2; ++k) dst[m][k] = *(const LAS bf16x8*)(lds + PG8_SA(b, h) + aoff + m * 2048 + k * 1024); } while (0)
; #define PG8_LDB(dst, b, h) do { _Pragma("unroll") for (int n = 0; n < 2; ++n) _Pragma("unroll") for (int k = 0; k < 2; ++k) dst[n][k] = *(const LAS bf16x8*)(lds + PG8_SB(b, h) + boff + n * 2048 + k * 1024); } while (0)
; #define PG8_MMA(ai, bj, At, Bt) do { __builtin_amdgcn_s_setprio(1); _Pragma("unroll") for (int m = 0; m < 4; ++m) _Pragma("unroll") for (int n = 0; n < 2; ++n) _Pragma("unroll") for (int k = 0; k < 2; ++k) \
;         acc[ai][bj][m][n] = __builtin_amdgcn_mfma_f32_16x16x32_bf16(Bt[n][k], At[m][k], acc[ai][bj][m][n], 0, 0, 0); __builtin_amdgcn_s_setprio(0); } while (0)
; #define PG8_WAIT_L(n) asm volatile("s_waitcnt lgkmcnt(" #n ")" ::: "memory")
; #define PG8_BAR __builtin_amdgcn_s_barrier()
; #define PG8_SCHED __builtin_amdgcn_sched_barrier(0)
; template <class Epi, class Sched>
; DI void gemm_phase(LAS unsigned char* lds, const Gemm g, const Sched& S, const Epi& E) {
;     ...
;             PG8_LDB(B0, 0, 0); PG8_SCHED; PG8_LDA(At, 0, 0); PG8_STAGE(PG8_SA(1, 1), a1 + hstepA, voffA);
;             PG8_WAIT_L(8); PG8_BAR; PG8_WAIT_L(0); PG8_MMA(0, 0, At, B0); PG8_BAR; PG8_SCHED;
;             PG8_LDB(B1, 0, 1); PG8_STAGE(PG8_SB(0, 0), b2, voffB);
;             PG8_BAR; PG8_WAIT_L(0); PG8_MMA(0, 1, At, B1); PG8_BAR;
;             PG8_LDA(At, 0, 1); PG8_STAGE(PG8_SA(0, 0), a2, voffA);
;             PG8_BAR; PG8_WAIT_L(0); PG8_MMA(1, 0, At, B0); PG8_BAR; PG8_SCHED;
.LBB0_110:
	s_add_i32 s81, s6, 2
	s_add_u32 s8, s74, 0x80
	s_addc_u32 s7, s75, 0
	s_add_i32 s82, 0, 0x10000
	v_add_u32_e32 v156, s82, v146
	ds_read_b128 v[140:143], v156
	ds_read_b128 v[148:151], v156 offset:1024
	ds_read_b128 v[152:155], v156 offset:2048
	ds_read_b128 v[156:159], v156 offset:3072
	s_cmp_eq_u32 s60, s6
	s_cselect_b32 s6, s44, s8
	s_cselect_b32 s7, s45, s7
	s_cselect_b32 s9, s47, s80
	s_cselect_b32 s8, s46, s41
	v_lshl_add_u64 v[164:165], s[74:75], 0, v[138:139]
	s_add_i32 m0, s89, 0xc000
	ds_read_b128 v[160:163], v147
	ds_read_b128 v[168:171], v147 offset:1024
	ds_read_b128 v[172:175], v147 offset:2048
	ds_read_b128 v[176:179], v147 offset:3072
	ds_read_b128 v[196:199], v147 offset:4096
	ds_read_b128 v[200:203], v147 offset:5120
	ds_read_b128 v[204:207], v147 offset:6144
	ds_read_b128 v[208:211], v147 offset:7168
	global_load_lds_dwordx4 v[164:165], off
	v_lshl_add_u64 v[164:165], s[74:75], 0, v[136:137]
	s_add_i32 m0, s89, 0xe000
	s_nop 0
	global_load_lds_dwordx4 v[164:165], off
	s_waitcnt lgkmcnt(8)
	s_barrier
	s_setprio 1
	s_waitcnt lgkmcnt(7)
	v_mfma_f32_16x16x32_bf16 v[122:125], v[140:143], v[160:163], v[122:125]
	v_mfma_f32_16x16x32_bf16 v[126:129], v[152:155], v[160:163], v[126:129]
	s_waitcnt lgkmcnt(5)
	v_mfma_f32_16x16x32_bf16 v[110:113], v[140:143], v[172:175], v[110:113]
	v_mfma_f32_16x16x32_bf16 v[106:109], v[152:155], v[172:175], v[106:109]
	s_waitcnt lgkmcnt(3)
	v_mfma_f32_16x16x32_bf16 v[92:95], v[140:143], v[196:199], v[92:95]
	v_mfma_f32_16x16x32_bf16 v[88:91], v[152:155], v[196:199], v[88:91]
	s_waitcnt lgkmcnt(1)
	v_mfma_f32_16x16x32_bf16 v[76:79], v[140:143], v[204:207], v[76:79]
	v_mfma_f32_16x16x32_bf16 v[72:75], v[152:155], v[204:207], v[72:75]
	v_mfma_f32_16x16x32_bf16 v[122:125], v[148:151], v[168:171], v[122:125]
	v_mfma_f32_16x16x32_bf16 v[126:129], v[156:159], v[168:171], v[126:129]
	v_mfma_f32_16x16x32_bf16 v[110:113], v[148:151], v[176:179], v[110:113]
	v_mfma_f32_16x16x32_bf16 v[106:109], v[156:159], v[176:179], v[106:109]
	v_mfma_f32_16x16x32_bf16 v[92:95], v[148:151], v[200:203], v[92:95]
	v_mfma_f32_16x16x32_bf16 v[88:91], v[156:159], v[200:203], v[88:91]
	s_waitcnt lgkmcnt(0)
	v_mfma_f32_16x16x32_bf16 v[76:79], v[148:151], v[208:211], v[76:79]
	v_mfma_f32_16x16x32_bf16 v[72:75], v[156:159], v[208:211], v[72:75]
	s_setprio 0
	s_barrier
	s_add_i32 s83, 0, 0x14000
	v_add_u32_e32 v164, s83, v146
	s_add_i32 s82, s82, s84
	ds_read_b128 v[212:215], v164
	ds_read_b128 v[216:219], v164 offset:1024
	ds_read_b128 v[220:223], v164 offset:2048
	ds_read_b128 v[224:227], v164 offset:3072
	v_lshl_add_u64 v[164:165], s[8:9], 0, v[96:97]
	s_mov_b32 m0, s82
	v_lshl_add_u64 v[180:181], s[8:9], 0, v[134:135]
	global_load_lds_dwordx4 v[164:165], off
	s_add_i32 m0, s82, 0x2000
	s_nop 0
	global_load_lds_dwordx4 v[180:181], off
	s_barrier
	s_setprio 1
	s_waitcnt lgkmcnt(3)
	v_mfma_f32_16x16x32_bf16 v[118:121], v[212:215], v[160:163], v[118:121]
	s_waitcnt lgkmcnt(1)
	v_mfma_f32_16x16x32_bf16 v[114:117], v[220:223], v[160:163], v[114:117]
	v_mfma_f32_16x16x32_bf16 v[102:105], v[212:215], v[172:175], v[102:105]
	v_mfma_f32_16x16x32_bf16 v[98:101], v[220:223], v[172:175], v[98:101]
	v_mfma_f32_16x16x32_bf16 v[84:87], v[212:215], v[196:199], v[84:87]
	v_mfma_f32_16x16x32_bf16 v[80:83], v[220:223], v[196:199], v[80:83]
	v_mfma_f32_16x16x32_bf16 v[68:71], v[212:215], v[204:207], v[68:71]
	v_mfma_f32_16x16x32_bf16 v[64:67], v[220:223], v[204:207], v[64:67]
	v_mfma_f32_16x16x32_bf16 v[118:121], v[216:219], v[168:171], v[118:121]
	s_waitcnt lgkmcnt(0)
	v_mfma_f32_16x16x32_bf16 v[114:117], v[224:227], v[168:171], v[114:117]
	v_mfma_f32_16x16x32_bf16 v[102:105], v[216:219], v[176:179], v[102:105]
	v_mfma_f32_16x16x32_bf16 v[98:101], v[224:227], v[176:179], v[98:101]
	v_mfma_f32_16x16x32_bf16 v[84:87], v[216:219], v[200:203], v[84:87]
	v_mfma_f32_16x16x32_bf16 v[80:83], v[224:227], v[200:203], v[80:83]
	v_mfma_f32_16x16x32_bf16 v[68:71], v[216:219], v[208:211], v[68:71]
	v_mfma_f32_16x16x32_bf16 v[64:67], v[224:227], v[208:211], v[64:67]
	s_setprio 0
	s_mov_b32 m0, s89
	v_lshl_add_u64 v[228:229], s[6:7], 0, v[130:131]
	s_barrier
	ds_read_b128 v[160:163], v147 offset:16384
	ds_read_b128 v[168:171], v147 offset:17408
	ds_read_b128 v[172:175], v147 offset:18432
	ds_read_b128 v[176:179], v147 offset:19456
	ds_read_b128 v[196:199], v147 offset:20480
	ds_read_b128 v[200:203], v147 offset:21504
	ds_read_b128 v[204:207], v147 offset:22528
	ds_read_b128 v[208:211], v147 offset:23552
	global_load_lds_dwordx4 v[228:229], off
	v_lshl_add_u64 v[230:231], s[6:7], 0, v[132:133]
	s_mov_b32 m0, s90
	s_nop 0
	global_load_lds_dwordx4 v[230:231], off
	s_barrier
	s_setprio 1
	s_waitcnt lgkmcnt(7)
	v_mfma_f32_16x16x32_bf16 v[60:63], v[140:143], v[160:163], v[60:63]
	v_mfma_f32_16x16x32_bf16 v[56:59], v[152:155], v[160:163], v[56:59]
	s_waitcnt lgkmcnt(5)
	v_mfma_f32_16x16x32_bf16 v[44:47], v[140:143], v[172:175], v[44:47]
	v_mfma_f32_16x16x32_bf16 v[40:43], v[152:155], v[172:175], v[40:43]
	s_waitcnt lgkmcnt(3)
	v_mfma_f32_16x16x32_bf16 v[28:31], v[140:143], v[196:199], v[28:31]
	v_mfma_f32_16x16x32_bf16 v[24:27], v[152:155], v[196:199], v[24:27]
	s_waitcnt lgkmcnt(1)
	v_mfma_f32_16x16x32_bf16 v[12:15], v[140:143], v[204:207], v[12:15]
	v_mfma_f32_16x16x32_bf16 v[8:11], v[152:155], v[204:207], v[8:11]
	v_mfma_f32_16x16x32_bf16 v[60:63], v[148:151], v[168:171], v[60:63]
	v_mfma_f32_16x16x32_bf16 v[56:59], v[156:159], v[168:171], v[56:59]
	v_mfma_f32_16x16x32_bf16 v[44:47], v[148:151], v[176:179], v[44:47]
	v_mfma_f32_16x16x32_bf16 v[40:43], v[156:159], v[176:179], v[40:43]
	v_mfma_f32_16x16x32_bf16 v[28:31], v[148:151], v[200:203], v[28:31]
	v_mfma_f32_16x16x32_bf16 v[24:27], v[156:159], v[200:203], v[24:27]
	s_waitcnt lgkmcnt(0)
	v_mfma_f32_16x16x32_bf16 v[12:15], v[148:151], v[208:211], v[12:15]
	v_mfma_f32_16x16x32_bf16 v[8:11], v[156:159], v[208:211], v[8:11]
	s_setprio 0
	s_barrier
; #define PG8_STAGE(bufoff, gbase, voff) do { _Pragma("unroll") for (int _i = 0; _i < 2; ++_i) \
;         __builtin_amdgcn_global_load_lds((const unsigned*)((const char*)(gbase) + (voff)[_i]), (LAS unsigned*)(lds + (bufoff) + ldsw + _i * 8192), 16, 0, 0); } while (0)
; #define PG8_LDA(dst, b, h) do { _Pragma("unroll") for (int m = 0; m < 4; ++m) _Pragma("unroll") for (int k = 0; k < 2; ++k) dst[m][k] = *(const LAS bf16x8*)(lds + PG8_SA(b, h) + aoff + m * 2048 + k * 1024); } while (0)
; #define PG8_LDB(dst, b, h) do { _Pragma("unroll") for (int n = 0; n < 2; ++n) _Pragma("unroll") for (int k = 0; k < 2; ++k) dst[n][k] = *(const LAS bf16x8*)(lds + PG8_SB(b, h) + boff + n * 2048 + k * 1024); } while (0)
; #define PG8_MMA(ai, bj, At, Bt) do { __builtin_amdgcn_s_setprio(1); _Pragma("unroll") for (int m = 0; m < 4; ++m) _Pragma("unroll") for (int n = 0; n < 2; ++n) _Pragma("unroll") for (int k = 0; k < 2; ++k) \
;         acc[ai][bj][m][n] = __builtin_amdgcn_mfma_f32_16x16x32_bf16(Bt[n][k], At[m][k], acc[ai][bj][m][n], 0, 0, 0); __builtin_amdgcn_s_setprio(0); } while (0)
; #define PG8_WAIT_V(n) asm volatile("s_waitcnt vmcnt(" #n ")" ::: "memory")
; #define PG8_WAIT_L(n) asm volatile("s_waitcnt lgkmcnt(" #n ")" ::: "memory")
; #define PG8_BAR __builtin_amdgcn_s_barrier()
; #define PG8_SCHED __builtin_amdgcn_sched_barrier(0)
; template <class Epi, class Sched>
; DI void gemm_phase(LAS unsigned char* lds, const Gemm g, const Sched& S, const Epi& E) {
;     ...
;             PG8_STAGE(PG8_SB(0, 1), b2 + hstepB, voffB);
;             PG8_WAIT_V(6); PG8_BAR; PG8_MMA(1, 1, At, B1); PG8_BAR;
;             PG8_LDB(B0, 1, 0); PG8_SCHED; PG8_LDA(At, 1, 0); PG8_STAGE(PG8_SA(0, 1), a2 + hstepA, voffA);
;             PG8_WAIT_L(8); PG8_BAR; PG8_WAIT_L(0); PG8_MMA(0, 0, At, B0); PG8_BAR; PG8_SCHED;
;             PG8_LDB(B1, 1, 1); PG8_STAGE(PG8_SB(1, 0), b3, voffB);
	s_add_u32 s8, s8, s52
	s_addc_u32 s9, s9, s53
	s_add_i32 s82, s83, s84
	v_lshl_add_u64 v[232:233], s[8:9], 0, v[96:97]
	s_mov_b32 m0, s82
	v_lshl_add_u64 v[234:235], s[8:9], 0, v[134:135]
	global_load_lds_dwordx4 v[232:233], off
	s_add_i32 m0, s82, 0x2000
	s_nop 0
	global_load_lds_dwordx4 v[234:235], off
	s_waitcnt vmcnt(6)
	s_barrier
	s_setprio 1
	v_mfma_f32_16x16x32_bf16 v[52:55], v[212:215], v[160:163], v[52:55]
	v_mfma_f32_16x16x32_bf16 v[48:51], v[220:223], v[160:163], v[48:51]
	v_mfma_f32_16x16x32_bf16 v[36:39], v[212:215], v[172:175], v[36:39]
	v_mfma_f32_16x16x32_bf16 v[32:35], v[220:223], v[172:175], v[32:35]
	v_mfma_f32_16x16x32_bf16 v[20:23], v[212:215], v[196:199], v[20:23]
	v_mfma_f32_16x16x32_bf16 v[16:19], v[220:223], v[196:199], v[16:19]
	v_mfma_f32_16x16x32_bf16 v[4:7], v[212:215], v[204:207], v[4:7]
	v_mfma_f32_16x16x32_bf16 v[0:3], v[220:223], v[204:207], v[0:3]
	v_mfma_f32_16x16x32_bf16 v[52:55], v[216:219], v[168:171], v[52:55]
	v_mfma_f32_16x16x32_bf16 v[48:51], v[224:227], v[168:171], v[48:51]
	v_mfma_f32_16x16x32_bf16 v[36:39], v[216:219], v[176:179], v[36:39]
	v_mfma_f32_16x16x32_bf16 v[32:35], v[224:227], v[176:179], v[32:35]
	v_mfma_f32_16x16x32_bf16 v[20:23], v[216:219], v[200:203], v[20:23]
	v_mfma_f32_16x16x32_bf16 v[16:19], v[224:227], v[200:203], v[16:19]
	v_mfma_f32_16x16x32_bf16 v[4:7], v[216:219], v[208:211], v[4:7]
	v_mfma_f32_16x16x32_bf16 v[0:3], v[224:227], v[208:211], v[0:3]
	s_setprio 0
	s_add_i32 s8, 0, 0x18000
	v_add_u32_e32 v156, s8, v146
	s_barrier
	ds_read_b128 v[140:143], v156
	ds_read_b128 v[148:151], v156 offset:1024
	ds_read_b128 v[152:155], v156 offset:2048
	ds_read_b128 v[156:159], v156 offset:3072
	s_add_u32 s6, s6, s52
	s_addc_u32 s7, s7, s53
	s_mov_b32 m0, s91
	v_lshl_add_u64 v[212:213], s[6:7], 0, v[130:131]
	ds_read_b128 v[160:163], v147 offset:32768
	ds_read_b128 v[168:171], v147 offset:33792
	ds_read_b128 v[172:175], v147 offset:34816
	ds_read_b128 v[176:179], v147 offset:35840
	ds_read_b128 v[196:199], v147 offset:36864
	ds_read_b128 v[200:203], v147 offset:37888
	ds_read_b128 v[204:207], v147 offset:38912
	ds_read_b128 v[208:211], v147 offset:39936
	global_load_lds_dwordx4 v[212:213], off
	v_lshl_add_u64 v[212:213], s[6:7], 0, v[132:133]
	s_mov_b32 m0, s92
	s_nop 0
	global_load_lds_dwordx4 v[212:213], off
	s_waitcnt lgkmcnt(8)
	s_barrier
	s_setprio 1
	s_waitcnt lgkmcnt(7)
	v_mfma_f32_16x16x32_bf16 v[122:125], v[140:143], v[160:163], v[122:125]
	v_mfma_f32_16x16x32_bf16 v[126:129], v[152:155], v[160:163], v[126:129]
	s_waitcnt lgkmcnt(5)
	v_mfma_f32_16x16x32_bf16 v[110:113], v[140:143], v[172:175], v[110:113]
	v_mfma_f32_16x16x32_bf16 v[106:109], v[152:155], v[172:175], v[106:109]
	s_waitcnt lgkmcnt(3)
	v_mfma_f32_16x16x32_bf16 v[92:95], v[140:143], v[196:199], v[92:95]
	v_mfma_f32_16x16x32_bf16 v[88:91], v[152:155], v[196:199], v[88:91]
	s_waitcnt lgkmcnt(1)
	v_mfma_f32_16x16x32_bf16 v[76:79], v[140:143], v[204:207], v[76:79]
	v_mfma_f32_16x16x32_bf16 v[72:75], v[152:155], v[204:207], v[72:75]
	v_mfma_f32_16x16x32_bf16 v[122:125], v[148:151], v[168:171], v[122:125]
	v_mfma_f32_16x16x32_bf16 v[126:129], v[156:159], v[168:171], v[126:129]
	v_mfma_f32_16x16x32_bf16 v[110:113], v[148:151], v[176:179], v[110:113]
	v_mfma_f32_16x16x32_bf16 v[106:109], v[156:159], v[176:179], v[106:109]
	v_mfma_f32_16x16x32_bf16 v[92:95], v[148:151], v[200:203], v[92:95]
	v_mfma_f32_16x16x32_bf16 v[88:91], v[156:159], v[200:203], v[88:91]
	s_waitcnt lgkmcnt(0)
	v_mfma_f32_16x16x32_bf16 v[76:79], v[148:151], v[208:211], v[76:79]
	v_mfma_f32_16x16x32_bf16 v[72:75], v[156:159], v[208:211], v[72:75]
	s_setprio 0
	s_barrier
	s_add_i32 s6, 0, 0x1c000
	s_add_i32 s7, s8, s84
	v_add_u32_e32 v182, s6, v146
	v_lshl_add_u64 v[164:165], v[164:165], 0, s[28:29]
	s_mov_b32 m0, s7
	ds_read_b128 v[212:215], v182
	ds_read_b128 v[216:219], v182 offset:1024
	ds_read_b128 v[220:223], v182 offset:2048
	ds_read_b128 v[224:227], v182 offset:3072
	global_load_lds_dwordx4 v[164:165], off
	v_lshl_add_u64 v[164:165], v[180:181], 0, s[28:29]
	s_add_i32 m0, s7, 0x2000
	s_nop 0
	global_load_lds_dwordx4 v[164:165], off
	s_barrier
; #define PG8_STAGE(bufoff, gbase, voff) do { _Pragma("unroll") for (int _i = 0; _i < 2; ++_i) \
;         __builtin_amdgcn_global_load_lds((const unsigned*)((const char*)(gbase) + (voff)[_i]), (LAS unsigned*)(lds + (bufoff) + ldsw + _i * 8192), 16, 0, 0); } while (0)
; #define PG8_LDA(dst, b, h) do { _Pragma("unroll") for (int m = 0; m < 4; ++m) _Pragma("unroll") for (int k = 0; k < 2; ++k) dst[m][k] = *(const LAS bf16x8*)(lds + PG8_SA(b, h) + aoff + m * 2048 + k * 1024); } while (0)
; #define PG8_MMA(ai, bj, At, Bt) do { __builtin_amdgcn_s_setprio(1); _Pragma("unroll") for (int m = 0; m < 4; ++m) _Pragma("unroll") for (int n = 0; n < 2; ++n) _Pragma("unroll") for (int k = 0; k < 2; ++k) \
;         acc[ai][bj][m][n] = __builtin_amdgcn_mfma_f32_16x16x32_bf16(Bt[n][k], At[m][k], acc[ai][bj][m][n], 0, 0, 0); __builtin_amdgcn_s_setprio(0); } while (0)
; #define PG8_WAIT_V(n) asm volatile("s_waitcnt vmcnt(" #n ")" ::: "memory")
; #define PG8_WAIT_L(n) asm volatile("s_waitcnt lgkmcnt(" #n ")" ::: "memory")
; #define PG8_BAR __builtin_amdgcn_s_barrier()
; #define PG8_SCHED __builtin_amdgcn_sched_barrier(0)
; template <class Epi, class Sched>
; DI void gemm_phase(LAS unsigned char* lds, const Gemm g, const Sched& S, const Epi& E) {
;     ...
;             PG8_BAR; PG8_WAIT_L(0); PG8_MMA(0, 1, At, B1); PG8_BAR;
;             PG8_LDA(At, 1, 1); PG8_STAGE(PG8_SA(1, 0), a3, voffA);
;             PG8_BAR; PG8_WAIT_L(0); PG8_MMA(1, 0, At, B0); PG8_BAR; PG8_SCHED;
;             PG8_STAGE(PG8_SB(1, 1), b3 + hstepB, voffB);
;             PG8_WAIT_V(6); PG8_BAR; PG8_MMA(1, 1, At, B1); PG8_BAR;
;         }
	s_setprio 1
	s_waitcnt lgkmcnt(3)
	v_mfma_f32_16x16x32_bf16 v[118:121], v[212:215], v[160:163], v[118:121]
	s_waitcnt lgkmcnt(1)
	v_mfma_f32_16x16x32_bf16 v[114:117], v[220:223], v[160:163], v[114:117]
	v_mfma_f32_16x16x32_bf16 v[102:105], v[212:215], v[172:175], v[102:105]
	v_mfma_f32_16x16x32_bf16 v[98:101], v[220:223], v[172:175], v[98:101]
	v_mfma_f32_16x16x32_bf16 v[84:87], v[212:215], v[196:199], v[84:87]
	v_mfma_f32_16x16x32_bf16 v[80:83], v[220:223], v[196:199], v[80:83]
	v_mfma_f32_16x16x32_bf16 v[68:71], v[212:215], v[204:207], v[68:71]
	v_mfma_f32_16x16x32_bf16 v[64:67], v[220:223], v[204:207], v[64:67]
	v_mfma_f32_16x16x32_bf16 v[118:121], v[216:219], v[168:171], v[118:121]
	s_waitcnt lgkmcnt(0)
	v_mfma_f32_16x16x32_bf16 v[114:117], v[224:227], v[168:171], v[114:117]
	v_mfma_f32_16x16x32_bf16 v[102:105], v[216:219], v[176:179], v[102:105]
	v_mfma_f32_16x16x32_bf16 v[98:101], v[224:227], v[176:179], v[98:101]
	v_mfma_f32_16x16x32_bf16 v[84:87], v[216:219], v[200:203], v[84:87]
	v_mfma_f32_16x16x32_bf16 v[80:83], v[224:227], v[200:203], v[80:83]
	v_mfma_f32_16x16x32_bf16 v[68:71], v[216:219], v[208:211], v[68:71]
	v_mfma_f32_16x16x32_bf16 v[64:67], v[224:227], v[208:211], v[64:67]
	s_setprio 0
	s_mov_b32 m0, s73
	v_lshl_add_u64 v[164:165], v[228:229], 0, s[28:29]
	s_barrier
	ds_read_b128 v[160:163], v147 offset:49152
	ds_read_b128 v[168:171], v147 offset:50176
	ds_read_b128 v[172:175], v147 offset:51200
	ds_read_b128 v[176:179], v147 offset:52224
	ds_read_b128 v[196:199], v147 offset:53248
	ds_read_b128 v[200:203], v147 offset:54272
	ds_read_b128 v[204:207], v147 offset:55296
	ds_read_b128 v[208:211], v147 offset:56320
	global_load_lds_dwordx4 v[164:165], off
	v_lshl_add_u64 v[164:165], v[230:231], 0, s[28:29]
	s_mov_b32 m0, s78
	s_nop 0
	global_load_lds_dwordx4 v[164:165], off
	s_barrier
	s_setprio 1
	s_waitcnt lgkmcnt(7)
	v_mfma_f32_16x16x32_bf16 v[60:63], v[140:143], v[160:163], v[60:63]
	v_mfma_f32_16x16x32_bf16 v[56:59], v[152:155], v[160:163], v[56:59]
	s_waitcnt lgkmcnt(5)
	v_mfma_f32_16x16x32_bf16 v[44:47], v[140:143], v[172:175], v[44:47]
	v_mfma_f32_16x16x32_bf16 v[40:43], v[152:155], v[172:175], v[40:43]
	s_waitcnt lgkmcnt(3)
	v_mfma_f32_16x16x32_bf16 v[28:31], v[140:143], v[196:199], v[28:31]
	v_mfma_f32_16x16x32_bf16 v[24:27], v[152:155], v[196:199], v[24:27]
	s_waitcnt lgkmcnt(1)
	v_mfma_f32_16x16x32_bf16 v[12:15], v[140:143], v[204:207], v[12:15]
	v_mfma_f32_16x16x32_bf16 v[8:11], v[152:155], v[204:207], v[8:11]
	v_mfma_f32_16x16x32_bf16 v[60:63], v[148:151], v[168:171], v[60:63]
	v_mfma_f32_16x16x32_bf16 v[56:59], v[156:159], v[168:171], v[56:59]
	v_mfma_f32_16x16x32_bf16 v[44:47], v[148:151], v[176:179], v[44:47]
	v_mfma_f32_16x16x32_bf16 v[40:43], v[156:159], v[176:179], v[40:43]
	v_mfma_f32_16x16x32_bf16 v[28:31], v[148:151], v[200:203], v[28:31]
	v_mfma_f32_16x16x32_bf16 v[24:27], v[156:159], v[200:203], v[24:27]
	s_waitcnt lgkmcnt(0)
	v_mfma_f32_16x16x32_bf16 v[12:15], v[148:151], v[208:211], v[12:15]
	v_mfma_f32_16x16x32_bf16 v[8:11], v[156:159], v[208:211], v[8:11]
	s_setprio 0
	s_barrier
	s_add_i32 s6, s6, s84
	v_lshl_add_u64 v[140:141], v[232:233], 0, s[28:29]
	s_mov_b32 m0, s6
	s_nop 0
	global_load_lds_dwordx4 v[140:141], off
	v_lshl_add_u64 v[140:141], v[234:235], 0, s[28:29]
	s_add_i32 m0, s6, 0x2000
	s_nop 0
	global_load_lds_dwordx4 v[140:141], off
	s_waitcnt vmcnt(6)
	s_barrier
	s_setprio 1
	v_mfma_f32_16x16x32_bf16 v[52:55], v[212:215], v[160:163], v[52:55]
	v_mfma_f32_16x16x32_bf16 v[48:51], v[220:223], v[160:163], v[48:51]
	v_mfma_f32_16x16x32_bf16 v[36:39], v[212:215], v[172:175], v[36:39]
	v_mfma_f32_16x16x32_bf16 v[32:35], v[220:223], v[172:175], v[32:35]
	v_mfma_f32_16x16x32_bf16 v[20:23], v[212:215], v[196:199], v[20:23]
	v_mfma_f32_16x16x32_bf16 v[16:19], v[220:223], v[196:199], v[16:19]
	v_mfma_f32_16x16x32_bf16 v[4:7], v[212:215], v[204:207], v[4:7]
	v_mfma_f32_16x16x32_bf16 v[0:3], v[220:223], v[204:207], v[0:3]
	v_mfma_f32_16x16x32_bf16 v[52:55], v[216:219], v[168:171], v[52:55]
	v_mfma_f32_16x16x32_bf16 v[48:51], v[224:227], v[168:171], v[48:51]
	v_mfma_f32_16x16x32_bf16 v[36:39], v[216:219], v[176:179], v[36:39]
	v_mfma_f32_16x16x32_bf16 v[32:35], v[224:227], v[176:179], v[32:35]
	v_mfma_f32_16x16x32_bf16 v[20:23], v[216:219], v[200:203], v[20:23]
	v_mfma_f32_16x16x32_bf16 v[16:19], v[224:227], v[200:203], v[16:19]
	v_mfma_f32_16x16x32_bf16 v[4:7], v[216:219], v[208:211], v[4:7]
	v_mfma_f32_16x16x32_bf16 v[0:3], v[224:227], v[208:211], v[0:3]
	s_setprio 0
	s_add_u32 s41, s41, 0x100
	s_addc_u32 s80, s80, 0
	s_add_u32 s74, s74, 0x100
	s_addc_u32 s75, s75, 0
	s_cmp_ge_i32 s81, s93
	s_mov_b32 s6, s81
	s_barrier
	s_cbranch_scc0 .LBB0_110
	s_branch .LBB0_97

; #define PG8_STAGE(bufoff, gbase, voff) do { _Pragma("unroll") for (int _i = 0; _i < 2; ++_i) \
;         __builtin_amdgcn_global_load_lds((const unsigned*)((const char*)(gbase) + (voff)[_i]), (LAS unsigned*)(lds + (bufoff) + ldsw + _i * 8192), 16, 0, 0); } while (0)
; #define PG8_LDA(dst, b, h) do { _Pragma("unroll") for (int m = 0; m < 4; ++m) _Pragma("unroll") for (int k = 0; k < 2; ++k) dst[m][k] = *(const LAS bf16x8*)(lds + PG8_SA(b, h) + aoff + m * 2048 + k * 1024); } while (0)
; #define PG8_LDB(dst, b, h) do { _Pragma("unroll") for (int n = 0; n < 2; ++n) _Pragma("unroll") for (int k = 0; k < 2; ++k) dst[n][k] = *(const LAS bf16x8*)(lds + PG8_SB(b, h) + boff + n * 2048 + k * 1024); } while (0)
; #define PG8_MMA(ai, bj, At, Bt) do { __builtin_amdgcn_s_setprio(1); _Pragma("unroll") for (int m = 0; m < 4; ++m) _Pragma("unroll") for (int n = 0; n < 2; ++n) _Pragma("unroll") for (int k = 0; k < 2; ++k) \
;         acc[ai][bj][m][n] = __builtin_amdgcn_mfma_f32_16x16x32_bf16(Bt[n][k], At[m][k], acc[ai][bj][m][n], 0, 0, 0); __builtin_amdgcn_s_setprio(0); } while (0)
; #define PG8_WAIT_L(n) asm volatile("s_waitcnt lgkmcnt(" #n ")" ::: "memory")
; #define PG8_BAR __builtin_amdgcn_s_barrier()
; #define PG8_SCHED __builtin_amdgcn_sched_barrier(0)
; template <class Epi, class Sched>
; DI void gemm_phase(LAS unsigned char* lds, const Gemm g, const Sched& S, const Epi& E) {
;     ...
;             PG8_LDB(B0, 0, 0); PG8_SCHED; PG8_LDA(At, 0, 0); PG8_STAGE(PG8_SA(1, 1), a1 + hstepA, voffA);
;             PG8_WAIT_L(8); PG8_BAR; PG8_WAIT_L(0); PG8_MMA(0, 0, At, B0); PG8_BAR; PG8_SCHED;
;             PG8_LDB(B1, 0, 1); PG8_STAGE(PG8_SB(0, 0), b2, voffB);
;             PG8_BAR; PG8_WAIT_L(0); PG8_MMA(0, 1, At, B1); PG8_BAR;
;             PG8_LDA(At, 0, 1); PG8_STAGE(PG8_SA(0, 0), a2, voffA);
;             PG8_BAR; PG8_WAIT_L(0); PG8_MMA(1, 0, At, B0); PG8_BAR; PG8_SCHED;
.LBB0_185:
	s_add_i32 s70, s6, 2
	s_add_u32 s8, s74, 0x80
	s_addc_u32 s7, s75, 0
	s_add_i32 s76, 0, 0x10000
	v_add_u32_e32 v142, s76, v160
	ds_read_b128 v[130:133], v142
	ds_read_b128 v[134:137], v142 offset:1024
	ds_read_b128 v[138:141], v142 offset:2048
	ds_read_b128 v[142:145], v142 offset:3072
	s_cmp_eq_u32 s23, s6
	s_cselect_b32 s6, s44, s8
	s_cselect_b32 s7, s45, s7
	s_cselect_b32 s9, s47, s31
	s_cselect_b32 s8, s46, s11
	v_lshl_add_u64 v[156:157], s[74:75], 0, v[150:151]
	s_add_i32 m0, s93, 0xc000
	ds_read_b128 v[152:155], v161
	ds_read_b128 v[162:165], v161 offset:1024
	ds_read_b128 v[168:171], v161 offset:2048
	ds_read_b128 v[172:175], v161 offset:3072
	ds_read_b128 v[176:179], v161 offset:4096
	ds_read_b128 v[196:199], v161 offset:5120
	ds_read_b128 v[200:203], v161 offset:6144
	ds_read_b128 v[204:207], v161 offset:7168
	global_load_lds_dwordx4 v[156:157], off
	v_lshl_add_u64 v[156:157], s[74:75], 0, v[148:149]
	s_add_i32 m0, s93, 0xe000
	s_nop 0
	global_load_lds_dwordx4 v[156:157], off
	s_waitcnt lgkmcnt(8)
	s_barrier
	s_setprio 1
	s_waitcnt lgkmcnt(7)
	v_mfma_f32_16x16x32_bf16 v[126:129], v[130:133], v[152:155], v[126:129]
	v_mfma_f32_16x16x32_bf16 v[122:125], v[138:141], v[152:155], v[122:125]
	s_waitcnt lgkmcnt(5)
	v_mfma_f32_16x16x32_bf16 v[110:113], v[130:133], v[168:171], v[110:113]
	v_mfma_f32_16x16x32_bf16 v[106:109], v[138:141], v[168:171], v[106:109]
	s_waitcnt lgkmcnt(3)
	v_mfma_f32_16x16x32_bf16 v[92:95], v[130:133], v[176:179], v[92:95]
	v_mfma_f32_16x16x32_bf16 v[88:91], v[138:141], v[176:179], v[88:91]
	s_waitcnt lgkmcnt(1)
	v_mfma_f32_16x16x32_bf16 v[76:79], v[130:133], v[200:203], v[76:79]
	v_mfma_f32_16x16x32_bf16 v[72:75], v[138:141], v[200:203], v[72:75]
	v_mfma_f32_16x16x32_bf16 v[126:129], v[134:137], v[162:165], v[126:129]
	v_mfma_f32_16x16x32_bf16 v[122:125], v[142:145], v[162:165], v[122:125]
	v_mfma_f32_16x16x32_bf16 v[110:113], v[134:137], v[172:175], v[110:113]
	v_mfma_f32_16x16x32_bf16 v[106:109], v[142:145], v[172:175], v[106:109]
	v_mfma_f32_16x16x32_bf16 v[92:95], v[134:137], v[196:199], v[92:95]
	v_mfma_f32_16x16x32_bf16 v[88:91], v[142:145], v[196:199], v[88:91]
	s_waitcnt lgkmcnt(0)
	v_mfma_f32_16x16x32_bf16 v[76:79], v[134:137], v[204:207], v[76:79]
	v_mfma_f32_16x16x32_bf16 v[72:75], v[142:145], v[204:207], v[72:75]
	s_setprio 0
	s_barrier
	s_add_i32 s77, 0, 0x14000
	v_add_u32_e32 v156, s77, v160
	s_add_i32 s76, s76, s90
	ds_read_b128 v[208:211], v156
	ds_read_b128 v[212:215], v156 offset:1024
	ds_read_b128 v[216:219], v156 offset:2048
	ds_read_b128 v[220:223], v156 offset:3072
	v_lshl_add_u64 v[156:157], s[8:9], 0, v[96:97]
	s_mov_b32 m0, s76
	v_lshl_add_u64 v[180:181], s[8:9], 0, v[146:147]
	global_load_lds_dwordx4 v[156:157], off
	s_add_i32 m0, s76, 0x2000
	s_nop 0
	global_load_lds_dwordx4 v[180:181], off
	s_barrier
	s_setprio 1
	s_waitcnt lgkmcnt(3)
	v_mfma_f32_16x16x32_bf16 v[118:121], v[208:211], v[152:155], v[118:121]
	s_waitcnt lgkmcnt(1)
	v_mfma_f32_16x16x32_bf16 v[114:117], v[216:219], v[152:155], v[114:117]
	v_mfma_f32_16x16x32_bf16 v[102:105], v[208:211], v[168:171], v[102:105]
	v_mfma_f32_16x16x32_bf16 v[98:101], v[216:219], v[168:171], v[98:101]
	v_mfma_f32_16x16x32_bf16 v[84:87], v[208:211], v[176:179], v[84:87]
	v_mfma_f32_16x16x32_bf16 v[80:83], v[216:219], v[176:179], v[80:83]
	v_mfma_f32_16x16x32_bf16 v[68:71], v[208:211], v[200:203], v[68:71]
	v_mfma_f32_16x16x32_bf16 v[64:67], v[216:219], v[200:203], v[64:67]
	v_mfma_f32_16x16x32_bf16 v[118:121], v[212:215], v[162:165], v[118:121]
	s_waitcnt lgkmcnt(0)
	v_mfma_f32_16x16x32_bf16 v[114:117], v[220:223], v[162:165], v[114:117]
	v_mfma_f32_16x16x32_bf16 v[102:105], v[212:215], v[172:175], v[102:105]
	v_mfma_f32_16x16x32_bf16 v[98:101], v[220:223], v[172:175], v[98:101]
	v_mfma_f32_16x16x32_bf16 v[84:87], v[212:215], v[196:199], v[84:87]
	v_mfma_f32_16x16x32_bf16 v[80:83], v[220:223], v[196:199], v[80:83]
	v_mfma_f32_16x16x32_bf16 v[68:71], v[212:215], v[204:207], v[68:71]
	v_mfma_f32_16x16x32_bf16 v[64:67], v[220:223], v[204:207], v[64:67]
	s_setprio 0
	s_mov_b32 m0, s93
	v_lshl_add_u64 v[224:225], s[6:7], 0, v[96:97]
	s_barrier
	ds_read_b128 v[152:155], v161 offset:16384
	ds_read_b128 v[162:165], v161 offset:17408
	ds_read_b128 v[168:171], v161 offset:18432
	ds_read_b128 v[172:175], v161 offset:19456
	ds_read_b128 v[176:179], v161 offset:20480
	ds_read_b128 v[196:199], v161 offset:21504
	ds_read_b128 v[200:203], v161 offset:22528
	ds_read_b128 v[204:207], v161 offset:23552
	global_load_lds_dwordx4 v[224:225], off
	v_lshl_add_u64 v[226:227], s[6:7], 0, v[146:147]
	s_mov_b32 m0, s94
	s_nop 0
	global_load_lds_dwordx4 v[226:227], off
	s_barrier
	s_setprio 1
	s_waitcnt lgkmcnt(7)
	v_mfma_f32_16x16x32_bf16 v[60:63], v[130:133], v[152:155], v[60:63]
	v_mfma_f32_16x16x32_bf16 v[56:59], v[138:141], v[152:155], v[56:59]
	s_waitcnt lgkmcnt(5)
	v_mfma_f32_16x16x32_bf16 v[44:47], v[130:133], v[168:171], v[44:47]
	v_mfma_f32_16x16x32_bf16 v[40:43], v[138:141], v[168:171], v[40:43]
	s_waitcnt lgkmcnt(3)
	v_mfma_f32_16x16x32_bf16 v[28:31], v[130:133], v[176:179], v[28:31]
	v_mfma_f32_16x16x32_bf16 v[24:27], v[138:141], v[176:179], v[24:27]
	s_waitcnt lgkmcnt(1)
	v_mfma_f32_16x16x32_bf16 v[12:15], v[130:133], v[200:203], v[12:15]
	v_mfma_f32_16x16x32_bf16 v[8:11], v[138:141], v[200:203], v[8:11]
	v_mfma_f32_16x16x32_bf16 v[60:63], v[134:137], v[162:165], v[60:63]
	v_mfma_f32_16x16x32_bf16 v[56:59], v[142:145], v[162:165], v[56:59]
	v_mfma_f32_16x16x32_bf16 v[44:47], v[134:137], v[172:175], v[44:47]
	v_mfma_f32_16x16x32_bf16 v[40:43], v[142:145], v[172:175], v[40:43]
	v_mfma_f32_16x16x32_bf16 v[28:31], v[134:137], v[196:199], v[28:31]
	v_mfma_f32_16x16x32_bf16 v[24:27], v[142:145], v[196:199], v[24:27]
	s_waitcnt lgkmcnt(0)
	v_mfma_f32_16x16x32_bf16 v[12:15], v[134:137], v[204:207], v[12:15]
	v_mfma_f32_16x16x32_bf16 v[8:11], v[142:145], v[204:207], v[8:11]
	s_setprio 0
	s_barrier
; #define PG8_STAGE(bufoff, gbase, voff) do { _Pragma("unroll") for (int _i = 0; _i < 2; ++_i) \
;         __builtin_amdgcn_global_load_lds((const unsigned*)((const char*)(gbase) + (voff)[_i]), (LAS unsigned*)(lds + (bufoff) + ldsw + _i * 8192), 16, 0, 0); } while (0)
; #define PG8_LDA(dst, b, h) do { _Pragma("unroll") for (int m = 0; m < 4; ++m) _Pragma("unroll") for (int k = 0; k < 2; ++k) dst[m][k] = *(const LAS bf16x8*)(lds + PG8_SA(b, h) + aoff + m * 2048 + k * 1024); } while (0)
; #define PG8_LDB(dst, b, h) do { _Pragma("unroll") for (int n = 0; n < 2; ++n) _Pragma("unroll") for (int k = 0; k < 2; ++k) dst[n][k] = *(const LAS bf16x8*)(lds + PG8_SB(b, h) + boff + n * 2048 + k * 1024); } while (0)
; #define PG8_MMA(ai, bj, At, Bt) do { __builtin_amdgcn_s_setprio(1); _Pragma("unroll") for (int m = 0; m < 4; ++m) _Pragma("unroll") for (int n = 0; n < 2; ++n) _Pragma("unroll") for (int k = 0; k < 2; ++k) \
;         acc[ai][bj][m][n] = __builtin_amdgcn_mfma_f32_16x16x32_bf16(Bt[n][k], At[m][k], acc[ai][bj][m][n], 0, 0, 0); __builtin_amdgcn_s_setprio(0); } while (0)
; #define PG8_WAIT_V(n) asm volatile("s_waitcnt vmcnt(" #n ")" ::: "memory")
; #define PG8_WAIT_L(n) asm volatile("s_waitcnt lgkmcnt(" #n ")" ::: "memory")
; #define PG8_BAR __builtin_amdgcn_s_barrier()
; #define PG8_SCHED __builtin_amdgcn_sched_barrier(0)
; template <class Epi, class Sched>
; DI void gemm_phase(LAS unsigned char* lds, const Gemm g, const Sched& S, const Epi& E) {
;     ...
;             PG8_STAGE(PG8_SB(0, 1), b2 + hstepB, voffB);
;             PG8_WAIT_V(6); PG8_BAR; PG8_MMA(1, 1, At, B1); PG8_BAR;
;             PG8_LDB(B0, 1, 0); PG8_SCHED; PG8_LDA(At, 1, 0); PG8_STAGE(PG8_SA(0, 1), a2 + hstepA, voffA);
;             PG8_WAIT_L(8); PG8_BAR; PG8_WAIT_L(0); PG8_MMA(0, 0, At, B0); PG8_BAR; PG8_SCHED;
;             PG8_LDB(B1, 1, 1); PG8_STAGE(PG8_SB(1, 0), b3, voffB);
	s_add_u32 s8, s8, s50
	s_addc_u32 s9, s9, s51
	s_add_i32 s76, s77, s90
	v_lshl_add_u64 v[228:229], s[8:9], 0, v[96:97]
	s_mov_b32 m0, s76
	v_lshl_add_u64 v[230:231], s[8:9], 0, v[146:147]
	global_load_lds_dwordx4 v[228:229], off
	s_add_i32 m0, s76, 0x2000
	s_nop 0
	global_load_lds_dwordx4 v[230:231], off
	s_waitcnt vmcnt(6)
	s_barrier
	s_setprio 1
	v_mfma_f32_16x16x32_bf16 v[52:55], v[208:211], v[152:155], v[52:55]
	v_mfma_f32_16x16x32_bf16 v[48:51], v[216:219], v[152:155], v[48:51]
	v_mfma_f32_16x16x32_bf16 v[36:39], v[208:211], v[168:171], v[36:39]
	v_mfma_f32_16x16x32_bf16 v[32:35], v[216:219], v[168:171], v[32:35]
	v_mfma_f32_16x16x32_bf16 v[20:23], v[208:211], v[176:179], v[20:23]
	v_mfma_f32_16x16x32_bf16 v[16:19], v[216:219], v[176:179], v[16:19]
	v_mfma_f32_16x16x32_bf16 v[4:7], v[208:211], v[200:203], v[4:7]
	v_mfma_f32_16x16x32_bf16 v[0:3], v[216:219], v[200:203], v[0:3]
	v_mfma_f32_16x16x32_bf16 v[52:55], v[212:215], v[162:165], v[52:55]
	v_mfma_f32_16x16x32_bf16 v[48:51], v[220:223], v[162:165], v[48:51]
	v_mfma_f32_16x16x32_bf16 v[36:39], v[212:215], v[172:175], v[36:39]
	v_mfma_f32_16x16x32_bf16 v[32:35], v[220:223], v[172:175], v[32:35]
	v_mfma_f32_16x16x32_bf16 v[20:23], v[212:215], v[196:199], v[20:23]
	v_mfma_f32_16x16x32_bf16 v[16:19], v[220:223], v[196:199], v[16:19]
	v_mfma_f32_16x16x32_bf16 v[4:7], v[212:215], v[204:207], v[4:7]
	v_mfma_f32_16x16x32_bf16 v[0:3], v[220:223], v[204:207], v[0:3]
	s_setprio 0
	s_add_i32 s8, 0, 0x18000
	v_add_u32_e32 v142, s8, v160
	s_barrier
	ds_read_b128 v[130:133], v142
	ds_read_b128 v[134:137], v142 offset:1024
	ds_read_b128 v[138:141], v142 offset:2048
	ds_read_b128 v[142:145], v142 offset:3072
	s_add_u32 s6, s6, s50
	s_addc_u32 s7, s7, s51
	s_mov_b32 m0, s95
	v_lshl_add_u64 v[208:209], s[6:7], 0, v[96:97]
	ds_read_b128 v[152:155], v161 offset:32768
	ds_read_b128 v[162:165], v161 offset:33792
	ds_read_b128 v[168:171], v161 offset:34816
	ds_read_b128 v[172:175], v161 offset:35840
	ds_read_b128 v[176:179], v161 offset:36864
	ds_read_b128 v[196:199], v161 offset:37888
	ds_read_b128 v[200:203], v161 offset:38912
	ds_read_b128 v[204:207], v161 offset:39936
	global_load_lds_dwordx4 v[208:209], off
	v_lshl_add_u64 v[208:209], s[6:7], 0, v[146:147]
	s_mov_b32 m0, s96
	s_nop 0
	global_load_lds_dwordx4 v[208:209], off
	s_waitcnt lgkmcnt(8)
	s_barrier
	s_setprio 1
	s_waitcnt lgkmcnt(7)
	v_mfma_f32_16x16x32_bf16 v[126:129], v[130:133], v[152:155], v[126:129]
	v_mfma_f32_16x16x32_bf16 v[122:125], v[138:141], v[152:155], v[122:125]
	s_waitcnt lgkmcnt(5)
	v_mfma_f32_16x16x32_bf16 v[110:113], v[130:133], v[168:171], v[110:113]
	v_mfma_f32_16x16x32_bf16 v[106:109], v[138:141], v[168:171], v[106:109]
	s_waitcnt lgkmcnt(3)
	v_mfma_f32_16x16x32_bf16 v[92:95], v[130:133], v[176:179], v[92:95]
	v_mfma_f32_16x16x32_bf16 v[88:91], v[138:141], v[176:179], v[88:91]
	s_waitcnt lgkmcnt(1)
	v_mfma_f32_16x16x32_bf16 v[76:79], v[130:133], v[200:203], v[76:79]
	v_mfma_f32_16x16x32_bf16 v[72:75], v[138:141], v[200:203], v[72:75]
	v_mfma_f32_16x16x32_bf16 v[126:129], v[134:137], v[162:165], v[126:129]
	v_mfma_f32_16x16x32_bf16 v[122:125], v[142:145], v[162:165], v[122:125]
	v_mfma_f32_16x16x32_bf16 v[110:113], v[134:137], v[172:175], v[110:113]
	v_mfma_f32_16x16x32_bf16 v[106:109], v[142:145], v[172:175], v[106:109]
	v_mfma_f32_16x16x32_bf16 v[92:95], v[134:137], v[196:199], v[92:95]
	v_mfma_f32_16x16x32_bf16 v[88:91], v[142:145], v[196:199], v[88:91]
	s_waitcnt lgkmcnt(0)
	v_mfma_f32_16x16x32_bf16 v[76:79], v[134:137], v[204:207], v[76:79]
	v_mfma_f32_16x16x32_bf16 v[72:75], v[142:145], v[204:207], v[72:75]
	s_setprio 0
	s_barrier
	s_add_i32 s6, 0, 0x1c000
	s_add_i32 s7, s8, s90
	v_add_u32_e32 v182, s6, v160
	v_lshl_add_u64 v[156:157], v[156:157], 0, s[28:29]
	s_mov_b32 m0, s7
	ds_read_b128 v[208:211], v182
	ds_read_b128 v[212:215], v182 offset:1024
	ds_read_b128 v[216:219], v182 offset:2048
	ds_read_b128 v[220:223], v182 offset:3072
	global_load_lds_dwordx4 v[156:157], off
	v_lshl_add_u64 v[156:157], v[180:181], 0, s[28:29]
	s_add_i32 m0, s7, 0x2000
	s_nop 0
	global_load_lds_dwordx4 v[156:157], off
	s_barrier
; #define PG8_STAGE(bufoff, gbase, voff) do { _Pragma("unroll") for (int _i = 0; _i < 2; ++_i) \
;         __builtin_amdgcn_global_load_lds((const unsigned*)((const char*)(gbase) + (voff)[_i]), (LAS unsigned*)(lds + (bufoff) + ldsw + _i * 8192), 16, 0, 0); } while (0)
; #define PG8_LDA(dst, b, h) do { _Pragma("unroll") for (int m = 0; m < 4; ++m) _Pragma("unroll") for (int k = 0; k < 2; ++k) dst[m][k] = *(const LAS bf16x8*)(lds + PG8_SA(b, h) + aoff + m * 2048 + k * 1024); } while (0)
; #define PG8_MMA(ai, bj, At, Bt) do { __builtin_amdgcn_s_setprio(1); _Pragma("unroll") for (int m = 0; m < 4; ++m) _Pragma("unroll") for (int n = 0; n < 2; ++n) _Pragma("unroll") for (int k = 0; k < 2; ++k) \
;         acc[ai][bj][m][n] = __builtin_amdgcn_mfma_f32_16x16x32_bf16(Bt[n][k], At[m][k], acc[ai][bj][m][n], 0, 0, 0); __builtin_amdgcn_s_setprio(0); } while (0)
; #define PG8_WAIT_V(n) asm volatile("s_waitcnt vmcnt(" #n ")" ::: "memory")
; #define PG8_WAIT_L(n) asm volatile("s_waitcnt lgkmcnt(" #n ")" ::: "memory")
; #define PG8_BAR __builtin_amdgcn_s_barrier()
; #define PG8_SCHED __builtin_amdgcn_sched_barrier(0)
; template <class Epi, class Sched>
; DI void gemm_phase(LAS unsigned char* lds, const Gemm g, const Sched& S, const Epi& E) {
;     ...
;             PG8_BAR; PG8_WAIT_L(0); PG8_MMA(0, 1, At, B1); PG8_BAR;
;             PG8_LDA(At, 1, 1); PG8_STAGE(PG8_SA(1, 0), a3, voffA);
;             PG8_BAR; PG8_WAIT_L(0); PG8_MMA(1, 0, At, B0); PG8_BAR; PG8_SCHED;
;             PG8_STAGE(PG8_SB(1, 1), b3 + hstepB, voffB);
;             PG8_WAIT_V(6); PG8_BAR; PG8_MMA(1, 1, At, B1); PG8_BAR;
;         }
	s_setprio 1
	s_waitcnt lgkmcnt(3)
	v_mfma_f32_16x16x32_bf16 v[118:121], v[208:211], v[152:155], v[118:121]
	s_waitcnt lgkmcnt(1)
	v_mfma_f32_16x16x32_bf16 v[114:117], v[216:219], v[152:155], v[114:117]
	v_mfma_f32_16x16x32_bf16 v[102:105], v[208:211], v[168:171], v[102:105]
	v_mfma_f32_16x16x32_bf16 v[98:101], v[216:219], v[168:171], v[98:101]
	v_mfma_f32_16x16x32_bf16 v[84:87], v[208:211], v[176:179], v[84:87]
	v_mfma_f32_16x16x32_bf16 v[80:83], v[216:219], v[176:179], v[80:83]
	v_mfma_f32_16x16x32_bf16 v[68:71], v[208:211], v[200:203], v[68:71]
	v_mfma_f32_16x16x32_bf16 v[64:67], v[216:219], v[200:203], v[64:67]
	v_mfma_f32_16x16x32_bf16 v[118:121], v[212:215], v[162:165], v[118:121]
	s_waitcnt lgkmcnt(0)
	v_mfma_f32_16x16x32_bf16 v[114:117], v[220:223], v[162:165], v[114:117]
	v_mfma_f32_16x16x32_bf16 v[102:105], v[212:215], v[172:175], v[102:105]
	v_mfma_f32_16x16x32_bf16 v[98:101], v[220:223], v[172:175], v[98:101]
	v_mfma_f32_16x16x32_bf16 v[84:87], v[212:215], v[196:199], v[84:87]
	v_mfma_f32_16x16x32_bf16 v[80:83], v[220:223], v[196:199], v[80:83]
	v_mfma_f32_16x16x32_bf16 v[68:71], v[212:215], v[204:207], v[68:71]
	v_mfma_f32_16x16x32_bf16 v[64:67], v[220:223], v[204:207], v[64:67]
	s_setprio 0
	s_mov_b32 m0, s60
	v_lshl_add_u64 v[156:157], v[224:225], 0, s[28:29]
	s_barrier
	ds_read_b128 v[152:155], v161 offset:49152
	ds_read_b128 v[162:165], v161 offset:50176
	ds_read_b128 v[168:171], v161 offset:51200
	ds_read_b128 v[172:175], v161 offset:52224
	ds_read_b128 v[176:179], v161 offset:53248
	ds_read_b128 v[196:199], v161 offset:54272
	ds_read_b128 v[200:203], v161 offset:55296
	ds_read_b128 v[204:207], v161 offset:56320
	global_load_lds_dwordx4 v[156:157], off
	v_lshl_add_u64 v[156:157], v[226:227], 0, s[28:29]
	s_mov_b32 m0, s61
	s_nop 0
	global_load_lds_dwordx4 v[156:157], off
	s_barrier
	s_setprio 1
	s_waitcnt lgkmcnt(7)
	v_mfma_f32_16x16x32_bf16 v[60:63], v[130:133], v[152:155], v[60:63]
	v_mfma_f32_16x16x32_bf16 v[56:59], v[138:141], v[152:155], v[56:59]
	s_waitcnt lgkmcnt(5)
	v_mfma_f32_16x16x32_bf16 v[44:47], v[130:133], v[168:171], v[44:47]
	v_mfma_f32_16x16x32_bf16 v[40:43], v[138:141], v[168:171], v[40:43]
	s_waitcnt lgkmcnt(3)
	v_mfma_f32_16x16x32_bf16 v[28:31], v[130:133], v[176:179], v[28:31]
	v_mfma_f32_16x16x32_bf16 v[24:27], v[138:141], v[176:179], v[24:27]
	s_waitcnt lgkmcnt(1)
	v_mfma_f32_16x16x32_bf16 v[12:15], v[130:133], v[200:203], v[12:15]
	v_mfma_f32_16x16x32_bf16 v[8:11], v[138:141], v[200:203], v[8:11]
	v_mfma_f32_16x16x32_bf16 v[60:63], v[134:137], v[162:165], v[60:63]
	v_mfma_f32_16x16x32_bf16 v[56:59], v[142:145], v[162:165], v[56:59]
	v_mfma_f32_16x16x32_bf16 v[44:47], v[134:137], v[172:175], v[44:47]
	v_mfma_f32_16x16x32_bf16 v[40:43], v[142:145], v[172:175], v[40:43]
	v_mfma_f32_16x16x32_bf16 v[28:31], v[134:137], v[196:199], v[28:31]
	v_mfma_f32_16x16x32_bf16 v[24:27], v[142:145], v[196:199], v[24:27]
	s_waitcnt lgkmcnt(0)
	v_mfma_f32_16x16x32_bf16 v[12:15], v[134:137], v[204:207], v[12:15]
	v_mfma_f32_16x16x32_bf16 v[8:11], v[142:145], v[204:207], v[8:11]
	s_setprio 0
	s_barrier
	s_add_i32 s6, s6, s90
	v_lshl_add_u64 v[130:131], v[228:229], 0, s[28:29]
	s_mov_b32 m0, s6
	s_nop 0
	global_load_lds_dwordx4 v[130:131], off
	v_lshl_add_u64 v[130:131], v[230:231], 0, s[28:29]
	s_add_i32 m0, s6, 0x2000
	s_nop 0
	global_load_lds_dwordx4 v[130:131], off
	s_waitcnt vmcnt(6)
	s_barrier
	s_setprio 1
	v_mfma_f32_16x16x32_bf16 v[52:55], v[208:211], v[152:155], v[52:55]
	v_mfma_f32_16x16x32_bf16 v[48:51], v[216:219], v[152:155], v[48:51]
	v_mfma_f32_16x16x32_bf16 v[36:39], v[208:211], v[168:171], v[36:39]
	v_mfma_f32_16x16x32_bf16 v[32:35], v[216:219], v[168:171], v[32:35]
	v_mfma_f32_16x16x32_bf16 v[20:23], v[208:211], v[176:179], v[20:23]
	v_mfma_f32_16x16x32_bf16 v[16:19], v[216:219], v[176:179], v[16:19]
	v_mfma_f32_16x16x32_bf16 v[4:7], v[208:211], v[200:203], v[4:7]
	v_mfma_f32_16x16x32_bf16 v[0:3], v[216:219], v[200:203], v[0:3]
	v_mfma_f32_16x16x32_bf16 v[52:55], v[212:215], v[162:165], v[52:55]
	v_mfma_f32_16x16x32_bf16 v[48:51], v[220:223], v[162:165], v[48:51]
	v_mfma_f32_16x16x32_bf16 v[36:39], v[212:215], v[172:175], v[36:39]
	v_mfma_f32_16x16x32_bf16 v[32:35], v[220:223], v[172:175], v[32:35]
	v_mfma_f32_16x16x32_bf16 v[20:23], v[212:215], v[196:199], v[20:23]
	v_mfma_f32_16x16x32_bf16 v[16:19], v[220:223], v[196:199], v[16:19]
	v_mfma_f32_16x16x32_bf16 v[4:7], v[212:215], v[204:207], v[4:7]
	v_mfma_f32_16x16x32_bf16 v[0:3], v[220:223], v[204:207], v[0:3]
	s_setprio 0
	s_add_u32 s11, s11, 0x100
	s_addc_u32 s31, s31, 0
	s_add_u32 s74, s74, 0x100
	s_addc_u32 s75, s75, 0
	s_cmp_ge_i32 s70, s41
	s_mov_b32 s6, s70
	s_barrier
	s_cbranch_scc0 .LBB0_185
	s_movk_i32 s70, 0x300

; #define PG8_STAGE(bufoff, gbase, voff) do { _Pragma("unroll") for (int _i = 0; _i < 2; ++_i) \
;         __builtin_amdgcn_global_load_lds((const unsigned*)((const char*)(gbase) + (voff)[_i]), (LAS unsigned*)(lds + (bufoff) + ldsw + _i * 8192), 16, 0, 0); } while (0)
; #define PG8_LDA(dst, b, h) do { _Pragma("unroll") for (int m = 0; m < 4; ++m) _Pragma("unroll") for (int k = 0; k < 2; ++k) dst[m][k] = *(const LAS bf16x8*)(lds + PG8_SA(b, h) + aoff + m * 2048 + k * 1024); } while (0)
; #define PG8_LDB(dst, b, h) do { _Pragma("unroll") for (int n = 0; n < 2; ++n) _Pragma("unroll") for (int k = 0; k < 2; ++k) dst[n][k] = *(const LAS bf16x8*)(lds + PG8_SB(b, h) + boff + n * 2048 + k * 1024); } while (0)
; #define PG8_MMA(ai, bj, At, Bt) do { __builtin_amdgcn_s_setprio(1); _Pragma("unroll") for (int m = 0; m < 4; ++m) _Pragma("unroll") for (int n = 0; n < 2; ++n) _Pragma("unroll") for (int k = 0; k < 2; ++k) \
;         acc[ai][bj][m][n] = __builtin_amdgcn_mfma_f32_16x16x32_bf16(Bt[n][k], At[m][k], acc[ai][bj][m][n], 0, 0, 0); __builtin_amdgcn_s_setprio(0); } while (0)
; #define PG8_WAIT_L(n) asm volatile("s_waitcnt lgkmcnt(" #n ")" ::: "memory")
; #define PG8_BAR __builtin_amdgcn_s_barrier()
; #define PG8_SCHED __builtin_amdgcn_sched_barrier(0)
; template <class Epi, class Sched>
; DI void gemm_phase(LAS unsigned char* lds, const Gemm g, const Sched& S, const Epi& E) {
;     ...
;             PG8_LDB(B0, 0, 0); PG8_SCHED; PG8_LDA(At, 0, 0); PG8_STAGE(PG8_SA(1, 1), a1 + hstepA, voffA);
;             PG8_WAIT_L(8); PG8_BAR; PG8_WAIT_L(0); PG8_MMA(0, 0, At, B0); PG8_BAR; PG8_SCHED;
;             PG8_LDB(B1, 0, 1); PG8_STAGE(PG8_SB(0, 0), b2, voffB);
;             PG8_BAR; PG8_WAIT_L(0); PG8_MMA(0, 1, At, B1); PG8_BAR;
;             PG8_LDA(At, 0, 1); PG8_STAGE(PG8_SA(0, 0), a2, voffA);
;             PG8_BAR; PG8_WAIT_L(0); PG8_MMA(1, 0, At, B0); PG8_BAR; PG8_SCHED;
.LBB0_315:
	s_add_i32 s27, s6, 2
	s_add_u32 s44, s48, 0x100
	s_addc_u32 s45, s49, 0
	s_waitcnt lgkmcnt(0)
	s_add_i32 s30, 0, 0x10000
	v_add_u32_e32 v152, s30, v156
	ds_read_b128 v[80:83], v152
	ds_read_b128 v[84:87], v152 offset:1024
	ds_read_b128 v[148:151], v152 offset:2048
	ds_read_b128 v[158:161], v152 offset:3072
	s_cmp_eq_u32 s50, s6
	s_cselect_b32 s6, s4, s24
	s_cselect_b32 s9, s37, s45
	s_cselect_b32 s8, s36, s44
	s_cselect_b32 s7, s5, s26
	v_lshl_add_u64 v[152:153], s[48:49], 0, v[146:147]
	s_add_i32 m0, s70, 0xc000
	ds_read_b128 v[162:165], v157
	ds_read_b128 v[168:171], v157 offset:1024
	ds_read_b128 v[172:175], v157 offset:2048
	ds_read_b128 v[176:179], v157 offset:3072
	ds_read_b128 v[196:199], v157 offset:4096
	ds_read_b128 v[200:203], v157 offset:5120
	ds_read_b128 v[204:207], v157 offset:6144
	ds_read_b128 v[208:211], v157 offset:7168
	global_load_lds_dwordx4 v[152:153], off
	v_lshl_add_u64 v[152:153], s[48:49], 0, v[144:145]
	s_add_i32 m0, s70, 0xe000
	s_nop 0
	global_load_lds_dwordx4 v[152:153], off
	s_waitcnt lgkmcnt(8)
	s_barrier
	s_setprio 1
	s_waitcnt lgkmcnt(7)
	v_mfma_f32_16x16x32_bf16 v[130:133], v[80:83], v[162:165], v[130:133]
	v_mfma_f32_16x16x32_bf16 v[134:137], v[148:151], v[162:165], v[134:137]
	s_waitcnt lgkmcnt(5)
	v_mfma_f32_16x16x32_bf16 v[126:129], v[80:83], v[172:175], v[126:129]
	v_mfma_f32_16x16x32_bf16 v[122:125], v[148:151], v[172:175], v[122:125]
	s_waitcnt lgkmcnt(3)
	v_mfma_f32_16x16x32_bf16 v[118:121], v[80:83], v[196:199], v[118:121]
	v_mfma_f32_16x16x32_bf16 v[114:117], v[148:151], v[196:199], v[114:117]
	s_waitcnt lgkmcnt(1)
	v_mfma_f32_16x16x32_bf16 v[110:113], v[80:83], v[204:207], v[110:113]
	v_mfma_f32_16x16x32_bf16 v[106:109], v[148:151], v[204:207], v[106:109]
	v_mfma_f32_16x16x32_bf16 v[130:133], v[84:87], v[168:171], v[130:133]
	v_mfma_f32_16x16x32_bf16 v[134:137], v[158:161], v[168:171], v[134:137]
	v_mfma_f32_16x16x32_bf16 v[126:129], v[84:87], v[176:179], v[126:129]
	v_mfma_f32_16x16x32_bf16 v[122:125], v[158:161], v[176:179], v[122:125]
	v_mfma_f32_16x16x32_bf16 v[118:121], v[84:87], v[200:203], v[118:121]
	v_mfma_f32_16x16x32_bf16 v[114:117], v[158:161], v[200:203], v[114:117]
	s_waitcnt lgkmcnt(0)
	v_mfma_f32_16x16x32_bf16 v[110:113], v[84:87], v[208:211], v[110:113]
	v_mfma_f32_16x16x32_bf16 v[106:109], v[158:161], v[208:211], v[106:109]
	s_setprio 0
	s_barrier
	s_add_i32 s41, 0, 0x14000
	v_add_u32_e32 v152, s41, v156
	s_add_i32 s30, s30, s93
	ds_read_b128 v[212:215], v152
	ds_read_b128 v[216:219], v152 offset:1024
	ds_read_b128 v[220:223], v152 offset:2048
	ds_read_b128 v[224:227], v152 offset:3072
	v_lshl_add_u64 v[152:153], s[6:7], 0, v[96:97]
	s_mov_b32 m0, s30
	v_lshl_add_u64 v[180:181], s[6:7], 0, v[142:143]
	global_load_lds_dwordx4 v[152:153], off
	s_add_i32 m0, s30, 0x2000
	s_nop 0
	global_load_lds_dwordx4 v[180:181], off
	s_barrier
	s_setprio 1
	s_waitcnt lgkmcnt(3)
	v_mfma_f32_16x16x32_bf16 v[60:63], v[212:215], v[162:165], v[60:63]
	s_waitcnt lgkmcnt(1)
	v_mfma_f32_16x16x32_bf16 v[56:59], v[220:223], v[162:165], v[56:59]
	v_mfma_f32_16x16x32_bf16 v[52:55], v[212:215], v[172:175], v[52:55]
	v_mfma_f32_16x16x32_bf16 v[48:51], v[220:223], v[172:175], v[48:51]
	v_mfma_f32_16x16x32_bf16 v[44:47], v[212:215], v[196:199], v[44:47]
	v_mfma_f32_16x16x32_bf16 v[40:43], v[220:223], v[196:199], v[40:43]
	v_mfma_f32_16x16x32_bf16 v[36:39], v[212:215], v[204:207], v[36:39]
	v_mfma_f32_16x16x32_bf16 v[32:35], v[220:223], v[204:207], v[32:35]
	v_mfma_f32_16x16x32_bf16 v[60:63], v[216:219], v[168:171], v[60:63]
	s_waitcnt lgkmcnt(0)
	v_mfma_f32_16x16x32_bf16 v[56:59], v[224:227], v[168:171], v[56:59]
	v_mfma_f32_16x16x32_bf16 v[52:55], v[216:219], v[176:179], v[52:55]
	v_mfma_f32_16x16x32_bf16 v[48:51], v[224:227], v[176:179], v[48:51]
	v_mfma_f32_16x16x32_bf16 v[44:47], v[216:219], v[200:203], v[44:47]
	v_mfma_f32_16x16x32_bf16 v[40:43], v[224:227], v[200:203], v[40:43]
	v_mfma_f32_16x16x32_bf16 v[36:39], v[216:219], v[208:211], v[36:39]
	v_mfma_f32_16x16x32_bf16 v[32:35], v[224:227], v[208:211], v[32:35]
	s_setprio 0
	s_mov_b32 m0, s70
	v_lshl_add_u64 v[228:229], s[8:9], 0, v[138:139]
	s_barrier
	ds_read_b128 v[162:165], v157 offset:16384
	ds_read_b128 v[168:171], v157 offset:17408
	ds_read_b128 v[172:175], v157 offset:18432
	ds_read_b128 v[176:179], v157 offset:19456
	ds_read_b128 v[196:199], v157 offset:20480
	ds_read_b128 v[200:203], v157 offset:21504
	ds_read_b128 v[204:207], v157 offset:22528
	ds_read_b128 v[208:211], v157 offset:23552
	global_load_lds_dwordx4 v[228:229], off
	v_lshl_add_u64 v[230:231], s[8:9], 0, v[140:141]
	s_mov_b32 m0, s76
	s_nop 0
	global_load_lds_dwordx4 v[230:231], off
	s_barrier
	s_setprio 1
	s_waitcnt lgkmcnt(7)
	v_mfma_f32_16x16x32_bf16 v[102:105], v[80:83], v[162:165], v[102:105]
	v_mfma_f32_16x16x32_bf16 v[98:101], v[148:151], v[162:165], v[98:101]
	s_waitcnt lgkmcnt(5)
	v_mfma_f32_16x16x32_bf16 v[92:95], v[80:83], v[172:175], v[92:95]
	v_mfma_f32_16x16x32_bf16 v[88:91], v[148:151], v[172:175], v[88:91]
	s_waitcnt lgkmcnt(3)
	v_mfma_f32_16x16x32_bf16 v[76:79], v[80:83], v[196:199], v[76:79]
	v_mfma_f32_16x16x32_bf16 v[72:75], v[148:151], v[196:199], v[72:75]
	s_waitcnt lgkmcnt(1)
	v_mfma_f32_16x16x32_bf16 v[68:71], v[80:83], v[204:207], v[68:71]
	v_mfma_f32_16x16x32_bf16 v[64:67], v[148:151], v[204:207], v[64:67]
	v_mfma_f32_16x16x32_bf16 v[102:105], v[84:87], v[168:171], v[102:105]
	v_mfma_f32_16x16x32_bf16 v[98:101], v[158:161], v[168:171], v[98:101]
	v_mfma_f32_16x16x32_bf16 v[92:95], v[84:87], v[176:179], v[92:95]
	v_mfma_f32_16x16x32_bf16 v[88:91], v[158:161], v[176:179], v[88:91]
	v_mfma_f32_16x16x32_bf16 v[76:79], v[84:87], v[200:203], v[76:79]
	v_mfma_f32_16x16x32_bf16 v[72:75], v[158:161], v[200:203], v[72:75]
	s_waitcnt lgkmcnt(0)
	v_mfma_f32_16x16x32_bf16 v[68:71], v[84:87], v[208:211], v[68:71]
	v_mfma_f32_16x16x32_bf16 v[64:67], v[158:161], v[208:211], v[64:67]
	s_setprio 0
	s_barrier
; #define PG8_STAGE(bufoff, gbase, voff) do { _Pragma("unroll") for (int _i = 0; _i < 2; ++_i) \
;         __builtin_amdgcn_global_load_lds((const unsigned*)((const char*)(gbase) + (voff)[_i]), (LAS unsigned*)(lds + (bufoff) + ldsw + _i * 8192), 16, 0, 0); } while (0)
; #define PG8_LDA(dst, b, h) do { _Pragma("unroll") for (int m = 0; m < 4; ++m) _Pragma("unroll") for (int k = 0; k < 2; ++k) dst[m][k] = *(const LAS bf16x8*)(lds + PG8_SA(b, h) + aoff + m * 2048 + k * 1024); } while (0)
; #define PG8_LDB(dst, b, h) do { _Pragma("unroll") for (int n = 0; n < 2; ++n) _Pragma("unroll") for (int k = 0; k < 2; ++k) dst[n][k] = *(const LAS bf16x8*)(lds + PG8_SB(b, h) + boff + n * 2048 + k * 1024); } while (0)
; #define PG8_MMA(ai, bj, At, Bt) do { __builtin_amdgcn_s_setprio(1); _Pragma("unroll") for (int m = 0; m < 4; ++m) _Pragma("unroll") for (int n = 0; n < 2; ++n) _Pragma("unroll") for (int k = 0; k < 2; ++k) \
;         acc[ai][bj][m][n] = __builtin_amdgcn_mfma_f32_16x16x32_bf16(Bt[n][k], At[m][k], acc[ai][bj][m][n], 0, 0, 0); __builtin_amdgcn_s_setprio(0); } while (0)
; #define PG8_WAIT_V(n) asm volatile("s_waitcnt vmcnt(" #n ")" ::: "memory")
; #define PG8_WAIT_L(n) asm volatile("s_waitcnt lgkmcnt(" #n ")" ::: "memory")
; #define PG8_BAR __builtin_amdgcn_s_barrier()
; #define PG8_SCHED __builtin_amdgcn_sched_barrier(0)
; template <class Epi, class Sched>
; DI void gemm_phase(LAS unsigned char* lds, const Gemm g, const Sched& S, const Epi& E) {
;     ...
;             PG8_STAGE(PG8_SB(0, 1), b2 + hstepB, voffB);
;             PG8_WAIT_V(6); PG8_BAR; PG8_MMA(1, 1, At, B1); PG8_BAR;
;             PG8_LDB(B0, 1, 0); PG8_SCHED; PG8_LDA(At, 1, 0); PG8_STAGE(PG8_SA(0, 1), a2 + hstepA, voffA);
;             PG8_WAIT_L(8); PG8_BAR; PG8_WAIT_L(0); PG8_MMA(0, 0, At, B0); PG8_BAR; PG8_SCHED;
;             PG8_LDB(B1, 1, 1); PG8_STAGE(PG8_SB(1, 0), b3, voffB);
	s_add_u32 s30, s6, 0x28000
	s_addc_u32 s31, s7, 0
	s_add_i32 s41, s41, s93
	v_lshl_add_u64 v[80:81], s[30:31], 0, v[96:97]
	s_mov_b32 m0, s41
	s_nop 0
	global_load_lds_dwordx4 v[80:81], off
	v_lshl_add_u64 v[80:81], s[30:31], 0, v[142:143]
	s_add_i32 m0, s41, 0x2000
	s_nop 0
	global_load_lds_dwordx4 v[80:81], off
	s_waitcnt vmcnt(6)
	s_barrier
	s_setprio 1
	v_mfma_f32_16x16x32_bf16 v[28:31], v[212:215], v[162:165], v[28:31]
	v_mfma_f32_16x16x32_bf16 v[24:27], v[220:223], v[162:165], v[24:27]
	v_mfma_f32_16x16x32_bf16 v[20:23], v[212:215], v[172:175], v[20:23]
	v_mfma_f32_16x16x32_bf16 v[16:19], v[220:223], v[172:175], v[16:19]
	v_mfma_f32_16x16x32_bf16 v[12:15], v[212:215], v[196:199], v[12:15]
	v_mfma_f32_16x16x32_bf16 v[8:11], v[220:223], v[196:199], v[8:11]
	v_mfma_f32_16x16x32_bf16 v[4:7], v[212:215], v[204:207], v[4:7]
	v_mfma_f32_16x16x32_bf16 v[0:3], v[220:223], v[204:207], v[0:3]
	v_mfma_f32_16x16x32_bf16 v[28:31], v[216:219], v[168:171], v[28:31]
	v_mfma_f32_16x16x32_bf16 v[24:27], v[224:227], v[168:171], v[24:27]
	v_mfma_f32_16x16x32_bf16 v[20:23], v[216:219], v[176:179], v[20:23]
	v_mfma_f32_16x16x32_bf16 v[16:19], v[224:227], v[176:179], v[16:19]
	v_mfma_f32_16x16x32_bf16 v[12:15], v[216:219], v[200:203], v[12:15]
	v_mfma_f32_16x16x32_bf16 v[8:11], v[224:227], v[200:203], v[8:11]
	v_mfma_f32_16x16x32_bf16 v[4:7], v[216:219], v[208:211], v[4:7]
	v_mfma_f32_16x16x32_bf16 v[0:3], v[224:227], v[208:211], v[0:3]
	s_setprio 0
	s_add_i32 s30, 0, 0x18000
	v_add_u32_e32 v158, s30, v156
	s_barrier
	ds_read_b128 v[80:83], v158
	ds_read_b128 v[84:87], v158 offset:1024
	ds_read_b128 v[148:151], v158 offset:2048
	ds_read_b128 v[158:161], v158 offset:3072
	s_add_u32 s8, s8, 0x28000
	s_addc_u32 s9, s9, 0
	s_mov_b32 m0, s77
	v_lshl_add_u64 v[212:213], s[8:9], 0, v[138:139]
	ds_read_b128 v[162:165], v157 offset:32768
	ds_read_b128 v[168:171], v157 offset:33792
	ds_read_b128 v[172:175], v157 offset:34816
	ds_read_b128 v[176:179], v157 offset:35840
	ds_read_b128 v[196:199], v157 offset:36864
	ds_read_b128 v[200:203], v157 offset:37888
	ds_read_b128 v[204:207], v157 offset:38912
	ds_read_b128 v[208:211], v157 offset:39936
	global_load_lds_dwordx4 v[212:213], off
	v_lshl_add_u64 v[212:213], s[8:9], 0, v[140:141]
	s_mov_b32 m0, s94
	s_nop 0
	global_load_lds_dwordx4 v[212:213], off
	s_waitcnt lgkmcnt(8)
	s_barrier
	s_setprio 1
	s_waitcnt lgkmcnt(7)
	v_mfma_f32_16x16x32_bf16 v[130:133], v[80:83], v[162:165], v[130:133]
	v_mfma_f32_16x16x32_bf16 v[134:137], v[148:151], v[162:165], v[134:137]
	s_waitcnt lgkmcnt(5)
	v_mfma_f32_16x16x32_bf16 v[126:129], v[80:83], v[172:175], v[126:129]
	v_mfma_f32_16x16x32_bf16 v[122:125], v[148:151], v[172:175], v[122:125]
	s_waitcnt lgkmcnt(3)
	v_mfma_f32_16x16x32_bf16 v[118:121], v[80:83], v[196:199], v[118:121]
	v_mfma_f32_16x16x32_bf16 v[114:117], v[148:151], v[196:199], v[114:117]
	s_waitcnt lgkmcnt(1)
	v_mfma_f32_16x16x32_bf16 v[110:113], v[80:83], v[204:207], v[110:113]
	v_mfma_f32_16x16x32_bf16 v[106:109], v[148:151], v[204:207], v[106:109]
	v_mfma_f32_16x16x32_bf16 v[130:133], v[84:87], v[168:171], v[130:133]
	v_mfma_f32_16x16x32_bf16 v[134:137], v[158:161], v[168:171], v[134:137]
	v_mfma_f32_16x16x32_bf16 v[126:129], v[84:87], v[176:179], v[126:129]
	v_mfma_f32_16x16x32_bf16 v[122:125], v[158:161], v[176:179], v[122:125]
	v_mfma_f32_16x16x32_bf16 v[118:121], v[84:87], v[200:203], v[118:121]
	v_mfma_f32_16x16x32_bf16 v[114:117], v[158:161], v[200:203], v[114:117]
	s_waitcnt lgkmcnt(0)
	v_mfma_f32_16x16x32_bf16 v[110:113], v[84:87], v[208:211], v[110:113]
	v_mfma_f32_16x16x32_bf16 v[106:109], v[158:161], v[208:211], v[106:109]
	s_setprio 0
	s_barrier
	s_add_i32 s8, 0, 0x1c000
	s_add_i32 s9, s30, s93
	v_add_u32_e32 v182, s8, v156
	v_lshl_add_u64 v[152:153], v[152:153], 0, s[28:29]
	s_mov_b32 m0, s9
	ds_read_b128 v[212:215], v182
	ds_read_b128 v[216:219], v182 offset:1024
	ds_read_b128 v[220:223], v182 offset:2048
	ds_read_b128 v[224:227], v182 offset:3072
	global_load_lds_dwordx4 v[152:153], off
	v_lshl_add_u64 v[152:153], v[180:181], 0, s[28:29]
	s_add_i32 m0, s9, 0x2000
	s_nop 0
	global_load_lds_dwordx4 v[152:153], off
	s_barrier
; #define PG8_STAGE(bufoff, gbase, voff) do { _Pragma("unroll") for (int _i = 0; _i < 2; ++_i) \
;         __builtin_amdgcn_global_load_lds((const unsigned*)((const char*)(gbase) + (voff)[_i]), (LAS unsigned*)(lds + (bufoff) + ldsw + _i * 8192), 16, 0, 0); } while (0)
; #define PG8_LDA(dst, b, h) do { _Pragma("unroll") for (int m = 0; m < 4; ++m) _Pragma("unroll") for (int k = 0; k < 2; ++k) dst[m][k] = *(const LAS bf16x8*)(lds + PG8_SA(b, h) + aoff + m * 2048 + k * 1024); } while (0)
; #define PG8_MMA(ai, bj, At, Bt) do { __builtin_amdgcn_s_setprio(1); _Pragma("unroll") for (int m = 0; m < 4; ++m) _Pragma("unroll") for (int n = 0; n < 2; ++n) _Pragma("unroll") for (int k = 0; k < 2; ++k) \
;         acc[ai][bj][m][n] = __builtin_amdgcn_mfma_f32_16x16x32_bf16(Bt[n][k], At[m][k], acc[ai][bj][m][n], 0, 0, 0); __builtin_amdgcn_s_setprio(0); } while (0)
; #define PG8_WAIT_V(n) asm volatile("s_waitcnt vmcnt(" #n ")" ::: "memory")
; #define PG8_WAIT_L(n) asm volatile("s_waitcnt lgkmcnt(" #n ")" ::: "memory")
; #define PG8_BAR __builtin_amdgcn_s_barrier()
; #define PG8_SCHED __builtin_amdgcn_sched_barrier(0)
; template <class Epi, class Sched>
; DI void gemm_phase(LAS unsigned char* lds, const Gemm g, const Sched& S, const Epi& E) {
;     ...
;             PG8_BAR; PG8_WAIT_L(0); PG8_MMA(0, 1, At, B1); PG8_BAR;
;             PG8_LDA(At, 1, 1); PG8_STAGE(PG8_SA(1, 0), a3, voffA);
;             PG8_BAR; PG8_WAIT_L(0); PG8_MMA(1, 0, At, B0); PG8_BAR; PG8_SCHED;
;             PG8_STAGE(PG8_SB(1, 1), b3 + hstepB, voffB);
;             PG8_WAIT_V(6); PG8_BAR; PG8_MMA(1, 1, At, B1); PG8_BAR;
;         }
	s_setprio 1
	s_waitcnt lgkmcnt(3)
	v_mfma_f32_16x16x32_bf16 v[60:63], v[212:215], v[162:165], v[60:63]
	s_waitcnt lgkmcnt(1)
	v_mfma_f32_16x16x32_bf16 v[56:59], v[220:223], v[162:165], v[56:59]
	v_mfma_f32_16x16x32_bf16 v[52:55], v[212:215], v[172:175], v[52:55]
	v_mfma_f32_16x16x32_bf16 v[48:51], v[220:223], v[172:175], v[48:51]
	v_mfma_f32_16x16x32_bf16 v[44:47], v[212:215], v[196:199], v[44:47]
	v_mfma_f32_16x16x32_bf16 v[40:43], v[220:223], v[196:199], v[40:43]
	v_mfma_f32_16x16x32_bf16 v[36:39], v[212:215], v[204:207], v[36:39]
	v_mfma_f32_16x16x32_bf16 v[32:35], v[220:223], v[204:207], v[32:35]
	v_mfma_f32_16x16x32_bf16 v[60:63], v[216:219], v[168:171], v[60:63]
	s_waitcnt lgkmcnt(0)
	v_mfma_f32_16x16x32_bf16 v[56:59], v[224:227], v[168:171], v[56:59]
	v_mfma_f32_16x16x32_bf16 v[52:55], v[216:219], v[176:179], v[52:55]
	v_mfma_f32_16x16x32_bf16 v[48:51], v[224:227], v[176:179], v[48:51]
	v_mfma_f32_16x16x32_bf16 v[44:47], v[216:219], v[200:203], v[44:47]
	v_mfma_f32_16x16x32_bf16 v[40:43], v[224:227], v[200:203], v[40:43]
	v_mfma_f32_16x16x32_bf16 v[36:39], v[216:219], v[208:211], v[36:39]
	v_mfma_f32_16x16x32_bf16 v[32:35], v[224:227], v[208:211], v[32:35]
	s_setprio 0
	s_mov_b32 m0, s53
	v_lshl_add_u64 v[152:153], v[228:229], 0, s[28:29]
	s_barrier
	ds_read_b128 v[162:165], v157 offset:49152
	ds_read_b128 v[168:171], v157 offset:50176
	ds_read_b128 v[172:175], v157 offset:51200
	ds_read_b128 v[176:179], v157 offset:52224
	ds_read_b128 v[196:199], v157 offset:53248
	ds_read_b128 v[200:203], v157 offset:54272
	ds_read_b128 v[204:207], v157 offset:55296
	ds_read_b128 v[208:211], v157 offset:56320
	global_load_lds_dwordx4 v[152:153], off
	v_lshl_add_u64 v[152:153], v[230:231], 0, s[28:29]
	s_mov_b32 m0, s97
	s_nop 0
	global_load_lds_dwordx4 v[152:153], off
	s_barrier
	s_setprio 1
	s_waitcnt lgkmcnt(7)
	v_mfma_f32_16x16x32_bf16 v[102:105], v[80:83], v[162:165], v[102:105]
	v_mfma_f32_16x16x32_bf16 v[98:101], v[148:151], v[162:165], v[98:101]
	s_waitcnt lgkmcnt(5)
	v_mfma_f32_16x16x32_bf16 v[92:95], v[80:83], v[172:175], v[92:95]
	v_mfma_f32_16x16x32_bf16 v[88:91], v[148:151], v[172:175], v[88:91]
	s_waitcnt lgkmcnt(3)
	v_mfma_f32_16x16x32_bf16 v[76:79], v[80:83], v[196:199], v[76:79]
	v_mfma_f32_16x16x32_bf16 v[72:75], v[148:151], v[196:199], v[72:75]
	s_waitcnt lgkmcnt(1)
	v_mfma_f32_16x16x32_bf16 v[68:71], v[80:83], v[204:207], v[68:71]
	v_mfma_f32_16x16x32_bf16 v[64:67], v[148:151], v[204:207], v[64:67]
	v_mfma_f32_16x16x32_bf16 v[102:105], v[84:87], v[168:171], v[102:105]
	v_mfma_f32_16x16x32_bf16 v[98:101], v[158:161], v[168:171], v[98:101]
	v_mfma_f32_16x16x32_bf16 v[92:95], v[84:87], v[176:179], v[92:95]
	v_mfma_f32_16x16x32_bf16 v[88:91], v[158:161], v[176:179], v[88:91]
	v_mfma_f32_16x16x32_bf16 v[76:79], v[84:87], v[200:203], v[76:79]
	v_mfma_f32_16x16x32_bf16 v[72:75], v[158:161], v[200:203], v[72:75]
	s_waitcnt lgkmcnt(0)
	v_mfma_f32_16x16x32_bf16 v[68:71], v[84:87], v[208:211], v[68:71]
	v_mfma_f32_16x16x32_bf16 v[64:67], v[158:161], v[208:211], v[64:67]
	s_setprio 0
	s_barrier
	s_add_u32 s6, s6, 0x28080
	s_addc_u32 s7, s7, 0
	s_add_i32 s8, s8, s93
	v_lshl_add_u64 v[80:81], s[6:7], 0, v[96:97]
	s_mov_b32 m0, s8
	s_nop 0
	global_load_lds_dwordx4 v[80:81], off
	v_lshl_add_u64 v[80:81], s[6:7], 0, v[142:143]
	s_add_i32 m0, s8, 0x2000
	s_nop 0
	global_load_lds_dwordx4 v[80:81], off
	s_waitcnt vmcnt(6)
	s_barrier
	s_setprio 1
	v_mfma_f32_16x16x32_bf16 v[28:31], v[212:215], v[162:165], v[28:31]
	v_mfma_f32_16x16x32_bf16 v[24:27], v[220:223], v[162:165], v[24:27]
	v_mfma_f32_16x16x32_bf16 v[20:23], v[212:215], v[172:175], v[20:23]
	v_mfma_f32_16x16x32_bf16 v[16:19], v[220:223], v[172:175], v[16:19]
	v_mfma_f32_16x16x32_bf16 v[12:15], v[212:215], v[196:199], v[12:15]
	v_mfma_f32_16x16x32_bf16 v[8:11], v[220:223], v[196:199], v[8:11]
	v_mfma_f32_16x16x32_bf16 v[4:7], v[212:215], v[204:207], v[4:7]
	v_mfma_f32_16x16x32_bf16 v[0:3], v[220:223], v[204:207], v[0:3]
	v_mfma_f32_16x16x32_bf16 v[28:31], v[216:219], v[168:171], v[28:31]
	v_mfma_f32_16x16x32_bf16 v[24:27], v[224:227], v[168:171], v[24:27]
	v_mfma_f32_16x16x32_bf16 v[20:23], v[216:219], v[176:179], v[20:23]
	v_mfma_f32_16x16x32_bf16 v[16:19], v[224:227], v[176:179], v[16:19]
	v_mfma_f32_16x16x32_bf16 v[12:15], v[216:219], v[200:203], v[12:15]
	v_mfma_f32_16x16x32_bf16 v[8:11], v[224:227], v[200:203], v[8:11]
	v_mfma_f32_16x16x32_bf16 v[4:7], v[216:219], v[208:211], v[4:7]
	v_mfma_f32_16x16x32_bf16 v[0:3], v[224:227], v[208:211], v[0:3]
	s_setprio 0
	s_add_u32 s24, s24, 0x100
	s_addc_u32 s26, s26, 0
	s_cmp_ge_i32 s27, s96
	s_mov_b64 s[48:49], s[44:45]
	s_mov_b32 s6, s27
	s_barrier
	s_cbranch_scc0 .LBB0_315
	s_load_dwordx2 s[30:31], s[0:1], 0x70

; #define PG8_STAGE(bufoff, gbase, voff) do { _Pragma("unroll") for (int _i = 0; _i < 2; ++_i) \
;         __builtin_amdgcn_global_load_lds((const unsigned*)((const char*)(gbase) + (voff)[_i]), (LAS unsigned*)(lds + (bufoff) + ldsw + _i * 8192), 16, 0, 0); } while (0)
; #define PG8_LDA(dst, b, h) do { _Pragma("unroll") for (int m = 0; m < 4; ++m) _Pragma("unroll") for (int k = 0; k < 2; ++k) dst[m][k] = *(const LAS bf16x8*)(lds + PG8_SA(b, h) + aoff + m * 2048 + k * 1024); } while (0)
; #define PG8_LDB(dst, b, h) do { _Pragma("unroll") for (int n = 0; n < 2; ++n) _Pragma("unroll") for (int k = 0; k < 2; ++k) dst[n][k] = *(const LAS bf16x8*)(lds + PG8_SB(b, h) + boff + n * 2048 + k * 1024); } while (0)
; #define PG8_MMA(ai, bj, At, Bt) do { __builtin_amdgcn_s_setprio(1); _Pragma("unroll") for (int m = 0; m < 4; ++m) _Pragma("unroll") for (int n = 0; n < 2; ++n) _Pragma("unroll") for (int k = 0; k < 2; ++k) \
;         acc[ai][bj][m][n] = __builtin_amdgcn_mfma_f32_16x16x32_bf16(Bt[n][k], At[m][k], acc[ai][bj][m][n], 0, 0, 0); __builtin_amdgcn_s_setprio(0); } while (0)
; #define PG8_WAIT_L(n) asm volatile("s_waitcnt lgkmcnt(" #n ")" ::: "memory")
; #define PG8_BAR __builtin_amdgcn_s_barrier()
; #define PG8_SCHED __builtin_amdgcn_sched_barrier(0)
; template <class Epi, class Sched>
; DI void gemm_phase(LAS unsigned char* lds, const Gemm g, const Sched& S, const Epi& E) {
;     ...
;             PG8_LDB(B0, 0, 0); PG8_SCHED; PG8_LDA(At, 0, 0); PG8_STAGE(PG8_SA(1, 1), a1 + hstepA, voffA);
;             PG8_WAIT_L(8); PG8_BAR; PG8_WAIT_L(0); PG8_MMA(0, 0, At, B0); PG8_BAR; PG8_SCHED;
;             PG8_LDB(B1, 0, 1); PG8_STAGE(PG8_SB(0, 0), b2, voffB);
;             PG8_BAR; PG8_WAIT_L(0); PG8_MMA(0, 1, At, B1); PG8_BAR;
;             PG8_LDA(At, 0, 1); PG8_STAGE(PG8_SA(0, 0), a2, voffA);
;             PG8_BAR; PG8_WAIT_L(0); PG8_MMA(1, 0, At, B0); PG8_BAR; PG8_SCHED;
.LBB0_635:
	s_add_i32 s61, s6, 2
	s_add_u32 s8, s44, 0x80
	s_addc_u32 s7, s45, 0
	s_add_i32 s68, 0, 0x10000
	v_add_u32_e32 v96, s68, v148
	ds_read_b128 v[142:145], v96
	ds_read_b128 v[150:153], v96 offset:1024
	ds_read_b128 v[154:157], v96 offset:2048
	ds_read_b128 v[158:161], v96 offset:3072
	s_cmp_eq_u32 s88, s6
	s_cselect_b32 s6, s56, s8
	s_cselect_b32 s7, s57, s7
	s_cselect_b32 s9, s47, s31
	s_cselect_b32 s8, s46, s30
	v_lshl_add_u64 v[180:181], s[44:45], 0, v[140:141]
	s_add_i32 m0, s70, 0xc000
	ds_read_b128 v[162:165], v149
	ds_read_b128 v[168:171], v149 offset:1024
	ds_read_b128 v[172:175], v149 offset:2048
	ds_read_b128 v[176:179], v149 offset:3072
	ds_read_b128 v[196:199], v149 offset:4096
	ds_read_b128 v[200:203], v149 offset:5120
	ds_read_b128 v[204:207], v149 offset:6144
	ds_read_b128 v[208:211], v149 offset:7168
	global_load_lds_dwordx4 v[180:181], off
	v_lshl_add_u64 v[180:181], s[44:45], 0, v[138:139]
	s_add_i32 m0, s70, 0xe000
	s_nop 0
	global_load_lds_dwordx4 v[180:181], off
	s_waitcnt lgkmcnt(8)
	s_barrier
	s_setprio 1
	s_waitcnt lgkmcnt(7)
	v_mfma_f32_16x16x32_bf16 v[122:125], v[142:145], v[162:165], v[122:125]
	v_mfma_f32_16x16x32_bf16 v[126:129], v[154:157], v[162:165], v[126:129]
	s_waitcnt lgkmcnt(5)
	v_mfma_f32_16x16x32_bf16 v[110:113], v[142:145], v[172:175], v[110:113]
	v_mfma_f32_16x16x32_bf16 v[106:109], v[154:157], v[172:175], v[106:109]
	s_waitcnt lgkmcnt(3)
	v_mfma_f32_16x16x32_bf16 v[92:95], v[142:145], v[196:199], v[92:95]
	v_mfma_f32_16x16x32_bf16 v[88:91], v[154:157], v[196:199], v[88:91]
	s_waitcnt lgkmcnt(1)
	v_mfma_f32_16x16x32_bf16 v[76:79], v[142:145], v[204:207], v[76:79]
	v_mfma_f32_16x16x32_bf16 v[72:75], v[154:157], v[204:207], v[72:75]
	v_mfma_f32_16x16x32_bf16 v[122:125], v[150:153], v[168:171], v[122:125]
	v_mfma_f32_16x16x32_bf16 v[126:129], v[158:161], v[168:171], v[126:129]
	v_mfma_f32_16x16x32_bf16 v[110:113], v[150:153], v[176:179], v[110:113]
	v_mfma_f32_16x16x32_bf16 v[106:109], v[158:161], v[176:179], v[106:109]
	v_mfma_f32_16x16x32_bf16 v[92:95], v[150:153], v[200:203], v[92:95]
	v_mfma_f32_16x16x32_bf16 v[88:91], v[158:161], v[200:203], v[88:91]
	s_waitcnt lgkmcnt(0)
	v_mfma_f32_16x16x32_bf16 v[76:79], v[150:153], v[208:211], v[76:79]
	v_mfma_f32_16x16x32_bf16 v[72:75], v[158:161], v[208:211], v[72:75]
	s_setprio 0
	s_barrier
	s_add_i32 s69, 0, 0x14000
	s_add_i32 s68, s68, s27
	v_add_u32_e32 v96, s69, v148
	v_lshl_add_u64 v[180:181], s[8:9], 0, v[132:133]
	s_mov_b32 m0, s68
	ds_read_b128 v[212:215], v96
	ds_read_b128 v[216:219], v96 offset:1024
	ds_read_b128 v[220:223], v96 offset:2048
	ds_read_b128 v[224:227], v96 offset:3072
	global_load_lds_dwordx4 v[180:181], off
	v_lshl_add_u64 v[228:229], s[8:9], 0, v[136:137]
	s_add_i32 m0, s68, 0x2000
	s_nop 0
	global_load_lds_dwordx4 v[228:229], off
	s_barrier
	s_setprio 1
	s_waitcnt lgkmcnt(3)
	v_mfma_f32_16x16x32_bf16 v[118:121], v[212:215], v[162:165], v[118:121]
	s_waitcnt lgkmcnt(1)
	v_mfma_f32_16x16x32_bf16 v[114:117], v[220:223], v[162:165], v[114:117]
	v_mfma_f32_16x16x32_bf16 v[102:105], v[212:215], v[172:175], v[102:105]
	v_mfma_f32_16x16x32_bf16 v[98:101], v[220:223], v[172:175], v[98:101]
	v_mfma_f32_16x16x32_bf16 v[84:87], v[212:215], v[196:199], v[84:87]
	v_mfma_f32_16x16x32_bf16 v[80:83], v[220:223], v[196:199], v[80:83]
	v_mfma_f32_16x16x32_bf16 v[68:71], v[212:215], v[204:207], v[68:71]
	v_mfma_f32_16x16x32_bf16 v[64:67], v[220:223], v[204:207], v[64:67]
	v_mfma_f32_16x16x32_bf16 v[118:121], v[216:219], v[168:171], v[118:121]
	s_waitcnt lgkmcnt(0)
	v_mfma_f32_16x16x32_bf16 v[114:117], v[224:227], v[168:171], v[114:117]
	v_mfma_f32_16x16x32_bf16 v[102:105], v[216:219], v[176:179], v[102:105]
	v_mfma_f32_16x16x32_bf16 v[98:101], v[224:227], v[176:179], v[98:101]
	v_mfma_f32_16x16x32_bf16 v[84:87], v[216:219], v[200:203], v[84:87]
	v_mfma_f32_16x16x32_bf16 v[80:83], v[224:227], v[200:203], v[80:83]
	v_mfma_f32_16x16x32_bf16 v[68:71], v[216:219], v[208:211], v[68:71]
	v_mfma_f32_16x16x32_bf16 v[64:67], v[224:227], v[208:211], v[64:67]
	s_setprio 0
	s_mov_b32 m0, s70
	v_lshl_add_u64 v[230:231], s[6:7], 0, v[130:131]
	s_barrier
	ds_read_b128 v[162:165], v149 offset:16384
	ds_read_b128 v[168:171], v149 offset:17408
	ds_read_b128 v[172:175], v149 offset:18432
	ds_read_b128 v[176:179], v149 offset:19456
	ds_read_b128 v[196:199], v149 offset:20480
	ds_read_b128 v[200:203], v149 offset:21504
	ds_read_b128 v[204:207], v149 offset:22528
	ds_read_b128 v[208:211], v149 offset:23552
	global_load_lds_dwordx4 v[230:231], off
	v_lshl_add_u64 v[232:233], s[6:7], 0, v[134:135]
	s_mov_b32 m0, s76
	s_nop 0
	global_load_lds_dwordx4 v[232:233], off
	s_barrier
	s_setprio 1
	s_waitcnt lgkmcnt(7)
	v_mfma_f32_16x16x32_bf16 v[60:63], v[142:145], v[162:165], v[60:63]
	v_mfma_f32_16x16x32_bf16 v[56:59], v[154:157], v[162:165], v[56:59]
	s_waitcnt lgkmcnt(5)
	v_mfma_f32_16x16x32_bf16 v[44:47], v[142:145], v[172:175], v[44:47]
	v_mfma_f32_16x16x32_bf16 v[40:43], v[154:157], v[172:175], v[40:43]
	s_waitcnt lgkmcnt(3)
	v_mfma_f32_16x16x32_bf16 v[28:31], v[142:145], v[196:199], v[28:31]
	v_mfma_f32_16x16x32_bf16 v[24:27], v[154:157], v[196:199], v[24:27]
	s_waitcnt lgkmcnt(1)
	v_mfma_f32_16x16x32_bf16 v[12:15], v[142:145], v[204:207], v[12:15]
	v_mfma_f32_16x16x32_bf16 v[8:11], v[154:157], v[204:207], v[8:11]
	v_mfma_f32_16x16x32_bf16 v[60:63], v[150:153], v[168:171], v[60:63]
	v_mfma_f32_16x16x32_bf16 v[56:59], v[158:161], v[168:171], v[56:59]
	v_mfma_f32_16x16x32_bf16 v[44:47], v[150:153], v[176:179], v[44:47]
	v_mfma_f32_16x16x32_bf16 v[40:43], v[158:161], v[176:179], v[40:43]
	v_mfma_f32_16x16x32_bf16 v[28:31], v[150:153], v[200:203], v[28:31]
	v_mfma_f32_16x16x32_bf16 v[24:27], v[158:161], v[200:203], v[24:27]
	s_waitcnt lgkmcnt(0)
	v_mfma_f32_16x16x32_bf16 v[12:15], v[150:153], v[208:211], v[12:15]
	v_mfma_f32_16x16x32_bf16 v[8:11], v[158:161], v[208:211], v[8:11]
	s_setprio 0
	s_barrier
; #define PG8_STAGE(bufoff, gbase, voff) do { _Pragma("unroll") for (int _i = 0; _i < 2; ++_i) \
;         __builtin_amdgcn_global_load_lds((const unsigned*)((const char*)(gbase) + (voff)[_i]), (LAS unsigned*)(lds + (bufoff) + ldsw + _i * 8192), 16, 0, 0); } while (0)
; #define PG8_LDA(dst, b, h) do { _Pragma("unroll") for (int m = 0; m < 4; ++m) _Pragma("unroll") for (int k = 0; k < 2; ++k) dst[m][k] = *(const LAS bf16x8*)(lds + PG8_SA(b, h) + aoff + m * 2048 + k * 1024); } while (0)
; #define PG8_LDB(dst, b, h) do { _Pragma("unroll") for (int n = 0; n < 2; ++n) _Pragma("unroll") for (int k = 0; k < 2; ++k) dst[n][k] = *(const LAS bf16x8*)(lds + PG8_SB(b, h) + boff + n * 2048 + k * 1024); } while (0)
; #define PG8_MMA(ai, bj, At, Bt) do { __builtin_amdgcn_s_setprio(1); _Pragma("unroll") for (int m = 0; m < 4; ++m) _Pragma("unroll") for (int n = 0; n < 2; ++n) _Pragma("unroll") for (int k = 0; k < 2; ++k) \
;         acc[ai][bj][m][n] = __builtin_amdgcn_mfma_f32_16x16x32_bf16(Bt[n][k], At[m][k], acc[ai][bj][m][n], 0, 0, 0); __builtin_amdgcn_s_setprio(0); } while (0)
; #define PG8_WAIT_V(n) asm volatile("s_waitcnt vmcnt(" #n ")" ::: "memory")
; #define PG8_WAIT_L(n) asm volatile("s_waitcnt lgkmcnt(" #n ")" ::: "memory")
; #define PG8_BAR __builtin_amdgcn_s_barrier()
; #define PG8_SCHED __builtin_amdgcn_sched_barrier(0)
; template <class Epi, class Sched>
; DI void gemm_phase(LAS unsigned char* lds, const Gemm g, const Sched& S, const Epi& E) {
;     ...
;             PG8_STAGE(PG8_SB(0, 1), b2 + hstepB, voffB);
;             PG8_WAIT_V(6); PG8_BAR; PG8_MMA(1, 1, At, B1); PG8_BAR;
;             PG8_LDB(B0, 1, 0); PG8_SCHED; PG8_LDA(At, 1, 0); PG8_STAGE(PG8_SA(0, 1), a2 + hstepA, voffA);
;             PG8_WAIT_L(8); PG8_BAR; PG8_WAIT_L(0); PG8_MMA(0, 0, At, B0); PG8_BAR; PG8_SCHED;
;             PG8_LDB(B1, 1, 1); PG8_STAGE(PG8_SB(1, 0), b3, voffB);
	s_add_u32 s8, s8, s36
	s_addc_u32 s9, s9, s37
	s_add_i32 s68, s69, s27
	v_lshl_add_u64 v[234:235], s[8:9], 0, v[132:133]
	s_mov_b32 m0, s68
	v_lshl_add_u64 v[236:237], s[8:9], 0, v[136:137]
	global_load_lds_dwordx4 v[234:235], off
	s_add_i32 m0, s68, 0x2000
	s_nop 0
	global_load_lds_dwordx4 v[236:237], off
	s_waitcnt vmcnt(6)
	s_barrier
	s_setprio 1
	v_mfma_f32_16x16x32_bf16 v[52:55], v[212:215], v[162:165], v[52:55]
	v_mfma_f32_16x16x32_bf16 v[48:51], v[220:223], v[162:165], v[48:51]
	v_mfma_f32_16x16x32_bf16 v[36:39], v[212:215], v[172:175], v[36:39]
	v_mfma_f32_16x16x32_bf16 v[32:35], v[220:223], v[172:175], v[32:35]
	v_mfma_f32_16x16x32_bf16 v[20:23], v[212:215], v[196:199], v[20:23]
	v_mfma_f32_16x16x32_bf16 v[16:19], v[220:223], v[196:199], v[16:19]
	v_mfma_f32_16x16x32_bf16 v[4:7], v[212:215], v[204:207], v[4:7]
	v_mfma_f32_16x16x32_bf16 v[0:3], v[220:223], v[204:207], v[0:3]
	v_mfma_f32_16x16x32_bf16 v[52:55], v[216:219], v[168:171], v[52:55]
	v_mfma_f32_16x16x32_bf16 v[48:51], v[224:227], v[168:171], v[48:51]
	v_mfma_f32_16x16x32_bf16 v[36:39], v[216:219], v[176:179], v[36:39]
	v_mfma_f32_16x16x32_bf16 v[32:35], v[224:227], v[176:179], v[32:35]
	v_mfma_f32_16x16x32_bf16 v[20:23], v[216:219], v[200:203], v[20:23]
	v_mfma_f32_16x16x32_bf16 v[16:19], v[224:227], v[200:203], v[16:19]
	v_mfma_f32_16x16x32_bf16 v[4:7], v[216:219], v[208:211], v[4:7]
	v_mfma_f32_16x16x32_bf16 v[0:3], v[224:227], v[208:211], v[0:3]
	s_setprio 0
	s_add_i32 s8, 0, 0x18000
	v_add_u32_e32 v96, s8, v148
	s_barrier
	ds_read_b128 v[142:145], v96
	ds_read_b128 v[150:153], v96 offset:1024
	ds_read_b128 v[154:157], v96 offset:2048
	ds_read_b128 v[158:161], v96 offset:3072
	s_add_u32 s6, s6, s36
	s_addc_u32 s7, s7, s37
	s_mov_b32 m0, s77
	v_lshl_add_u64 v[212:213], s[6:7], 0, v[130:131]
	ds_read_b128 v[162:165], v149 offset:32768
	ds_read_b128 v[168:171], v149 offset:33792
	ds_read_b128 v[172:175], v149 offset:34816
	ds_read_b128 v[176:179], v149 offset:35840
	ds_read_b128 v[196:199], v149 offset:36864
	ds_read_b128 v[200:203], v149 offset:37888
	ds_read_b128 v[204:207], v149 offset:38912
	ds_read_b128 v[208:211], v149 offset:39936
	global_load_lds_dwordx4 v[212:213], off
	v_lshl_add_u64 v[212:213], s[6:7], 0, v[134:135]
	s_mov_b32 m0, s82
	s_nop 0
	global_load_lds_dwordx4 v[212:213], off
	s_waitcnt lgkmcnt(8)
	s_barrier
	s_setprio 1
	s_waitcnt lgkmcnt(7)
	v_mfma_f32_16x16x32_bf16 v[122:125], v[142:145], v[162:165], v[122:125]
	v_mfma_f32_16x16x32_bf16 v[126:129], v[154:157], v[162:165], v[126:129]
	s_waitcnt lgkmcnt(5)
	v_mfma_f32_16x16x32_bf16 v[110:113], v[142:145], v[172:175], v[110:113]
	v_mfma_f32_16x16x32_bf16 v[106:109], v[154:157], v[172:175], v[106:109]
	s_waitcnt lgkmcnt(3)
	v_mfma_f32_16x16x32_bf16 v[92:95], v[142:145], v[196:199], v[92:95]
	v_mfma_f32_16x16x32_bf16 v[88:91], v[154:157], v[196:199], v[88:91]
	s_waitcnt lgkmcnt(1)
	v_mfma_f32_16x16x32_bf16 v[76:79], v[142:145], v[204:207], v[76:79]
	v_mfma_f32_16x16x32_bf16 v[72:75], v[154:157], v[204:207], v[72:75]
	v_mfma_f32_16x16x32_bf16 v[122:125], v[150:153], v[168:171], v[122:125]
	v_mfma_f32_16x16x32_bf16 v[126:129], v[158:161], v[168:171], v[126:129]
	v_mfma_f32_16x16x32_bf16 v[110:113], v[150:153], v[176:179], v[110:113]
	v_mfma_f32_16x16x32_bf16 v[106:109], v[158:161], v[176:179], v[106:109]
	v_mfma_f32_16x16x32_bf16 v[92:95], v[150:153], v[200:203], v[92:95]
	v_mfma_f32_16x16x32_bf16 v[88:91], v[158:161], v[200:203], v[88:91]
	s_waitcnt lgkmcnt(0)
	v_mfma_f32_16x16x32_bf16 v[76:79], v[150:153], v[208:211], v[76:79]
	v_mfma_f32_16x16x32_bf16 v[72:75], v[158:161], v[208:211], v[72:75]
	s_setprio 0
	s_barrier
	s_add_i32 s6, 0, 0x1c000
	s_add_i32 s7, s8, s27
	v_add_u32_e32 v96, s6, v148
	v_lshl_add_u64 v[180:181], v[180:181], 0, s[28:29]
	s_mov_b32 m0, s7
	ds_read_b128 v[212:215], v96
	ds_read_b128 v[216:219], v96 offset:1024
	ds_read_b128 v[220:223], v96 offset:2048
	ds_read_b128 v[224:227], v96 offset:3072
	global_load_lds_dwordx4 v[180:181], off
	v_lshl_add_u64 v[180:181], v[228:229], 0, s[28:29]
	s_add_i32 m0, s7, 0x2000
	s_nop 0
	global_load_lds_dwordx4 v[180:181], off
	s_barrier
; #define PG8_STAGE(bufoff, gbase, voff) do { _Pragma("unroll") for (int _i = 0; _i < 2; ++_i) \
;         __builtin_amdgcn_global_load_lds((const unsigned*)((const char*)(gbase) + (voff)[_i]), (LAS unsigned*)(lds + (bufoff) + ldsw + _i * 8192), 16, 0, 0); } while (0)
; #define PG8_LDA(dst, b, h) do { _Pragma("unroll") for (int m = 0; m < 4; ++m) _Pragma("unroll") for (int k = 0; k < 2; ++k) dst[m][k] = *(const LAS bf16x8*)(lds + PG8_SA(b, h) + aoff + m * 2048 + k * 1024); } while (0)
; #define PG8_MMA(ai, bj, At, Bt) do { __builtin_amdgcn_s_setprio(1); _Pragma("unroll") for (int m = 0; m < 4; ++m) _Pragma("unroll") for (int n = 0; n < 2; ++n) _Pragma("unroll") for (int k = 0; k < 2; ++k) \
;         acc[ai][bj][m][n] = __builtin_amdgcn_mfma_f32_16x16x32_bf16(Bt[n][k], At[m][k], acc[ai][bj][m][n], 0, 0, 0); __builtin_amdgcn_s_setprio(0); } while (0)
; #define PG8_WAIT_V(n) asm volatile("s_waitcnt vmcnt(" #n ")" ::: "memory")
; #define PG8_WAIT_L(n) asm volatile("s_waitcnt lgkmcnt(" #n ")" ::: "memory")
; #define PG8_BAR __builtin_amdgcn_s_barrier()
; #define PG8_SCHED __builtin_amdgcn_sched_barrier(0)
; template <class Epi, class Sched>
; DI void gemm_phase(LAS unsigned char* lds, const Gemm g, const Sched& S, const Epi& E) {
;     ...
;             PG8_BAR; PG8_WAIT_L(0); PG8_MMA(0, 1, At, B1); PG8_BAR;
;             PG8_LDA(At, 1, 1); PG8_STAGE(PG8_SA(1, 0), a3, voffA);
;             PG8_BAR; PG8_WAIT_L(0); PG8_MMA(1, 0, At, B0); PG8_BAR; PG8_SCHED;
;             PG8_STAGE(PG8_SB(1, 1), b3 + hstepB, voffB);
;             PG8_WAIT_V(6); PG8_BAR; PG8_MMA(1, 1, At, B1); PG8_BAR;
	s_setprio 1
	s_waitcnt lgkmcnt(3)
	v_mfma_f32_16x16x32_bf16 v[118:121], v[212:215], v[162:165], v[118:121]
	s_waitcnt lgkmcnt(1)
	v_mfma_f32_16x16x32_bf16 v[114:117], v[220:223], v[162:165], v[114:117]
	v_mfma_f32_16x16x32_bf16 v[102:105], v[212:215], v[172:175], v[102:105]
	v_mfma_f32_16x16x32_bf16 v[98:101], v[220:223], v[172:175], v[98:101]
	v_mfma_f32_16x16x32_bf16 v[84:87], v[212:215], v[196:199], v[84:87]
	v_mfma_f32_16x16x32_bf16 v[80:83], v[220:223], v[196:199], v[80:83]
	v_mfma_f32_16x16x32_bf16 v[68:71], v[212:215], v[204:207], v[68:71]
	v_mfma_f32_16x16x32_bf16 v[64:67], v[220:223], v[204:207], v[64:67]
	v_mfma_f32_16x16x32_bf16 v[118:121], v[216:219], v[168:171], v[118:121]
	s_waitcnt lgkmcnt(0)
	v_mfma_f32_16x16x32_bf16 v[114:117], v[224:227], v[168:171], v[114:117]
	v_mfma_f32_16x16x32_bf16 v[102:105], v[216:219], v[176:179], v[102:105]
	v_mfma_f32_16x16x32_bf16 v[98:101], v[224:227], v[176:179], v[98:101]
	v_mfma_f32_16x16x32_bf16 v[84:87], v[216:219], v[200:203], v[84:87]
	v_mfma_f32_16x16x32_bf16 v[80:83], v[224:227], v[200:203], v[80:83]
	v_mfma_f32_16x16x32_bf16 v[68:71], v[216:219], v[208:211], v[68:71]
	v_mfma_f32_16x16x32_bf16 v[64:67], v[224:227], v[208:211], v[64:67]
	s_setprio 0
	s_mov_b32 m0, s86
	v_lshl_add_u64 v[180:181], v[230:231], 0, s[28:29]
	s_barrier
	ds_read_b128 v[162:165], v149 offset:49152
	ds_read_b128 v[168:171], v149 offset:50176
	ds_read_b128 v[172:175], v149 offset:51200
	ds_read_b128 v[176:179], v149 offset:52224
	ds_read_b128 v[196:199], v149 offset:53248
	ds_read_b128 v[200:203], v149 offset:54272
	ds_read_b128 v[204:207], v149 offset:55296
	ds_read_b128 v[208:211], v149 offset:56320
	global_load_lds_dwordx4 v[180:181], off
	v_lshl_add_u64 v[180:181], v[232:233], 0, s[28:29]
	s_mov_b32 m0, s87
	s_nop 0
	global_load_lds_dwordx4 v[180:181], off
	s_barrier
	s_setprio 1
	s_waitcnt lgkmcnt(7)
	v_mfma_f32_16x16x32_bf16 v[60:63], v[142:145], v[162:165], v[60:63]
	v_mfma_f32_16x16x32_bf16 v[56:59], v[154:157], v[162:165], v[56:59]
	s_waitcnt lgkmcnt(5)
	v_mfma_f32_16x16x32_bf16 v[44:47], v[142:145], v[172:175], v[44:47]
	v_mfma_f32_16x16x32_bf16 v[40:43], v[154:157], v[172:175], v[40:43]
	s_waitcnt lgkmcnt(3)
	v_mfma_f32_16x16x32_bf16 v[28:31], v[142:145], v[196:199], v[28:31]
	v_mfma_f32_16x16x32_bf16 v[24:27], v[154:157], v[196:199], v[24:27]
	s_waitcnt lgkmcnt(1)
	v_mfma_f32_16x16x32_bf16 v[12:15], v[142:145], v[204:207], v[12:15]
	v_mfma_f32_16x16x32_bf16 v[8:11], v[154:157], v[204:207], v[8:11]
	v_mfma_f32_16x16x32_bf16 v[60:63], v[150:153], v[168:171], v[60:63]
	v_mfma_f32_16x16x32_bf16 v[56:59], v[158:161], v[168:171], v[56:59]
	v_mfma_f32_16x16x32_bf16 v[44:47], v[150:153], v[176:179], v[44:47]
	v_mfma_f32_16x16x32_bf16 v[40:43], v[158:161], v[176:179], v[40:43]
	v_mfma_f32_16x16x32_bf16 v[28:31], v[150:153], v[200:203], v[28:31]
	v_mfma_f32_16x16x32_bf16 v[24:27], v[158:161], v[200:203], v[24:27]
	s_waitcnt lgkmcnt(0)
	v_mfma_f32_16x16x32_bf16 v[12:15], v[150:153], v[208:211], v[12:15]
	v_mfma_f32_16x16x32_bf16 v[8:11], v[158:161], v[208:211], v[8:11]
	s_setprio 0
	s_barrier
	s_add_i32 s6, s6, s27
	v_lshl_add_u64 v[142:143], v[234:235], 0, s[28:29]
	s_mov_b32 m0, s6
	s_nop 0
	global_load_lds_dwordx4 v[142:143], off
	v_lshl_add_u64 v[142:143], v[236:237], 0, s[28:29]
	s_add_i32 m0, s6, 0x2000
	s_nop 0
	global_load_lds_dwordx4 v[142:143], off
	s_waitcnt vmcnt(6)
	s_barrier
	s_setprio 1
	v_mfma_f32_16x16x32_bf16 v[52:55], v[212:215], v[162:165], v[52:55]
	v_mfma_f32_16x16x32_bf16 v[48:51], v[220:223], v[162:165], v[48:51]
	v_mfma_f32_16x16x32_bf16 v[36:39], v[212:215], v[172:175], v[36:39]
	v_mfma_f32_16x16x32_bf16 v[32:35], v[220:223], v[172:175], v[32:35]
	v_mfma_f32_16x16x32_bf16 v[20:23], v[212:215], v[196:199], v[20:23]
	v_mfma_f32_16x16x32_bf16 v[16:19], v[220:223], v[196:199], v[16:19]
	v_mfma_f32_16x16x32_bf16 v[4:7], v[212:215], v[204:207], v[4:7]
	v_mfma_f32_16x16x32_bf16 v[0:3], v[220:223], v[204:207], v[0:3]
	v_mfma_f32_16x16x32_bf16 v[52:55], v[216:219], v[168:171], v[52:55]
	v_mfma_f32_16x16x32_bf16 v[48:51], v[224:227], v[168:171], v[48:51]
	v_mfma_f32_16x16x32_bf16 v[36:39], v[216:219], v[176:179], v[36:39]
	v_mfma_f32_16x16x32_bf16 v[32:35], v[224:227], v[176:179], v[32:35]
	v_mfma_f32_16x16x32_bf16 v[20:23], v[216:219], v[200:203], v[20:23]
	v_mfma_f32_16x16x32_bf16 v[16:19], v[224:227], v[200:203], v[16:19]
	v_mfma_f32_16x16x32_bf16 v[4:7], v[216:219], v[208:211], v[4:7]
	v_mfma_f32_16x16x32_bf16 v[0:3], v[224:227], v[208:211], v[0:3]
	s_setprio 0
	s_add_u32 s30, s30, 0x100
	s_addc_u32 s31, s31, 0
	s_add_u32 s44, s44, 0x100
	s_addc_u32 s45, s45, 0
	s_cmp_ge_i32 s61, s83
	s_mov_b32 s6, s61
	s_barrier
	s_cbranch_scc0 .LBB0_635

; #define PG8_STAGE(bufoff, gbase, voff) do { _Pragma("unroll") for (int _i = 0; _i < 2; ++_i) \
;         __builtin_amdgcn_global_load_lds((const unsigned*)((const char*)(gbase) + (voff)[_i]), (LAS unsigned*)(lds + (bufoff) + ldsw + _i * 8192), 16, 0, 0); } while (0)
; #define PG8_LDA(dst, b, h) do { _Pragma("unroll") for (int m = 0; m < 4; ++m) _Pragma("unroll") for (int k = 0; k < 2; ++k) dst[m][k] = *(const LAS bf16x8*)(lds + PG8_SA(b, h) + aoff + m * 2048 + k * 1024); } while (0)
; #define PG8_LDB(dst, b, h) do { _Pragma("unroll") for (int n = 0; n < 2; ++n) _Pragma("unroll") for (int k = 0; k < 2; ++k) dst[n][k] = *(const LAS bf16x8*)(lds + PG8_SB(b, h) + boff + n * 2048 + k * 1024); } while (0)
; #define PG8_MMA(ai, bj, At, Bt) do { __builtin_amdgcn_s_setprio(1); _Pragma("unroll") for (int m = 0; m < 4; ++m) _Pragma("unroll") for (int n = 0; n < 2; ++n) _Pragma("unroll") for (int k = 0; k < 2; ++k) \
;         acc[ai][bj][m][n] = __builtin_amdgcn_mfma_f32_16x16x32_bf16(Bt[n][k], At[m][k], acc[ai][bj][m][n], 0, 0, 0); __builtin_amdgcn_s_setprio(0); } while (0)
; #define PG8_WAIT_L(n) asm volatile("s_waitcnt lgkmcnt(" #n ")" ::: "memory")
; template <class Epi, class Sched>
; DI void gemm_phase(LAS unsigned char* lds, const Gemm g, const Sched& S, const Epi& E) {
;     ...
;         const char* nA = has_next ? (const char*)g.A + (size_t)nxt.pm * tstepA : cA; const char* nB = has_next ? (const char*)g.Bt + (size_t)nxt.pn * tstepB : cB;
; #pragma nounroll
;         for (int t = 0; t < nt; t += 2) {
;             const bool last = (t == nt - 2);
;             const char* a1 = cA + (size_t)(t + 1) * kstep;
;             const char* a2 = last ? nA : cA + (size_t)(t + 2) * kstep; const char* b2 = last ? nB : cB + (size_t)(t + 2) * kstep;
;             const char* a3 = a2 + kstep; const char* b3 = b2 + kstep;
;             if (last && has_next) S.a_ready(nxt);
;             PG8_LDB(B0, 0, 0); PG8_SCHED; PG8_LDA(At, 0, 0); PG8_STAGE(PG8_SA(1, 1), a1 + hstepA, voffA);
;             PG8_WAIT_L(8); PG8_BAR; PG8_WAIT_L(0); PG8_MMA(0, 0, At, B0); PG8_BAR; PG8_SCHED;
;             PG8_LDB(B1, 0, 1); PG8_STAGE(PG8_SB(0, 0), b2, voffB);
;             PG8_BAR; PG8_WAIT_L(0); PG8_MMA(0, 1, At, B1); PG8_BAR;
;             PG8_LDA(At, 0, 1); PG8_STAGE(PG8_SA(0, 0), a2, voffA);
;             PG8_BAR; PG8_WAIT_L(0); PG8_MMA(1, 0, At, B0); PG8_BAR; PG8_SCHED;
.LBB0_694:
	s_add_i32 s31, s6, 2
	s_add_u32 s8, s44, 0x80
	s_addc_u32 s7, s45, 0
	s_add_i32 s41, 0, 0x10000
	v_add_u32_e32 v96, s41, v144
	ds_read_b128 v[138:141], v96
	ds_read_b128 v[146:149], v96 offset:1024
	ds_read_b128 v[150:153], v96 offset:2048
	ds_read_b128 v[154:157], v96 offset:3072
	s_cmp_eq_u32 s96, s6
	s_cselect_b32 s6, s68, s8
	s_cselect_b32 s7, s69, s7
	s_cselect_b32 s9, s75, s30
	s_cselect_b32 s8, s74, s24
	v_lshl_add_u64 v[180:181], s[44:45], 0, v[136:137]
	s_add_i32 m0, s86, 0xc000
	ds_read_b128 v[158:161], v145
	ds_read_b128 v[162:165], v145 offset:1024
	ds_read_b128 v[168:171], v145 offset:2048
	ds_read_b128 v[172:175], v145 offset:3072
	ds_read_b128 v[176:179], v145 offset:4096
	ds_read_b128 v[196:199], v145 offset:5120
	ds_read_b128 v[200:203], v145 offset:6144
	ds_read_b128 v[204:207], v145 offset:7168
	global_load_lds_dwordx4 v[180:181], off
	v_lshl_add_u64 v[180:181], s[44:45], 0, v[134:135]
	s_add_i32 m0, s86, 0xe000
	s_nop 0
	global_load_lds_dwordx4 v[180:181], off
	s_waitcnt lgkmcnt(8)
	s_barrier
	s_setprio 1
	s_waitcnt lgkmcnt(7)
	v_mfma_f32_16x16x32_bf16 v[98:101], v[138:141], v[158:161], v[98:101]
	v_mfma_f32_16x16x32_bf16 v[126:129], v[150:153], v[158:161], v[126:129]
	s_waitcnt lgkmcnt(5)
	v_mfma_f32_16x16x32_bf16 v[122:125], v[138:141], v[168:171], v[122:125]
	v_mfma_f32_16x16x32_bf16 v[118:121], v[150:153], v[168:171], v[118:121]
	s_waitcnt lgkmcnt(3)
	v_mfma_f32_16x16x32_bf16 v[114:117], v[138:141], v[176:179], v[114:117]
	v_mfma_f32_16x16x32_bf16 v[110:113], v[150:153], v[176:179], v[110:113]
	s_waitcnt lgkmcnt(1)
	v_mfma_f32_16x16x32_bf16 v[106:109], v[138:141], v[200:203], v[106:109]
	v_mfma_f32_16x16x32_bf16 v[102:105], v[150:153], v[200:203], v[102:105]
	v_mfma_f32_16x16x32_bf16 v[98:101], v[146:149], v[162:165], v[98:101]
	v_mfma_f32_16x16x32_bf16 v[126:129], v[154:157], v[162:165], v[126:129]
	v_mfma_f32_16x16x32_bf16 v[122:125], v[146:149], v[172:175], v[122:125]
	v_mfma_f32_16x16x32_bf16 v[118:121], v[154:157], v[172:175], v[118:121]
	v_mfma_f32_16x16x32_bf16 v[114:117], v[146:149], v[196:199], v[114:117]
	v_mfma_f32_16x16x32_bf16 v[110:113], v[154:157], v[196:199], v[110:113]
	s_waitcnt lgkmcnt(0)
	v_mfma_f32_16x16x32_bf16 v[106:109], v[146:149], v[204:207], v[106:109]
	v_mfma_f32_16x16x32_bf16 v[102:105], v[154:157], v[204:207], v[102:105]
	s_setprio 0
	s_barrier
	s_add_i32 s46, 0, 0x14000
	s_add_i32 s41, s41, s77
	v_add_u32_e32 v96, s46, v144
	v_lshl_add_u64 v[180:181], s[8:9], 0, v[130:131]
	s_mov_b32 m0, s41
	ds_read_b128 v[208:211], v96
	ds_read_b128 v[212:215], v96 offset:1024
	ds_read_b128 v[216:219], v96 offset:2048
	ds_read_b128 v[220:223], v96 offset:3072
	global_load_lds_dwordx4 v[180:181], off
	v_lshl_add_u64 v[224:225], s[8:9], 0, v[132:133]
	s_add_i32 m0, s41, 0x2000
	s_nop 0
	global_load_lds_dwordx4 v[224:225], off
	s_barrier
	s_setprio 1
	s_waitcnt lgkmcnt(3)
	v_mfma_f32_16x16x32_bf16 v[76:79], v[208:211], v[158:161], v[76:79]
	s_waitcnt lgkmcnt(1)
	v_mfma_f32_16x16x32_bf16 v[52:55], v[216:219], v[158:161], v[52:55]
	v_mfma_f32_16x16x32_bf16 v[48:51], v[208:211], v[168:171], v[48:51]
	v_mfma_f32_16x16x32_bf16 v[44:47], v[216:219], v[168:171], v[44:47]
	v_mfma_f32_16x16x32_bf16 v[40:43], v[208:211], v[176:179], v[40:43]
	v_mfma_f32_16x16x32_bf16 v[36:39], v[216:219], v[176:179], v[36:39]
	v_mfma_f32_16x16x32_bf16 v[32:35], v[208:211], v[200:203], v[32:35]
	v_mfma_f32_16x16x32_bf16 v[92:95], v[216:219], v[200:203], v[92:95]
	v_mfma_f32_16x16x32_bf16 v[76:79], v[212:215], v[162:165], v[76:79]
	s_waitcnt lgkmcnt(0)
	v_mfma_f32_16x16x32_bf16 v[52:55], v[220:223], v[162:165], v[52:55]
	v_mfma_f32_16x16x32_bf16 v[48:51], v[212:215], v[172:175], v[48:51]
	v_mfma_f32_16x16x32_bf16 v[44:47], v[220:223], v[172:175], v[44:47]
	v_mfma_f32_16x16x32_bf16 v[40:43], v[212:215], v[196:199], v[40:43]
	v_mfma_f32_16x16x32_bf16 v[36:39], v[220:223], v[196:199], v[36:39]
	v_mfma_f32_16x16x32_bf16 v[32:35], v[212:215], v[204:207], v[32:35]
	v_mfma_f32_16x16x32_bf16 v[92:95], v[220:223], v[204:207], v[92:95]
	s_setprio 0
	s_mov_b32 m0, s86
	v_lshl_add_u64 v[226:227], s[6:7], 0, v[130:131]
	s_barrier
	ds_read_b128 v[158:161], v145 offset:16384
	ds_read_b128 v[162:165], v145 offset:17408
	ds_read_b128 v[168:171], v145 offset:18432
	ds_read_b128 v[172:175], v145 offset:19456
	ds_read_b128 v[176:179], v145 offset:20480
	ds_read_b128 v[196:199], v145 offset:21504
	ds_read_b128 v[200:203], v145 offset:22528
	ds_read_b128 v[204:207], v145 offset:23552
	global_load_lds_dwordx4 v[226:227], off
	v_lshl_add_u64 v[228:229], s[6:7], 0, v[132:133]
	s_mov_b32 m0, s87
	s_nop 0
	global_load_lds_dwordx4 v[228:229], off
	s_barrier
	s_setprio 1
	s_waitcnt lgkmcnt(7)
	v_mfma_f32_16x16x32_bf16 v[28:31], v[138:141], v[158:161], v[28:31]
	v_mfma_f32_16x16x32_bf16 v[88:91], v[150:153], v[158:161], v[88:91]
	s_waitcnt lgkmcnt(5)
	v_mfma_f32_16x16x32_bf16 v[84:87], v[138:141], v[168:171], v[84:87]
	v_mfma_f32_16x16x32_bf16 v[80:83], v[150:153], v[168:171], v[80:83]
	s_waitcnt lgkmcnt(3)
	v_mfma_f32_16x16x32_bf16 v[72:75], v[138:141], v[176:179], v[72:75]
	v_mfma_f32_16x16x32_bf16 v[68:71], v[150:153], v[176:179], v[68:71]
	s_waitcnt lgkmcnt(1)
	v_mfma_f32_16x16x32_bf16 v[64:67], v[138:141], v[200:203], v[64:67]
	v_mfma_f32_16x16x32_bf16 v[60:63], v[150:153], v[200:203], v[60:63]
	v_mfma_f32_16x16x32_bf16 v[28:31], v[146:149], v[162:165], v[28:31]
	v_mfma_f32_16x16x32_bf16 v[88:91], v[154:157], v[162:165], v[88:91]
	v_mfma_f32_16x16x32_bf16 v[84:87], v[146:149], v[172:175], v[84:87]
	v_mfma_f32_16x16x32_bf16 v[80:83], v[154:157], v[172:175], v[80:83]
	v_mfma_f32_16x16x32_bf16 v[72:75], v[146:149], v[196:199], v[72:75]
	v_mfma_f32_16x16x32_bf16 v[68:71], v[154:157], v[196:199], v[68:71]
	s_waitcnt lgkmcnt(0)
	v_mfma_f32_16x16x32_bf16 v[64:67], v[146:149], v[204:207], v[64:67]
	v_mfma_f32_16x16x32_bf16 v[60:63], v[154:157], v[204:207], v[60:63]
	s_setprio 0
	s_barrier
; #define PG8_STAGE(bufoff, gbase, voff) do { _Pragma("unroll") for (int _i = 0; _i < 2; ++_i) \
;         __builtin_amdgcn_global_load_lds((const unsigned*)((const char*)(gbase) + (voff)[_i]), (LAS unsigned*)(lds + (bufoff) + ldsw + _i * 8192), 16, 0, 0); } while (0)
; #define PG8_LDA(dst, b, h) do { _Pragma("unroll") for (int m = 0; m < 4; ++m) _Pragma("unroll") for (int k = 0; k < 2; ++k) dst[m][k] = *(const LAS bf16x8*)(lds + PG8_SA(b, h) + aoff + m * 2048 + k * 1024); } while (0)
; #define PG8_LDB(dst, b, h) do { _Pragma("unroll") for (int n = 0; n < 2; ++n) _Pragma("unroll") for (int k = 0; k < 2; ++k) dst[n][k] = *(const LAS bf16x8*)(lds + PG8_SB(b, h) + boff + n * 2048 + k * 1024); } while (0)
; #define PG8_MMA(ai, bj, At, Bt) do { __builtin_amdgcn_s_setprio(1); _Pragma("unroll") for (int m = 0; m < 4; ++m) _Pragma("unroll") for (int n = 0; n < 2; ++n) _Pragma("unroll") for (int k = 0; k < 2; ++k) \
;         acc[ai][bj][m][n] = __builtin_amdgcn_mfma_f32_16x16x32_bf16(Bt[n][k], At[m][k], acc[ai][bj][m][n], 0, 0, 0); __builtin_amdgcn_s_setprio(0); } while (0)
; #define PG8_WAIT_V(n) asm volatile("s_waitcnt vmcnt(" #n ")" ::: "memory")
; #define PG8_WAIT_L(n) asm volatile("s_waitcnt lgkmcnt(" #n ")" ::: "memory")
; #define PG8_BAR __builtin_amdgcn_s_barrier()
; #define PG8_SCHED __builtin_amdgcn_sched_barrier(0)
; template <class Epi, class Sched>
; DI void gemm_phase(LAS unsigned char* lds, const Gemm g, const Sched& S, const Epi& E) {
;     ...
;             PG8_STAGE(PG8_SB(0, 1), b2 + hstepB, voffB);
;             PG8_WAIT_V(6); PG8_BAR; PG8_MMA(1, 1, At, B1); PG8_BAR;
;             PG8_LDB(B0, 1, 0); PG8_SCHED; PG8_LDA(At, 1, 0); PG8_STAGE(PG8_SA(0, 1), a2 + hstepA, voffA);
;             PG8_WAIT_L(8); PG8_BAR; PG8_WAIT_L(0); PG8_MMA(0, 0, At, B0); PG8_BAR; PG8_SCHED;
;             PG8_LDB(B1, 1, 1); PG8_STAGE(PG8_SB(1, 0), b3, voffB);
	s_add_u32 s8, s8, s36
	s_addc_u32 s9, s9, s37
	s_add_i32 s41, s46, s77
	v_lshl_add_u64 v[230:231], s[8:9], 0, v[130:131]
	s_mov_b32 m0, s41
	v_lshl_add_u64 v[232:233], s[8:9], 0, v[132:133]
	global_load_lds_dwordx4 v[230:231], off
	s_add_i32 m0, s41, 0x2000
	s_nop 0
	global_load_lds_dwordx4 v[232:233], off
	s_waitcnt vmcnt(6)
	s_barrier
	s_setprio 1
	v_mfma_f32_16x16x32_bf16 v[24:27], v[208:211], v[158:161], v[24:27]
	v_mfma_f32_16x16x32_bf16 v[20:23], v[216:219], v[158:161], v[20:23]
	v_mfma_f32_16x16x32_bf16 v[16:19], v[208:211], v[168:171], v[16:19]
	v_mfma_f32_16x16x32_bf16 v[12:15], v[216:219], v[168:171], v[12:15]
	v_mfma_f32_16x16x32_bf16 v[8:11], v[208:211], v[176:179], v[8:11]
	v_mfma_f32_16x16x32_bf16 v[4:7], v[216:219], v[176:179], v[4:7]
	v_mfma_f32_16x16x32_bf16 v[0:3], v[208:211], v[200:203], v[0:3]
	v_mfma_f32_16x16x32_bf16 v[56:59], v[216:219], v[200:203], v[56:59]
	v_mfma_f32_16x16x32_bf16 v[24:27], v[212:215], v[162:165], v[24:27]
	v_mfma_f32_16x16x32_bf16 v[20:23], v[220:223], v[162:165], v[20:23]
	v_mfma_f32_16x16x32_bf16 v[16:19], v[212:215], v[172:175], v[16:19]
	v_mfma_f32_16x16x32_bf16 v[12:15], v[220:223], v[172:175], v[12:15]
	v_mfma_f32_16x16x32_bf16 v[8:11], v[212:215], v[196:199], v[8:11]
	v_mfma_f32_16x16x32_bf16 v[4:7], v[220:223], v[196:199], v[4:7]
	v_mfma_f32_16x16x32_bf16 v[0:3], v[212:215], v[204:207], v[0:3]
	v_mfma_f32_16x16x32_bf16 v[56:59], v[220:223], v[204:207], v[56:59]
	s_setprio 0
	s_add_i32 s8, 0, 0x18000
	v_add_u32_e32 v96, s8, v144
	s_barrier
	ds_read_b128 v[138:141], v96
	ds_read_b128 v[146:149], v96 offset:1024
	ds_read_b128 v[150:153], v96 offset:2048
	ds_read_b128 v[154:157], v96 offset:3072
	s_add_u32 s6, s6, s36
	s_addc_u32 s7, s7, s37
	s_mov_b32 m0, s88
	v_lshl_add_u64 v[208:209], s[6:7], 0, v[130:131]
	ds_read_b128 v[158:161], v145 offset:32768
	ds_read_b128 v[162:165], v145 offset:33792
	ds_read_b128 v[168:171], v145 offset:34816
	ds_read_b128 v[172:175], v145 offset:35840
	ds_read_b128 v[176:179], v145 offset:36864
	ds_read_b128 v[196:199], v145 offset:37888
	ds_read_b128 v[200:203], v145 offset:38912
	ds_read_b128 v[204:207], v145 offset:39936
	global_load_lds_dwordx4 v[208:209], off
	v_lshl_add_u64 v[208:209], s[6:7], 0, v[132:133]
	s_mov_b32 m0, s89
	s_nop 0
	global_load_lds_dwordx4 v[208:209], off
	s_waitcnt lgkmcnt(8)
	s_barrier
	s_setprio 1
	s_waitcnt lgkmcnt(7)
	v_mfma_f32_16x16x32_bf16 v[98:101], v[138:141], v[158:161], v[98:101]
	v_mfma_f32_16x16x32_bf16 v[126:129], v[150:153], v[158:161], v[126:129]
	s_waitcnt lgkmcnt(5)
	v_mfma_f32_16x16x32_bf16 v[122:125], v[138:141], v[168:171], v[122:125]
	v_mfma_f32_16x16x32_bf16 v[118:121], v[150:153], v[168:171], v[118:121]
	s_waitcnt lgkmcnt(3)
	v_mfma_f32_16x16x32_bf16 v[114:117], v[138:141], v[176:179], v[114:117]
	v_mfma_f32_16x16x32_bf16 v[110:113], v[150:153], v[176:179], v[110:113]
	s_waitcnt lgkmcnt(1)
	v_mfma_f32_16x16x32_bf16 v[106:109], v[138:141], v[200:203], v[106:109]
	v_mfma_f32_16x16x32_bf16 v[102:105], v[150:153], v[200:203], v[102:105]
	v_mfma_f32_16x16x32_bf16 v[98:101], v[146:149], v[162:165], v[98:101]
	v_mfma_f32_16x16x32_bf16 v[126:129], v[154:157], v[162:165], v[126:129]
	v_mfma_f32_16x16x32_bf16 v[122:125], v[146:149], v[172:175], v[122:125]
	v_mfma_f32_16x16x32_bf16 v[118:121], v[154:157], v[172:175], v[118:121]
	v_mfma_f32_16x16x32_bf16 v[114:117], v[146:149], v[196:199], v[114:117]
	v_mfma_f32_16x16x32_bf16 v[110:113], v[154:157], v[196:199], v[110:113]
	s_waitcnt lgkmcnt(0)
	v_mfma_f32_16x16x32_bf16 v[106:109], v[146:149], v[204:207], v[106:109]
	v_mfma_f32_16x16x32_bf16 v[102:105], v[154:157], v[204:207], v[102:105]
	s_setprio 0
	s_barrier
	s_add_i32 s6, 0, 0x1c000
	s_add_i32 s7, s8, s77
	v_add_u32_e32 v96, s6, v144
	v_lshl_add_u64 v[180:181], v[180:181], 0, s[28:29]
	s_mov_b32 m0, s7
	ds_read_b128 v[208:211], v96
	ds_read_b128 v[212:215], v96 offset:1024
	ds_read_b128 v[216:219], v96 offset:2048
	ds_read_b128 v[220:223], v96 offset:3072
	global_load_lds_dwordx4 v[180:181], off
	v_lshl_add_u64 v[180:181], v[224:225], 0, s[28:29]
	s_add_i32 m0, s7, 0x2000
	s_nop 0
	global_load_lds_dwordx4 v[180:181], off
	s_barrier
	s_setprio 1
	s_waitcnt lgkmcnt(3)
	v_mfma_f32_16x16x32_bf16 v[76:79], v[208:211], v[158:161], v[76:79]
	s_waitcnt lgkmcnt(1)
	v_mfma_f32_16x16x32_bf16 v[52:55], v[216:219], v[158:161], v[52:55]
	v_mfma_f32_16x16x32_bf16 v[48:51], v[208:211], v[168:171], v[48:51]
	v_mfma_f32_16x16x32_bf16 v[44:47], v[216:219], v[168:171], v[44:47]
	v_mfma_f32_16x16x32_bf16 v[40:43], v[208:211], v[176:179], v[40:43]
	v_mfma_f32_16x16x32_bf16 v[36:39], v[216:219], v[176:179], v[36:39]
	v_mfma_f32_16x16x32_bf16 v[32:35], v[208:211], v[200:203], v[32:35]
	v_mfma_f32_16x16x32_bf16 v[92:95], v[216:219], v[200:203], v[92:95]
	v_mfma_f32_16x16x32_bf16 v[76:79], v[212:215], v[162:165], v[76:79]
	s_waitcnt lgkmcnt(0)
	v_mfma_f32_16x16x32_bf16 v[52:55], v[220:223], v[162:165], v[52:55]
	v_mfma_f32_16x16x32_bf16 v[48:51], v[212:215], v[172:175], v[48:51]
	v_mfma_f32_16x16x32_bf16 v[44:47], v[220:223], v[172:175], v[44:47]
	v_mfma_f32_16x16x32_bf16 v[40:43], v[212:215], v[196:199], v[40:43]
	v_mfma_f32_16x16x32_bf16 v[36:39], v[220:223], v[196:199], v[36:39]
	v_mfma_f32_16x16x32_bf16 v[32:35], v[212:215], v[204:207], v[32:35]
	v_mfma_f32_16x16x32_bf16 v[92:95], v[220:223], v[204:207], v[92:95]
	s_setprio 0
	s_mov_b32 m0, s94
	v_lshl_add_u64 v[180:181], v[226:227], 0, s[28:29]
	s_barrier
; #define PG8_STAGE(bufoff, gbase, voff) do { _Pragma("unroll") for (int _i = 0; _i < 2; ++_i) \
;         __builtin_amdgcn_global_load_lds((const unsigned*)((const char*)(gbase) + (voff)[_i]), (LAS unsigned*)(lds + (bufoff) + ldsw + _i * 8192), 16, 0, 0); } while (0)
; #define PG8_LDA(dst, b, h) do { _Pragma("unroll") for (int m = 0; m < 4; ++m) _Pragma("unroll") for (int k = 0; k < 2; ++k) dst[m][k] = *(const LAS bf16x8*)(lds + PG8_SA(b, h) + aoff + m * 2048 + k * 1024); } while (0)
; #define PG8_MMA(ai, bj, At, Bt) do { __builtin_amdgcn_s_setprio(1); _Pragma("unroll") for (int m = 0; m < 4; ++m) _Pragma("unroll") for (int n = 0; n < 2; ++n) _Pragma("unroll") for (int k = 0; k < 2; ++k) \
;         acc[ai][bj][m][n] = __builtin_amdgcn_mfma_f32_16x16x32_bf16(Bt[n][k], At[m][k], acc[ai][bj][m][n], 0, 0, 0); __builtin_amdgcn_s_setprio(0); } while (0)
; #define PG8_WAIT_V(n) asm volatile("s_waitcnt vmcnt(" #n ")" ::: "memory")
; #define PG8_WAIT_L(n) asm volatile("s_waitcnt lgkmcnt(" #n ")" ::: "memory")
; #define PG8_BAR __builtin_amdgcn_s_barrier()
; #define PG8_SCHED __builtin_amdgcn_sched_barrier(0)
; template <class Epi, class Sched>
; DI void gemm_phase(LAS unsigned char* lds, const Gemm g, const Sched& S, const Epi& E) {
;     ...
;             PG8_LDA(At, 1, 1); PG8_STAGE(PG8_SA(1, 0), a3, voffA);
;             PG8_BAR; PG8_WAIT_L(0); PG8_MMA(1, 0, At, B0); PG8_BAR; PG8_SCHED;
;             PG8_STAGE(PG8_SB(1, 1), b3 + hstepB, voffB);
;             PG8_WAIT_V(6); PG8_BAR; PG8_MMA(1, 1, At, B1); PG8_BAR;
	ds_read_b128 v[158:161], v145 offset:49152
	ds_read_b128 v[162:165], v145 offset:50176
	ds_read_b128 v[168:171], v145 offset:51200
	ds_read_b128 v[172:175], v145 offset:52224
	ds_read_b128 v[176:179], v145 offset:53248
	ds_read_b128 v[196:199], v145 offset:54272
	ds_read_b128 v[200:203], v145 offset:55296
	ds_read_b128 v[204:207], v145 offset:56320
	global_load_lds_dwordx4 v[180:181], off
	v_lshl_add_u64 v[180:181], v[228:229], 0, s[28:29]
	s_mov_b32 m0, s95
	s_nop 0
	global_load_lds_dwordx4 v[180:181], off
	s_barrier
	s_setprio 1
	s_waitcnt lgkmcnt(7)
	v_mfma_f32_16x16x32_bf16 v[28:31], v[138:141], v[158:161], v[28:31]
	v_mfma_f32_16x16x32_bf16 v[88:91], v[150:153], v[158:161], v[88:91]
	s_waitcnt lgkmcnt(5)
	v_mfma_f32_16x16x32_bf16 v[84:87], v[138:141], v[168:171], v[84:87]
	v_mfma_f32_16x16x32_bf16 v[80:83], v[150:153], v[168:171], v[80:83]
	s_waitcnt lgkmcnt(3)
	v_mfma_f32_16x16x32_bf16 v[72:75], v[138:141], v[176:179], v[72:75]
	v_mfma_f32_16x16x32_bf16 v[68:71], v[150:153], v[176:179], v[68:71]
	s_waitcnt lgkmcnt(1)
	v_mfma_f32_16x16x32_bf16 v[64:67], v[138:141], v[200:203], v[64:67]
	v_mfma_f32_16x16x32_bf16 v[60:63], v[150:153], v[200:203], v[60:63]
	v_mfma_f32_16x16x32_bf16 v[28:31], v[146:149], v[162:165], v[28:31]
	v_mfma_f32_16x16x32_bf16 v[88:91], v[154:157], v[162:165], v[88:91]
	v_mfma_f32_16x16x32_bf16 v[84:87], v[146:149], v[172:175], v[84:87]
	v_mfma_f32_16x16x32_bf16 v[80:83], v[154:157], v[172:175], v[80:83]
	v_mfma_f32_16x16x32_bf16 v[72:75], v[146:149], v[196:199], v[72:75]
	v_mfma_f32_16x16x32_bf16 v[68:71], v[154:157], v[196:199], v[68:71]
	s_waitcnt lgkmcnt(0)
	v_mfma_f32_16x16x32_bf16 v[64:67], v[146:149], v[204:207], v[64:67]
	v_mfma_f32_16x16x32_bf16 v[60:63], v[154:157], v[204:207], v[60:63]
	s_setprio 0
	s_barrier
	s_add_i32 s6, s6, s77
	v_lshl_add_u64 v[138:139], v[230:231], 0, s[28:29]
	s_mov_b32 m0, s6
	s_nop 0
	global_load_lds_dwordx4 v[138:139], off
	v_lshl_add_u64 v[138:139], v[232:233], 0, s[28:29]
	s_add_i32 m0, s6, 0x2000
	s_nop 0
	global_load_lds_dwordx4 v[138:139], off
	s_waitcnt vmcnt(6)
	s_barrier
	s_setprio 1
	v_mfma_f32_16x16x32_bf16 v[24:27], v[208:211], v[158:161], v[24:27]
	v_mfma_f32_16x16x32_bf16 v[20:23], v[216:219], v[158:161], v[20:23]
	v_mfma_f32_16x16x32_bf16 v[16:19], v[208:211], v[168:171], v[16:19]
	v_mfma_f32_16x16x32_bf16 v[12:15], v[216:219], v[168:171], v[12:15]
	v_mfma_f32_16x16x32_bf16 v[8:11], v[208:211], v[176:179], v[8:11]
	v_mfma_f32_16x16x32_bf16 v[4:7], v[216:219], v[176:179], v[4:7]
	v_mfma_f32_16x16x32_bf16 v[0:3], v[208:211], v[200:203], v[0:3]
	v_mfma_f32_16x16x32_bf16 v[56:59], v[216:219], v[200:203], v[56:59]
	v_mfma_f32_16x16x32_bf16 v[24:27], v[212:215], v[162:165], v[24:27]
	v_mfma_f32_16x16x32_bf16 v[20:23], v[220:223], v[162:165], v[20:23]
	v_mfma_f32_16x16x32_bf16 v[16:19], v[212:215], v[172:175], v[16:19]
	v_mfma_f32_16x16x32_bf16 v[12:15], v[220:223], v[172:175], v[12:15]
	v_mfma_f32_16x16x32_bf16 v[8:11], v[212:215], v[196:199], v[8:11]
	v_mfma_f32_16x16x32_bf16 v[4:7], v[220:223], v[196:199], v[4:7]
	v_mfma_f32_16x16x32_bf16 v[0:3], v[212:215], v[204:207], v[0:3]
	v_mfma_f32_16x16x32_bf16 v[56:59], v[220:223], v[204:207], v[56:59]
	s_setprio 0
	s_add_u32 s24, s24, 0x100
	s_addc_u32 s30, s30, 0
	s_add_u32 s44, s44, 0x100
	s_addc_u32 s45, s45, 0
	s_cmp_ge_i32 s31, s90
	s_mov_b32 s6, s31
	s_barrier
	s_cbranch_scc0 .LBB0_694
;     DI void operator()(const f32x4 (&acc)[2][2][4][2], const Unit& u, int wr, int wc, int fr, int fq) const {
;     ...
;                     const int c0 = u.pn * BM + bj * HALF + wc * 32;
;                     const int hh = c0 / 192, within0 = c0 - hh * 192;
;                     f32x4 v0 = acc[ai][bj][m][0] * qscale, v1 = acc[ai][bj][m][1] * qscale;
	s_mov_b32 s6, 0x3dd53b94
	v_pk_mul_f32 v[100:101], v[100:101], s[6:7] op_sel_hi:[1,0]
	v_pk_mul_f32 v[98:99], v[98:99], s[6:7] op_sel_hi:[1,0]
	v_pk_mul_f32 v[140:141], v[128:129], s[6:7] op_sel_hi:[1,0]
	v_pk_mul_f32 v[138:139], v[126:127], s[6:7] op_sel_hi:[1,0]
	v_pk_mul_f32 v[78:79], v[78:79], s[6:7] op_sel_hi:[1,0]
	v_pk_mul_f32 v[76:77], v[76:77], s[6:7] op_sel_hi:[1,0]
	v_pk_mul_f32 v[128:129], v[54:55], s[6:7] op_sel_hi:[1,0]
	v_pk_mul_f32 v[126:127], v[52:53], s[6:7] op_sel_hi:[1,0]
	v_pk_mul_f32 v[54:55], v[124:125], s[6:7] op_sel_hi:[1,0]
	v_pk_mul_f32 v[52:53], v[122:123], s[6:7] op_sel_hi:[1,0]
	v_pk_mul_f32 v[124:125], v[120:121], s[6:7] op_sel_hi:[1,0]
	v_pk_mul_f32 v[122:123], v[118:119], s[6:7] op_sel_hi:[1,0]
	v_pk_mul_f32 v[50:51], v[50:51], s[6:7] op_sel_hi:[1,0]
	v_pk_mul_f32 v[48:49], v[48:49], s[6:7] op_sel_hi:[1,0]
	v_pk_mul_f32 v[120:121], v[46:47], s[6:7] op_sel_hi:[1,0]
	v_pk_mul_f32 v[118:119], v[44:45], s[6:7] op_sel_hi:[1,0]
	v_pk_mul_f32 v[46:47], v[116:117], s[6:7] op_sel_hi:[1,0]
	v_pk_mul_f32 v[44:45], v[114:115], s[6:7] op_sel_hi:[1,0]
	v_pk_mul_f32 v[116:117], v[112:113], s[6:7] op_sel_hi:[1,0]
	v_pk_mul_f32 v[114:115], v[110:111], s[6:7] op_sel_hi:[1,0]
	v_pk_mul_f32 v[42:43], v[42:43], s[6:7] op_sel_hi:[1,0]
	v_pk_mul_f32 v[40:41], v[40:41], s[6:7] op_sel_hi:[1,0]
	v_pk_mul_f32 v[112:113], v[38:39], s[6:7] op_sel_hi:[1,0]
	v_pk_mul_f32 v[110:111], v[36:37], s[6:7] op_sel_hi:[1,0]
	v_pk_mul_f32 v[38:39], v[108:109], s[6:7] op_sel_hi:[1,0]
	v_pk_mul_f32 v[36:37], v[106:107], s[6:7] op_sel_hi:[1,0]
	v_pk_mul_f32 v[108:109], v[104:105], s[6:7] op_sel_hi:[1,0]
	v_pk_mul_f32 v[106:107], v[102:103], s[6:7] op_sel_hi:[1,0]
	v_pk_mul_f32 v[34:35], v[34:35], s[6:7] op_sel_hi:[1,0]
	v_pk_mul_f32 v[32:33], v[32:33], s[6:7] op_sel_hi:[1,0]
	v_pk_mul_f32 v[104:105], v[94:95], s[6:7] op_sel_hi:[1,0]
	v_pk_mul_f32 v[102:103], v[92:93], s[6:7] op_sel_hi:[1,0]
	v_pk_mul_f32 v[30:31], v[30:31], s[6:7] op_sel_hi:[1,0]
	v_pk_mul_f32 v[28:29], v[28:29], s[6:7] op_sel_hi:[1,0]
	v_pk_mul_f32 v[94:95], v[90:91], s[6:7] op_sel_hi:[1,0]
	v_pk_mul_f32 v[92:93], v[88:89], s[6:7] op_sel_hi:[1,0]
	v_pk_mul_f32 v[26:27], v[26:27], s[6:7] op_sel_hi:[1,0]
	v_pk_mul_f32 v[24:25], v[24:25], s[6:7] op_sel_hi:[1,0]
	v_pk_mul_f32 v[90:91], v[22:23], s[6:7] op_sel_hi:[1,0]
	v_pk_mul_f32 v[88:89], v[20:21], s[6:7] op_sel_hi:[1,0]
	v_pk_mul_f32 v[22:23], v[86:87], s[6:7] op_sel_hi:[1,0]
	v_pk_mul_f32 v[20:21], v[84:85], s[6:7] op_sel_hi:[1,0]
	v_pk_mul_f32 v[86:87], v[82:83], s[6:7] op_sel_hi:[1,0]
	v_pk_mul_f32 v[84:85], v[80:81], s[6:7] op_sel_hi:[1,0]
	v_pk_mul_f32 v[18:19], v[18:19], s[6:7] op_sel_hi:[1,0]
	v_pk_mul_f32 v[16:17], v[16:17], s[6:7] op_sel_hi:[1,0]
	v_pk_mul_f32 v[82:83], v[14:15], s[6:7] op_sel_hi:[1,0]
	v_pk_mul_f32 v[80:81], v[12:13], s[6:7] op_sel_hi:[1,0]
	v_pk_mul_f32 v[14:15], v[74:75], s[6:7] op_sel_hi:[1,0]
	v_pk_mul_f32 v[12:13], v[72:73], s[6:7] op_sel_hi:[1,0]
	v_pk_mul_f32 v[74:75], v[70:71], s[6:7] op_sel_hi:[1,0]
	v_pk_mul_f32 v[72:73], v[68:69], s[6:7] op_sel_hi:[1,0]
	v_pk_mul_f32 v[10:11], v[10:11], s[6:7] op_sel_hi:[1,0]
	v_pk_mul_f32 v[8:9], v[8:9], s[6:7] op_sel_hi:[1,0]
	v_pk_mul_f32 v[70:71], v[6:7], s[6:7] op_sel_hi:[1,0]
	v_pk_mul_f32 v[68:69], v[4:5], s[6:7] op_sel_hi:[1,0]
	v_pk_mul_f32 v[6:7], v[66:67], s[6:7] op_sel_hi:[1,0]
	v_pk_mul_f32 v[4:5], v[64:65], s[6:7] op_sel_hi:[1,0]
	v_pk_mul_f32 v[62:63], v[62:63], s[6:7] op_sel_hi:[1,0]
	v_pk_mul_f32 v[60:61], v[60:61], s[6:7] op_sel_hi:[1,0]
	v_pk_mul_f32 v[2:3], v[2:3], s[6:7] op_sel_hi:[1,0]
	v_pk_mul_f32 v[0:1], v[0:1], s[6:7] op_sel_hi:[1,0]
	v_pk_mul_f32 v[58:59], v[58:59], s[6:7] op_sel_hi:[1,0]
	v_pk_mul_f32 v[56:57], v[56:57], s[6:7] op_sel_hi:[1,0]

; #define PG8_STAGE(bufoff, gbase, voff) do { _Pragma("unroll") for (int _i = 0; _i < 2; ++_i) \
;         __builtin_amdgcn_global_load_lds((const unsigned*)((const char*)(gbase) + (voff)[_i]), (LAS unsigned*)(lds + (bufoff) + ldsw + _i * 8192), 16, 0, 0); } while (0)
; #define PG8_LDA(dst, b, h) do { _Pragma("unroll") for (int m = 0; m < 4; ++m) _Pragma("unroll") for (int k = 0; k < 2; ++k) dst[m][k] = *(const LAS bf16x8*)(lds + PG8_SA(b, h) + aoff + m * 2048 + k * 1024); } while (0)
; #define PG8_LDB(dst, b, h) do { _Pragma("unroll") for (int n = 0; n < 2; ++n) _Pragma("unroll") for (int k = 0; k < 2; ++k) dst[n][k] = *(const LAS bf16x8*)(lds + PG8_SB(b, h) + boff + n * 2048 + k * 1024); } while (0)
; #define PG8_MMA(ai, bj, At, Bt) do { __builtin_amdgcn_s_setprio(1); _Pragma("unroll") for (int m = 0; m < 4; ++m) _Pragma("unroll") for (int n = 0; n < 2; ++n) _Pragma("unroll") for (int k = 0; k < 2; ++k) \
;         acc[ai][bj][m][n] = __builtin_amdgcn_mfma_f32_16x16x32_bf16(Bt[n][k], At[m][k], acc[ai][bj][m][n], 0, 0, 0); __builtin_amdgcn_s_setprio(0); } while (0)
; #define PG8_WAIT_L(n) asm volatile("s_waitcnt lgkmcnt(" #n ")" ::: "memory")
; template <class Epi, class Sched>
; DI void gemm_phase(LAS unsigned char* lds, const Gemm g, const Sched& S, const Epi& E) {
;     ...
;         const char* nA = has_next ? (const char*)g.A + (size_t)nxt.pm * tstepA : cA; const char* nB = has_next ? (const char*)g.Bt + (size_t)nxt.pn * tstepB : cB;
; #pragma nounroll
;         for (int t = 0; t < nt; t += 2) {
;             const bool last = (t == nt - 2);
;             const char* a1 = cA + (size_t)(t + 1) * kstep;
;             const char* a2 = last ? nA : cA + (size_t)(t + 2) * kstep; const char* b2 = last ? nB : cB + (size_t)(t + 2) * kstep;
;             const char* a3 = a2 + kstep; const char* b3 = b2 + kstep;
;             if (last && has_next) S.a_ready(nxt);
;             PG8_LDB(B0, 0, 0); PG8_SCHED; PG8_LDA(At, 0, 0); PG8_STAGE(PG8_SA(1, 1), a1 + hstepA, voffA);
;             PG8_WAIT_L(8); PG8_BAR; PG8_WAIT_L(0); PG8_MMA(0, 0, At, B0); PG8_BAR; PG8_SCHED;
;             PG8_LDB(B1, 0, 1); PG8_STAGE(PG8_SB(0, 0), b2, voffB);
;             PG8_BAR; PG8_WAIT_L(0); PG8_MMA(0, 1, At, B1); PG8_BAR;
;             PG8_LDA(At, 0, 1); PG8_STAGE(PG8_SA(0, 0), a2, voffA);
;             PG8_BAR; PG8_WAIT_L(0); PG8_MMA(1, 0, At, B0); PG8_BAR; PG8_SCHED;
.LBB0_784:
	s_add_i32 s56, s6, 2
	s_add_u32 s8, s54, 0x80
	s_addc_u32 s7, s55, 0
	s_add_i32 s57, 0, 0x10000
	v_add_u32_e32 v156, s57, v142
	ds_read_b128 v[144:147], v156
	ds_read_b128 v[148:151], v156 offset:1024
	ds_read_b128 v[152:155], v156 offset:2048
	ds_read_b128 v[156:159], v156 offset:3072
	s_cmp_eq_u32 s82, s6
	s_cselect_b32 s6, s44, s8
	s_cselect_b32 s7, s45, s7
	s_cselect_b32 s9, s47, s88
	s_cselect_b32 s8, s46, s87
	v_lshl_add_u64 v[164:165], s[54:55], 0, v[138:139]
	s_add_i32 m0, s24, 0xc000
	ds_read_b128 v[160:163], v143
	ds_read_b128 v[168:171], v143 offset:1024
	ds_read_b128 v[172:175], v143 offset:2048
	ds_read_b128 v[176:179], v143 offset:3072
	ds_read_b128 v[196:199], v143 offset:4096
	ds_read_b128 v[200:203], v143 offset:5120
	ds_read_b128 v[204:207], v143 offset:6144
	ds_read_b128 v[208:211], v143 offset:7168
	global_load_lds_dwordx4 v[164:165], off
	v_lshl_add_u64 v[164:165], s[54:55], 0, v[136:137]
	s_add_i32 m0, s24, 0xe000
	s_nop 0
	global_load_lds_dwordx4 v[164:165], off
	s_waitcnt lgkmcnt(8)
	s_barrier
	s_setprio 1
	s_waitcnt lgkmcnt(7)
	v_mfma_f32_16x16x32_bf16 v[122:125], v[144:147], v[160:163], v[122:125]
	v_mfma_f32_16x16x32_bf16 v[126:129], v[152:155], v[160:163], v[126:129]
	s_waitcnt lgkmcnt(5)
	v_mfma_f32_16x16x32_bf16 v[110:113], v[144:147], v[172:175], v[110:113]
	v_mfma_f32_16x16x32_bf16 v[106:109], v[152:155], v[172:175], v[106:109]
	s_waitcnt lgkmcnt(3)
	v_mfma_f32_16x16x32_bf16 v[92:95], v[144:147], v[196:199], v[92:95]
	v_mfma_f32_16x16x32_bf16 v[88:91], v[152:155], v[196:199], v[88:91]
	s_waitcnt lgkmcnt(1)
	v_mfma_f32_16x16x32_bf16 v[76:79], v[144:147], v[204:207], v[76:79]
	v_mfma_f32_16x16x32_bf16 v[72:75], v[152:155], v[204:207], v[72:75]
	v_mfma_f32_16x16x32_bf16 v[122:125], v[148:151], v[168:171], v[122:125]
	v_mfma_f32_16x16x32_bf16 v[126:129], v[156:159], v[168:171], v[126:129]
	v_mfma_f32_16x16x32_bf16 v[110:113], v[148:151], v[176:179], v[110:113]
	v_mfma_f32_16x16x32_bf16 v[106:109], v[156:159], v[176:179], v[106:109]
	v_mfma_f32_16x16x32_bf16 v[92:95], v[148:151], v[200:203], v[92:95]
	v_mfma_f32_16x16x32_bf16 v[88:91], v[156:159], v[200:203], v[88:91]
	s_waitcnt lgkmcnt(0)
	v_mfma_f32_16x16x32_bf16 v[76:79], v[148:151], v[208:211], v[76:79]
	v_mfma_f32_16x16x32_bf16 v[72:75], v[156:159], v[208:211], v[72:75]
	s_setprio 0
	s_barrier
	s_add_i32 s89, 0, 0x14000
	v_add_u32_e32 v164, s89, v142
	s_add_i32 s57, s57, s70
	ds_read_b128 v[212:215], v164
	ds_read_b128 v[216:219], v164 offset:1024
	ds_read_b128 v[220:223], v164 offset:2048
	ds_read_b128 v[224:227], v164 offset:3072
	v_lshl_add_u64 v[164:165], s[8:9], 0, v[96:97]
	s_mov_b32 m0, s57
	v_lshl_add_u64 v[180:181], s[8:9], 0, v[134:135]
	global_load_lds_dwordx4 v[164:165], off
	s_add_i32 m0, s57, 0x2000
	s_nop 0
	global_load_lds_dwordx4 v[180:181], off
	s_barrier
	s_setprio 1
	s_waitcnt lgkmcnt(3)
	v_mfma_f32_16x16x32_bf16 v[118:121], v[212:215], v[160:163], v[118:121]
	s_waitcnt lgkmcnt(1)
	v_mfma_f32_16x16x32_bf16 v[114:117], v[220:223], v[160:163], v[114:117]
	v_mfma_f32_16x16x32_bf16 v[102:105], v[212:215], v[172:175], v[102:105]
	v_mfma_f32_16x16x32_bf16 v[98:101], v[220:223], v[172:175], v[98:101]
	v_mfma_f32_16x16x32_bf16 v[84:87], v[212:215], v[196:199], v[84:87]
	v_mfma_f32_16x16x32_bf16 v[80:83], v[220:223], v[196:199], v[80:83]
	v_mfma_f32_16x16x32_bf16 v[68:71], v[212:215], v[204:207], v[68:71]
	v_mfma_f32_16x16x32_bf16 v[64:67], v[220:223], v[204:207], v[64:67]
	v_mfma_f32_16x16x32_bf16 v[118:121], v[216:219], v[168:171], v[118:121]
	s_waitcnt lgkmcnt(0)
	v_mfma_f32_16x16x32_bf16 v[114:117], v[224:227], v[168:171], v[114:117]
	v_mfma_f32_16x16x32_bf16 v[102:105], v[216:219], v[176:179], v[102:105]
	v_mfma_f32_16x16x32_bf16 v[98:101], v[224:227], v[176:179], v[98:101]
	v_mfma_f32_16x16x32_bf16 v[84:87], v[216:219], v[200:203], v[84:87]
	v_mfma_f32_16x16x32_bf16 v[80:83], v[224:227], v[200:203], v[80:83]
	v_mfma_f32_16x16x32_bf16 v[68:71], v[216:219], v[208:211], v[68:71]
	v_mfma_f32_16x16x32_bf16 v[64:67], v[224:227], v[208:211], v[64:67]
	s_setprio 0
	s_mov_b32 m0, s24
	v_lshl_add_u64 v[228:229], s[6:7], 0, v[130:131]
	s_barrier
	ds_read_b128 v[160:163], v143 offset:16384
	ds_read_b128 v[168:171], v143 offset:17408
	ds_read_b128 v[172:175], v143 offset:18432
	ds_read_b128 v[176:179], v143 offset:19456
	ds_read_b128 v[196:199], v143 offset:20480
	ds_read_b128 v[200:203], v143 offset:21504
	ds_read_b128 v[204:207], v143 offset:22528
	ds_read_b128 v[208:211], v143 offset:23552
	global_load_lds_dwordx4 v[228:229], off
	v_lshl_add_u64 v[230:231], s[6:7], 0, v[132:133]
	s_mov_b32 m0, s41
	s_nop 0
	global_load_lds_dwordx4 v[230:231], off
	s_barrier
	s_setprio 1
	s_waitcnt lgkmcnt(7)
	v_mfma_f32_16x16x32_bf16 v[60:63], v[144:147], v[160:163], v[60:63]
	v_mfma_f32_16x16x32_bf16 v[56:59], v[152:155], v[160:163], v[56:59]
	s_waitcnt lgkmcnt(5)
	v_mfma_f32_16x16x32_bf16 v[44:47], v[144:147], v[172:175], v[44:47]
	v_mfma_f32_16x16x32_bf16 v[40:43], v[152:155], v[172:175], v[40:43]
	s_waitcnt lgkmcnt(3)
	v_mfma_f32_16x16x32_bf16 v[28:31], v[144:147], v[196:199], v[28:31]
	v_mfma_f32_16x16x32_bf16 v[24:27], v[152:155], v[196:199], v[24:27]
	s_waitcnt lgkmcnt(1)
	v_mfma_f32_16x16x32_bf16 v[12:15], v[144:147], v[204:207], v[12:15]
	v_mfma_f32_16x16x32_bf16 v[8:11], v[152:155], v[204:207], v[8:11]
	v_mfma_f32_16x16x32_bf16 v[60:63], v[148:151], v[168:171], v[60:63]
	v_mfma_f32_16x16x32_bf16 v[56:59], v[156:159], v[168:171], v[56:59]
	v_mfma_f32_16x16x32_bf16 v[44:47], v[148:151], v[176:179], v[44:47]
	v_mfma_f32_16x16x32_bf16 v[40:43], v[156:159], v[176:179], v[40:43]
	v_mfma_f32_16x16x32_bf16 v[28:31], v[148:151], v[200:203], v[28:31]
	v_mfma_f32_16x16x32_bf16 v[24:27], v[156:159], v[200:203], v[24:27]
	s_waitcnt lgkmcnt(0)
	v_mfma_f32_16x16x32_bf16 v[12:15], v[148:151], v[208:211], v[12:15]
	v_mfma_f32_16x16x32_bf16 v[8:11], v[156:159], v[208:211], v[8:11]
	s_setprio 0
	s_barrier
; #define PG8_STAGE(bufoff, gbase, voff) do { _Pragma("unroll") for (int _i = 0; _i < 2; ++_i) \
;         __builtin_amdgcn_global_load_lds((const unsigned*)((const char*)(gbase) + (voff)[_i]), (LAS unsigned*)(lds + (bufoff) + ldsw + _i * 8192), 16, 0, 0); } while (0)
; #define PG8_LDA(dst, b, h) do { _Pragma("unroll") for (int m = 0; m < 4; ++m) _Pragma("unroll") for (int k = 0; k < 2; ++k) dst[m][k] = *(const LAS bf16x8*)(lds + PG8_SA(b, h) + aoff + m * 2048 + k * 1024); } while (0)
; #define PG8_LDB(dst, b, h) do { _Pragma("unroll") for (int n = 0; n < 2; ++n) _Pragma("unroll") for (int k = 0; k < 2; ++k) dst[n][k] = *(const LAS bf16x8*)(lds + PG8_SB(b, h) + boff + n * 2048 + k * 1024); } while (0)
; #define PG8_MMA(ai, bj, At, Bt) do { __builtin_amdgcn_s_setprio(1); _Pragma("unroll") for (int m = 0; m < 4; ++m) _Pragma("unroll") for (int n = 0; n < 2; ++n) _Pragma("unroll") for (int k = 0; k < 2; ++k) \
;         acc[ai][bj][m][n] = __builtin_amdgcn_mfma_f32_16x16x32_bf16(Bt[n][k], At[m][k], acc[ai][bj][m][n], 0, 0, 0); __builtin_amdgcn_s_setprio(0); } while (0)
; #define PG8_WAIT_V(n) asm volatile("s_waitcnt vmcnt(" #n ")" ::: "memory")
; #define PG8_WAIT_L(n) asm volatile("s_waitcnt lgkmcnt(" #n ")" ::: "memory")
; #define PG8_BAR __builtin_amdgcn_s_barrier()
; #define PG8_SCHED __builtin_amdgcn_sched_barrier(0)
; template <class Epi, class Sched>
; DI void gemm_phase(LAS unsigned char* lds, const Gemm g, const Sched& S, const Epi& E) {
;     ...
;             PG8_STAGE(PG8_SB(0, 1), b2 + hstepB, voffB);
;             PG8_WAIT_V(6); PG8_BAR; PG8_MMA(1, 1, At, B1); PG8_BAR;
;             PG8_LDB(B0, 1, 0); PG8_SCHED; PG8_LDA(At, 1, 0); PG8_STAGE(PG8_SA(0, 1), a2 + hstepA, voffA);
;             PG8_WAIT_L(8); PG8_BAR; PG8_WAIT_L(0); PG8_MMA(0, 0, At, B0); PG8_BAR; PG8_SCHED;
;             PG8_LDB(B1, 1, 1); PG8_STAGE(PG8_SB(1, 0), b3, voffB);
	s_add_u32 s8, s8, s36
	s_addc_u32 s9, s9, s37
	s_add_i32 s57, s89, s70
	v_lshl_add_u64 v[232:233], s[8:9], 0, v[96:97]
	s_mov_b32 m0, s57
	v_lshl_add_u64 v[234:235], s[8:9], 0, v[134:135]
	global_load_lds_dwordx4 v[232:233], off
	s_add_i32 m0, s57, 0x2000
	s_nop 0
	global_load_lds_dwordx4 v[234:235], off
	s_waitcnt vmcnt(6)
	s_barrier
	s_setprio 1
	v_mfma_f32_16x16x32_bf16 v[52:55], v[212:215], v[160:163], v[52:55]
	v_mfma_f32_16x16x32_bf16 v[48:51], v[220:223], v[160:163], v[48:51]
	v_mfma_f32_16x16x32_bf16 v[36:39], v[212:215], v[172:175], v[36:39]
	v_mfma_f32_16x16x32_bf16 v[32:35], v[220:223], v[172:175], v[32:35]
	v_mfma_f32_16x16x32_bf16 v[20:23], v[212:215], v[196:199], v[20:23]
	v_mfma_f32_16x16x32_bf16 v[16:19], v[220:223], v[196:199], v[16:19]
	v_mfma_f32_16x16x32_bf16 v[4:7], v[212:215], v[204:207], v[4:7]
	v_mfma_f32_16x16x32_bf16 v[0:3], v[220:223], v[204:207], v[0:3]
	v_mfma_f32_16x16x32_bf16 v[52:55], v[216:219], v[168:171], v[52:55]
	v_mfma_f32_16x16x32_bf16 v[48:51], v[224:227], v[168:171], v[48:51]
	v_mfma_f32_16x16x32_bf16 v[36:39], v[216:219], v[176:179], v[36:39]
	v_mfma_f32_16x16x32_bf16 v[32:35], v[224:227], v[176:179], v[32:35]
	v_mfma_f32_16x16x32_bf16 v[20:23], v[216:219], v[200:203], v[20:23]
	v_mfma_f32_16x16x32_bf16 v[16:19], v[224:227], v[200:203], v[16:19]
	v_mfma_f32_16x16x32_bf16 v[4:7], v[216:219], v[208:211], v[4:7]
	v_mfma_f32_16x16x32_bf16 v[0:3], v[224:227], v[208:211], v[0:3]
	s_setprio 0
	s_add_i32 s8, 0, 0x18000
	v_add_u32_e32 v156, s8, v142
	s_barrier
	ds_read_b128 v[144:147], v156
	ds_read_b128 v[148:151], v156 offset:1024
	ds_read_b128 v[152:155], v156 offset:2048
	ds_read_b128 v[156:159], v156 offset:3072
	s_add_u32 s6, s6, s36
	s_addc_u32 s7, s7, s37
	s_mov_b32 m0, s61
	v_lshl_add_u64 v[212:213], s[6:7], 0, v[130:131]
	ds_read_b128 v[160:163], v143 offset:32768
	ds_read_b128 v[168:171], v143 offset:33792
	ds_read_b128 v[172:175], v143 offset:34816
	ds_read_b128 v[176:179], v143 offset:35840
	ds_read_b128 v[196:199], v143 offset:36864
	ds_read_b128 v[200:203], v143 offset:37888
	ds_read_b128 v[204:207], v143 offset:38912
	ds_read_b128 v[208:211], v143 offset:39936
	global_load_lds_dwordx4 v[212:213], off
	v_lshl_add_u64 v[212:213], s[6:7], 0, v[132:133]
	s_mov_b32 m0, s76
	s_nop 0
	global_load_lds_dwordx4 v[212:213], off
	s_waitcnt lgkmcnt(8)
	s_barrier
	s_setprio 1
	s_waitcnt lgkmcnt(7)
	v_mfma_f32_16x16x32_bf16 v[122:125], v[144:147], v[160:163], v[122:125]
	v_mfma_f32_16x16x32_bf16 v[126:129], v[152:155], v[160:163], v[126:129]
	s_waitcnt lgkmcnt(5)
	v_mfma_f32_16x16x32_bf16 v[110:113], v[144:147], v[172:175], v[110:113]
	v_mfma_f32_16x16x32_bf16 v[106:109], v[152:155], v[172:175], v[106:109]
	s_waitcnt lgkmcnt(3)
	v_mfma_f32_16x16x32_bf16 v[92:95], v[144:147], v[196:199], v[92:95]
	v_mfma_f32_16x16x32_bf16 v[88:91], v[152:155], v[196:199], v[88:91]
	s_waitcnt lgkmcnt(1)
	v_mfma_f32_16x16x32_bf16 v[76:79], v[144:147], v[204:207], v[76:79]
	v_mfma_f32_16x16x32_bf16 v[72:75], v[152:155], v[204:207], v[72:75]
	v_mfma_f32_16x16x32_bf16 v[122:125], v[148:151], v[168:171], v[122:125]
	v_mfma_f32_16x16x32_bf16 v[126:129], v[156:159], v[168:171], v[126:129]
	v_mfma_f32_16x16x32_bf16 v[110:113], v[148:151], v[176:179], v[110:113]
	v_mfma_f32_16x16x32_bf16 v[106:109], v[156:159], v[176:179], v[106:109]
	v_mfma_f32_16x16x32_bf16 v[92:95], v[148:151], v[200:203], v[92:95]
	v_mfma_f32_16x16x32_bf16 v[88:91], v[156:159], v[200:203], v[88:91]
	s_waitcnt lgkmcnt(0)
	v_mfma_f32_16x16x32_bf16 v[76:79], v[148:151], v[208:211], v[76:79]
	v_mfma_f32_16x16x32_bf16 v[72:75], v[156:159], v[208:211], v[72:75]
	s_setprio 0
	s_barrier
	s_add_i32 s6, 0, 0x1c000
	s_add_i32 s7, s8, s70
	v_add_u32_e32 v182, s6, v142
	v_lshl_add_u64 v[164:165], v[164:165], 0, s[28:29]
	s_mov_b32 m0, s7
	ds_read_b128 v[212:215], v182
	ds_read_b128 v[216:219], v182 offset:1024
	ds_read_b128 v[220:223], v182 offset:2048
	ds_read_b128 v[224:227], v182 offset:3072
	global_load_lds_dwordx4 v[164:165], off
	v_lshl_add_u64 v[164:165], v[180:181], 0, s[28:29]
	s_add_i32 m0, s7, 0x2000
	s_nop 0
	global_load_lds_dwordx4 v[164:165], off
	s_barrier
; #define PG8_STAGE(bufoff, gbase, voff) do { _Pragma("unroll") for (int _i = 0; _i < 2; ++_i) \
;         __builtin_amdgcn_global_load_lds((const unsigned*)((const char*)(gbase) + (voff)[_i]), (LAS unsigned*)(lds + (bufoff) + ldsw + _i * 8192), 16, 0, 0); } while (0)
; #define PG8_LDA(dst, b, h) do { _Pragma("unroll") for (int m = 0; m < 4; ++m) _Pragma("unroll") for (int k = 0; k < 2; ++k) dst[m][k] = *(const LAS bf16x8*)(lds + PG8_SA(b, h) + aoff + m * 2048 + k * 1024); } while (0)
; #define PG8_MMA(ai, bj, At, Bt) do { __builtin_amdgcn_s_setprio(1); _Pragma("unroll") for (int m = 0; m < 4; ++m) _Pragma("unroll") for (int n = 0; n < 2; ++n) _Pragma("unroll") for (int k = 0; k < 2; ++k) \
;         acc[ai][bj][m][n] = __builtin_amdgcn_mfma_f32_16x16x32_bf16(Bt[n][k], At[m][k], acc[ai][bj][m][n], 0, 0, 0); __builtin_amdgcn_s_setprio(0); } while (0)
; #define PG8_WAIT_V(n) asm volatile("s_waitcnt vmcnt(" #n ")" ::: "memory")
; #define PG8_WAIT_L(n) asm volatile("s_waitcnt lgkmcnt(" #n ")" ::: "memory")
; #define PG8_BAR __builtin_amdgcn_s_barrier()
; #define PG8_SCHED __builtin_amdgcn_sched_barrier(0)
; template <class Epi, class Sched>
; DI void gemm_phase(LAS unsigned char* lds, const Gemm g, const Sched& S, const Epi& E) {
;     ...
;             PG8_BAR; PG8_WAIT_L(0); PG8_MMA(0, 1, At, B1); PG8_BAR;
;             PG8_LDA(At, 1, 1); PG8_STAGE(PG8_SA(1, 0), a3, voffA);
;             PG8_BAR; PG8_WAIT_L(0); PG8_MMA(1, 0, At, B0); PG8_BAR; PG8_SCHED;
;             PG8_STAGE(PG8_SB(1, 1), b3 + hstepB, voffB);
;             PG8_WAIT_V(6); PG8_BAR; PG8_MMA(1, 1, At, B1); PG8_BAR;
	s_setprio 1
	s_waitcnt lgkmcnt(3)
	v_mfma_f32_16x16x32_bf16 v[118:121], v[212:215], v[160:163], v[118:121]
	s_waitcnt lgkmcnt(1)
	v_mfma_f32_16x16x32_bf16 v[114:117], v[220:223], v[160:163], v[114:117]
	v_mfma_f32_16x16x32_bf16 v[102:105], v[212:215], v[172:175], v[102:105]
	v_mfma_f32_16x16x32_bf16 v[98:101], v[220:223], v[172:175], v[98:101]
	v_mfma_f32_16x16x32_bf16 v[84:87], v[212:215], v[196:199], v[84:87]
	v_mfma_f32_16x16x32_bf16 v[80:83], v[220:223], v[196:199], v[80:83]
	v_mfma_f32_16x16x32_bf16 v[68:71], v[212:215], v[204:207], v[68:71]
	v_mfma_f32_16x16x32_bf16 v[64:67], v[220:223], v[204:207], v[64:67]
	v_mfma_f32_16x16x32_bf16 v[118:121], v[216:219], v[168:171], v[118:121]
	s_waitcnt lgkmcnt(0)
	v_mfma_f32_16x16x32_bf16 v[114:117], v[224:227], v[168:171], v[114:117]
	v_mfma_f32_16x16x32_bf16 v[102:105], v[216:219], v[176:179], v[102:105]
	v_mfma_f32_16x16x32_bf16 v[98:101], v[224:227], v[176:179], v[98:101]
	v_mfma_f32_16x16x32_bf16 v[84:87], v[216:219], v[200:203], v[84:87]
	v_mfma_f32_16x16x32_bf16 v[80:83], v[224:227], v[200:203], v[80:83]
	v_mfma_f32_16x16x32_bf16 v[68:71], v[216:219], v[208:211], v[68:71]
	v_mfma_f32_16x16x32_bf16 v[64:67], v[224:227], v[208:211], v[64:67]
	s_setprio 0
	s_mov_b32 m0, s80
	v_lshl_add_u64 v[164:165], v[228:229], 0, s[28:29]
	s_barrier
	ds_read_b128 v[160:163], v143 offset:49152
	ds_read_b128 v[168:171], v143 offset:50176
	ds_read_b128 v[172:175], v143 offset:51200
	ds_read_b128 v[176:179], v143 offset:52224
	ds_read_b128 v[196:199], v143 offset:53248
	ds_read_b128 v[200:203], v143 offset:54272
	ds_read_b128 v[204:207], v143 offset:55296
	ds_read_b128 v[208:211], v143 offset:56320
	global_load_lds_dwordx4 v[164:165], off
	v_lshl_add_u64 v[164:165], v[230:231], 0, s[28:29]
	s_mov_b32 m0, s81
	s_nop 0
	global_load_lds_dwordx4 v[164:165], off
	s_barrier
	s_setprio 1
	s_waitcnt lgkmcnt(7)
	v_mfma_f32_16x16x32_bf16 v[60:63], v[144:147], v[160:163], v[60:63]
	v_mfma_f32_16x16x32_bf16 v[56:59], v[152:155], v[160:163], v[56:59]
	s_waitcnt lgkmcnt(5)
	v_mfma_f32_16x16x32_bf16 v[44:47], v[144:147], v[172:175], v[44:47]
	v_mfma_f32_16x16x32_bf16 v[40:43], v[152:155], v[172:175], v[40:43]
	s_waitcnt lgkmcnt(3)
	v_mfma_f32_16x16x32_bf16 v[28:31], v[144:147], v[196:199], v[28:31]
	v_mfma_f32_16x16x32_bf16 v[24:27], v[152:155], v[196:199], v[24:27]
	s_waitcnt lgkmcnt(1)
	v_mfma_f32_16x16x32_bf16 v[12:15], v[144:147], v[204:207], v[12:15]
	v_mfma_f32_16x16x32_bf16 v[8:11], v[152:155], v[204:207], v[8:11]
	v_mfma_f32_16x16x32_bf16 v[60:63], v[148:151], v[168:171], v[60:63]
	v_mfma_f32_16x16x32_bf16 v[56:59], v[156:159], v[168:171], v[56:59]
	v_mfma_f32_16x16x32_bf16 v[44:47], v[148:151], v[176:179], v[44:47]
	v_mfma_f32_16x16x32_bf16 v[40:43], v[156:159], v[176:179], v[40:43]
	v_mfma_f32_16x16x32_bf16 v[28:31], v[148:151], v[200:203], v[28:31]
	v_mfma_f32_16x16x32_bf16 v[24:27], v[156:159], v[200:203], v[24:27]
	s_waitcnt lgkmcnt(0)
	v_mfma_f32_16x16x32_bf16 v[12:15], v[148:151], v[208:211], v[12:15]
	v_mfma_f32_16x16x32_bf16 v[8:11], v[156:159], v[208:211], v[8:11]
	s_setprio 0
	s_barrier
	s_add_i32 s6, s6, s70
	v_lshl_add_u64 v[144:145], v[232:233], 0, s[28:29]
	s_mov_b32 m0, s6
	s_nop 0
	global_load_lds_dwordx4 v[144:145], off
	v_lshl_add_u64 v[144:145], v[234:235], 0, s[28:29]
	s_add_i32 m0, s6, 0x2000
	s_nop 0
	global_load_lds_dwordx4 v[144:145], off
	s_waitcnt vmcnt(6)
	s_barrier
	s_setprio 1
	v_mfma_f32_16x16x32_bf16 v[52:55], v[212:215], v[160:163], v[52:55]
	v_mfma_f32_16x16x32_bf16 v[48:51], v[220:223], v[160:163], v[48:51]
	v_mfma_f32_16x16x32_bf16 v[36:39], v[212:215], v[172:175], v[36:39]
	v_mfma_f32_16x16x32_bf16 v[32:35], v[220:223], v[172:175], v[32:35]
	v_mfma_f32_16x16x32_bf16 v[20:23], v[212:215], v[196:199], v[20:23]
	v_mfma_f32_16x16x32_bf16 v[16:19], v[220:223], v[196:199], v[16:19]
	v_mfma_f32_16x16x32_bf16 v[4:7], v[212:215], v[204:207], v[4:7]
	v_mfma_f32_16x16x32_bf16 v[0:3], v[220:223], v[204:207], v[0:3]
	v_mfma_f32_16x16x32_bf16 v[52:55], v[216:219], v[168:171], v[52:55]
	v_mfma_f32_16x16x32_bf16 v[48:51], v[224:227], v[168:171], v[48:51]
	v_mfma_f32_16x16x32_bf16 v[36:39], v[216:219], v[176:179], v[36:39]
	v_mfma_f32_16x16x32_bf16 v[32:35], v[224:227], v[176:179], v[32:35]
	v_mfma_f32_16x16x32_bf16 v[20:23], v[216:219], v[200:203], v[20:23]
	v_mfma_f32_16x16x32_bf16 v[16:19], v[224:227], v[200:203], v[16:19]
	v_mfma_f32_16x16x32_bf16 v[4:7], v[216:219], v[208:211], v[4:7]
	v_mfma_f32_16x16x32_bf16 v[0:3], v[224:227], v[208:211], v[0:3]
	s_setprio 0
	s_add_u32 s87, s87, 0x100
	s_addc_u32 s88, s88, 0
	s_add_u32 s54, s54, 0x100
	s_addc_u32 s55, s55, 0
	s_cmp_ge_i32 s56, s77
	s_mov_b32 s6, s56
	s_barrier
	s_cbranch_scc0 .LBB0_784
	s_branch .LBB0_771

; #define PG8_STAGE(bufoff, gbase, voff) do { _Pragma("unroll") for (int _i = 0; _i < 2; ++_i) \
;         __builtin_amdgcn_global_load_lds((const unsigned*)((const char*)(gbase) + (voff)[_i]), (LAS unsigned*)(lds + (bufoff) + ldsw + _i * 8192), 16, 0, 0); } while (0)
; #define PG8_LDA(dst, b, h) do { _Pragma("unroll") for (int m = 0; m < 4; ++m) _Pragma("unroll") for (int k = 0; k < 2; ++k) dst[m][k] = *(const LAS bf16x8*)(lds + PG8_SA(b, h) + aoff + m * 2048 + k * 1024); } while (0)
; #define PG8_LDB(dst, b, h) do { _Pragma("unroll") for (int n = 0; n < 2; ++n) _Pragma("unroll") for (int k = 0; k < 2; ++k) dst[n][k] = *(const LAS bf16x8*)(lds + PG8_SB(b, h) + boff + n * 2048 + k * 1024); } while (0)
; #define PG8_MMA(ai, bj, At, Bt) do { __builtin_amdgcn_s_setprio(1); _Pragma("unroll") for (int m = 0; m < 4; ++m) _Pragma("unroll") for (int n = 0; n < 2; ++n) _Pragma("unroll") for (int k = 0; k < 2; ++k) \
;         acc[ai][bj][m][n] = __builtin_amdgcn_mfma_f32_16x16x32_bf16(Bt[n][k], At[m][k], acc[ai][bj][m][n], 0, 0, 0); __builtin_amdgcn_s_setprio(0); } while (0)
; #define PG8_WAIT_L(n) asm volatile("s_waitcnt lgkmcnt(" #n ")" ::: "memory")
; template <class Epi, class Sched>
; DI void gemm_phase(LAS unsigned char* lds, const Gemm g, const Sched& S, const Epi& E) {
;     ...
;         const char* nA = has_next ? (const char*)g.A + (size_t)nxt.pm * tstepA : cA; const char* nB = has_next ? (const char*)g.Bt + (size_t)nxt.pn * tstepB : cB;
; #pragma nounroll
;         for (int t = 0; t < nt; t += 2) {
;             const bool last = (t == nt - 2);
;             const char* a1 = cA + (size_t)(t + 1) * kstep;
;             const char* a2 = last ? nA : cA + (size_t)(t + 2) * kstep; const char* b2 = last ? nB : cB + (size_t)(t + 2) * kstep;
;             const char* a3 = a2 + kstep; const char* b3 = b2 + kstep;
;             if (last && has_next) S.a_ready(nxt);
;             PG8_LDB(B0, 0, 0); PG8_SCHED; PG8_LDA(At, 0, 0); PG8_STAGE(PG8_SA(1, 1), a1 + hstepA, voffA);
;             PG8_WAIT_L(8); PG8_BAR; PG8_WAIT_L(0); PG8_MMA(0, 0, At, B0); PG8_BAR; PG8_SCHED;
;             PG8_LDB(B1, 0, 1); PG8_STAGE(PG8_SB(0, 0), b2, voffB);
;             PG8_BAR; PG8_WAIT_L(0); PG8_MMA(0, 1, At, B1); PG8_BAR;
;             PG8_LDA(At, 0, 1); PG8_STAGE(PG8_SA(0, 0), a2, voffA);
;             PG8_BAR; PG8_WAIT_L(0); PG8_MMA(1, 0, At, B0); PG8_BAR; PG8_SCHED;
.LBB0_982:
	s_add_i32 s56, s6, 2
	s_add_u32 s8, s54, 0x80
	s_addc_u32 s7, s55, 0
	s_add_i32 s57, 0, 0x10000
	v_add_u32_e32 v156, s57, v142
	ds_read_b128 v[144:147], v156
	ds_read_b128 v[148:151], v156 offset:1024
	ds_read_b128 v[152:155], v156 offset:2048
	ds_read_b128 v[156:159], v156 offset:3072
	s_cmp_eq_u32 s81, s6
	s_cselect_b32 s6, s44, s8
	s_cselect_b32 s7, s45, s7
	s_cselect_b32 s9, s47, s86
	s_cselect_b32 s8, s46, s85
	v_lshl_add_u64 v[164:165], s[54:55], 0, v[138:139]
	s_add_i32 m0, s24, 0xc000
	ds_read_b128 v[160:163], v143
	ds_read_b128 v[168:171], v143 offset:1024
	ds_read_b128 v[172:175], v143 offset:2048
	ds_read_b128 v[176:179], v143 offset:3072
	ds_read_b128 v[196:199], v143 offset:4096
	ds_read_b128 v[200:203], v143 offset:5120
	ds_read_b128 v[204:207], v143 offset:6144
	ds_read_b128 v[208:211], v143 offset:7168
	global_load_lds_dwordx4 v[164:165], off
	v_lshl_add_u64 v[164:165], s[54:55], 0, v[136:137]
	s_add_i32 m0, s24, 0xe000
	s_nop 0
	global_load_lds_dwordx4 v[164:165], off
	s_waitcnt lgkmcnt(8)
	s_barrier
	s_setprio 1
	s_waitcnt lgkmcnt(7)
	v_mfma_f32_16x16x32_bf16 v[122:125], v[144:147], v[160:163], v[122:125]
	v_mfma_f32_16x16x32_bf16 v[126:129], v[152:155], v[160:163], v[126:129]
	s_waitcnt lgkmcnt(5)
	v_mfma_f32_16x16x32_bf16 v[110:113], v[144:147], v[172:175], v[110:113]
	v_mfma_f32_16x16x32_bf16 v[106:109], v[152:155], v[172:175], v[106:109]
	s_waitcnt lgkmcnt(3)
	v_mfma_f32_16x16x32_bf16 v[92:95], v[144:147], v[196:199], v[92:95]
	v_mfma_f32_16x16x32_bf16 v[88:91], v[152:155], v[196:199], v[88:91]
	s_waitcnt lgkmcnt(1)
	v_mfma_f32_16x16x32_bf16 v[76:79], v[144:147], v[204:207], v[76:79]
	v_mfma_f32_16x16x32_bf16 v[72:75], v[152:155], v[204:207], v[72:75]
	v_mfma_f32_16x16x32_bf16 v[122:125], v[148:151], v[168:171], v[122:125]
	v_mfma_f32_16x16x32_bf16 v[126:129], v[156:159], v[168:171], v[126:129]
	v_mfma_f32_16x16x32_bf16 v[110:113], v[148:151], v[176:179], v[110:113]
	v_mfma_f32_16x16x32_bf16 v[106:109], v[156:159], v[176:179], v[106:109]
	v_mfma_f32_16x16x32_bf16 v[92:95], v[148:151], v[200:203], v[92:95]
	v_mfma_f32_16x16x32_bf16 v[88:91], v[156:159], v[200:203], v[88:91]
	s_waitcnt lgkmcnt(0)
	v_mfma_f32_16x16x32_bf16 v[76:79], v[148:151], v[208:211], v[76:79]
	v_mfma_f32_16x16x32_bf16 v[72:75], v[156:159], v[208:211], v[72:75]
	s_setprio 0
	s_barrier
	s_add_i32 s87, 0, 0x14000
	v_add_u32_e32 v164, s87, v142
	s_add_i32 s57, s57, s68
	ds_read_b128 v[212:215], v164
	ds_read_b128 v[216:219], v164 offset:1024
	ds_read_b128 v[220:223], v164 offset:2048
	ds_read_b128 v[224:227], v164 offset:3072
	v_lshl_add_u64 v[164:165], s[8:9], 0, v[96:97]
	s_mov_b32 m0, s57
	v_lshl_add_u64 v[180:181], s[8:9], 0, v[134:135]
	global_load_lds_dwordx4 v[164:165], off
	s_add_i32 m0, s57, 0x2000
	s_nop 0
	global_load_lds_dwordx4 v[180:181], off
	s_barrier
	s_setprio 1
	s_waitcnt lgkmcnt(3)
	v_mfma_f32_16x16x32_bf16 v[118:121], v[212:215], v[160:163], v[118:121]
	s_waitcnt lgkmcnt(1)
	v_mfma_f32_16x16x32_bf16 v[114:117], v[220:223], v[160:163], v[114:117]
	v_mfma_f32_16x16x32_bf16 v[102:105], v[212:215], v[172:175], v[102:105]
	v_mfma_f32_16x16x32_bf16 v[98:101], v[220:223], v[172:175], v[98:101]
	v_mfma_f32_16x16x32_bf16 v[84:87], v[212:215], v[196:199], v[84:87]
	v_mfma_f32_16x16x32_bf16 v[80:83], v[220:223], v[196:199], v[80:83]
	v_mfma_f32_16x16x32_bf16 v[68:71], v[212:215], v[204:207], v[68:71]
	v_mfma_f32_16x16x32_bf16 v[64:67], v[220:223], v[204:207], v[64:67]
	v_mfma_f32_16x16x32_bf16 v[118:121], v[216:219], v[168:171], v[118:121]
	s_waitcnt lgkmcnt(0)
	v_mfma_f32_16x16x32_bf16 v[114:117], v[224:227], v[168:171], v[114:117]
	v_mfma_f32_16x16x32_bf16 v[102:105], v[216:219], v[176:179], v[102:105]
	v_mfma_f32_16x16x32_bf16 v[98:101], v[224:227], v[176:179], v[98:101]
	v_mfma_f32_16x16x32_bf16 v[84:87], v[216:219], v[200:203], v[84:87]
	v_mfma_f32_16x16x32_bf16 v[80:83], v[224:227], v[200:203], v[80:83]
	v_mfma_f32_16x16x32_bf16 v[68:71], v[216:219], v[208:211], v[68:71]
	v_mfma_f32_16x16x32_bf16 v[64:67], v[224:227], v[208:211], v[64:67]
	s_setprio 0
	s_mov_b32 m0, s24
	v_lshl_add_u64 v[228:229], s[6:7], 0, v[130:131]
	s_barrier
	ds_read_b128 v[160:163], v143 offset:16384
	ds_read_b128 v[168:171], v143 offset:17408
	ds_read_b128 v[172:175], v143 offset:18432
	ds_read_b128 v[176:179], v143 offset:19456
	ds_read_b128 v[196:199], v143 offset:20480
	ds_read_b128 v[200:203], v143 offset:21504
	ds_read_b128 v[204:207], v143 offset:22528
	ds_read_b128 v[208:211], v143 offset:23552
	global_load_lds_dwordx4 v[228:229], off
	v_lshl_add_u64 v[230:231], s[6:7], 0, v[132:133]
	s_mov_b32 m0, s41
	s_nop 0
	global_load_lds_dwordx4 v[230:231], off
	s_barrier
	s_setprio 1
	s_waitcnt lgkmcnt(7)
	v_mfma_f32_16x16x32_bf16 v[60:63], v[144:147], v[160:163], v[60:63]
	v_mfma_f32_16x16x32_bf16 v[56:59], v[152:155], v[160:163], v[56:59]
	s_waitcnt lgkmcnt(5)
	v_mfma_f32_16x16x32_bf16 v[44:47], v[144:147], v[172:175], v[44:47]
	v_mfma_f32_16x16x32_bf16 v[40:43], v[152:155], v[172:175], v[40:43]
	s_waitcnt lgkmcnt(3)
	v_mfma_f32_16x16x32_bf16 v[28:31], v[144:147], v[196:199], v[28:31]
	v_mfma_f32_16x16x32_bf16 v[24:27], v[152:155], v[196:199], v[24:27]
	s_waitcnt lgkmcnt(1)
	v_mfma_f32_16x16x32_bf16 v[12:15], v[144:147], v[204:207], v[12:15]
	v_mfma_f32_16x16x32_bf16 v[8:11], v[152:155], v[204:207], v[8:11]
	v_mfma_f32_16x16x32_bf16 v[60:63], v[148:151], v[168:171], v[60:63]
	v_mfma_f32_16x16x32_bf16 v[56:59], v[156:159], v[168:171], v[56:59]
	v_mfma_f32_16x16x32_bf16 v[44:47], v[148:151], v[176:179], v[44:47]
	v_mfma_f32_16x16x32_bf16 v[40:43], v[156:159], v[176:179], v[40:43]
	v_mfma_f32_16x16x32_bf16 v[28:31], v[148:151], v[200:203], v[28:31]
	v_mfma_f32_16x16x32_bf16 v[24:27], v[156:159], v[200:203], v[24:27]
	s_waitcnt lgkmcnt(0)
	v_mfma_f32_16x16x32_bf16 v[12:15], v[148:151], v[208:211], v[12:15]
	v_mfma_f32_16x16x32_bf16 v[8:11], v[156:159], v[208:211], v[8:11]
	s_setprio 0
	s_barrier
; #define PG8_STAGE(bufoff, gbase, voff) do { _Pragma("unroll") for (int _i = 0; _i < 2; ++_i) \
;         __builtin_amdgcn_global_load_lds((const unsigned*)((const char*)(gbase) + (voff)[_i]), (LAS unsigned*)(lds + (bufoff) + ldsw + _i * 8192), 16, 0, 0); } while (0)
; #define PG8_LDA(dst, b, h) do { _Pragma("unroll") for (int m = 0; m < 4; ++m) _Pragma("unroll") for (int k = 0; k < 2; ++k) dst[m][k] = *(const LAS bf16x8*)(lds + PG8_SA(b, h) + aoff + m * 2048 + k * 1024); } while (0)
; #define PG8_LDB(dst, b, h) do { _Pragma("unroll") for (int n = 0; n < 2; ++n) _Pragma("unroll") for (int k = 0; k < 2; ++k) dst[n][k] = *(const LAS bf16x8*)(lds + PG8_SB(b, h) + boff + n * 2048 + k * 1024); } while (0)
; #define PG8_MMA(ai, bj, At, Bt) do { __builtin_amdgcn_s_setprio(1); _Pragma("unroll") for (int m = 0; m < 4; ++m) _Pragma("unroll") for (int n = 0; n < 2; ++n) _Pragma("unroll") for (int k = 0; k < 2; ++k) \
;         acc[ai][bj][m][n] = __builtin_amdgcn_mfma_f32_16x16x32_bf16(Bt[n][k], At[m][k], acc[ai][bj][m][n], 0, 0, 0); __builtin_amdgcn_s_setprio(0); } while (0)
; #define PG8_WAIT_V(n) asm volatile("s_waitcnt vmcnt(" #n ")" ::: "memory")
; #define PG8_WAIT_L(n) asm volatile("s_waitcnt lgkmcnt(" #n ")" ::: "memory")
; #define PG8_BAR __builtin_amdgcn_s_barrier()
; #define PG8_SCHED __builtin_amdgcn_sched_barrier(0)
; template <class Epi, class Sched>
; DI void gemm_phase(LAS unsigned char* lds, const Gemm g, const Sched& S, const Epi& E) {
;     ...
;             PG8_STAGE(PG8_SB(0, 1), b2 + hstepB, voffB);
;             PG8_WAIT_V(6); PG8_BAR; PG8_MMA(1, 1, At, B1); PG8_BAR;
;             PG8_LDB(B0, 1, 0); PG8_SCHED; PG8_LDA(At, 1, 0); PG8_STAGE(PG8_SA(0, 1), a2 + hstepA, voffA);
;             PG8_WAIT_L(8); PG8_BAR; PG8_WAIT_L(0); PG8_MMA(0, 0, At, B0); PG8_BAR; PG8_SCHED;
;             PG8_LDB(B1, 1, 1); PG8_STAGE(PG8_SB(1, 0), b3, voffB);
	s_add_u32 s8, s8, s36
	s_addc_u32 s9, s9, s37
	s_add_i32 s57, s87, s68
	v_lshl_add_u64 v[232:233], s[8:9], 0, v[96:97]
	s_mov_b32 m0, s57
	v_lshl_add_u64 v[234:235], s[8:9], 0, v[134:135]
	global_load_lds_dwordx4 v[232:233], off
	s_add_i32 m0, s57, 0x2000
	s_nop 0
	global_load_lds_dwordx4 v[234:235], off
	s_waitcnt vmcnt(6)
	s_barrier
	s_setprio 1
	v_mfma_f32_16x16x32_bf16 v[52:55], v[212:215], v[160:163], v[52:55]
	v_mfma_f32_16x16x32_bf16 v[48:51], v[220:223], v[160:163], v[48:51]
	v_mfma_f32_16x16x32_bf16 v[36:39], v[212:215], v[172:175], v[36:39]
	v_mfma_f32_16x16x32_bf16 v[32:35], v[220:223], v[172:175], v[32:35]
	v_mfma_f32_16x16x32_bf16 v[20:23], v[212:215], v[196:199], v[20:23]
	v_mfma_f32_16x16x32_bf16 v[16:19], v[220:223], v[196:199], v[16:19]
	v_mfma_f32_16x16x32_bf16 v[4:7], v[212:215], v[204:207], v[4:7]
	v_mfma_f32_16x16x32_bf16 v[0:3], v[220:223], v[204:207], v[0:3]
	v_mfma_f32_16x16x32_bf16 v[52:55], v[216:219], v[168:171], v[52:55]
	v_mfma_f32_16x16x32_bf16 v[48:51], v[224:227], v[168:171], v[48:51]
	v_mfma_f32_16x16x32_bf16 v[36:39], v[216:219], v[176:179], v[36:39]
	v_mfma_f32_16x16x32_bf16 v[32:35], v[224:227], v[176:179], v[32:35]
	v_mfma_f32_16x16x32_bf16 v[20:23], v[216:219], v[200:203], v[20:23]
	v_mfma_f32_16x16x32_bf16 v[16:19], v[224:227], v[200:203], v[16:19]
	v_mfma_f32_16x16x32_bf16 v[4:7], v[216:219], v[208:211], v[4:7]
	v_mfma_f32_16x16x32_bf16 v[0:3], v[224:227], v[208:211], v[0:3]
	s_setprio 0
	s_add_i32 s8, 0, 0x18000
	v_add_u32_e32 v156, s8, v142
	s_barrier
	ds_read_b128 v[144:147], v156
	ds_read_b128 v[148:151], v156 offset:1024
	ds_read_b128 v[152:155], v156 offset:2048
	ds_read_b128 v[156:159], v156 offset:3072
	s_add_u32 s6, s6, s36
	s_addc_u32 s7, s7, s37
	s_mov_b32 m0, s73
	v_lshl_add_u64 v[212:213], s[6:7], 0, v[130:131]
	ds_read_b128 v[160:163], v143 offset:32768
	ds_read_b128 v[168:171], v143 offset:33792
	ds_read_b128 v[172:175], v143 offset:34816
	ds_read_b128 v[176:179], v143 offset:35840
	ds_read_b128 v[196:199], v143 offset:36864
	ds_read_b128 v[200:203], v143 offset:37888
	ds_read_b128 v[204:207], v143 offset:38912
	ds_read_b128 v[208:211], v143 offset:39936
	global_load_lds_dwordx4 v[212:213], off
	v_lshl_add_u64 v[212:213], s[6:7], 0, v[132:133]
	s_mov_b32 m0, s74
	s_nop 0
	global_load_lds_dwordx4 v[212:213], off
	s_waitcnt lgkmcnt(8)
	s_barrier
	s_setprio 1
	s_waitcnt lgkmcnt(7)
	v_mfma_f32_16x16x32_bf16 v[122:125], v[144:147], v[160:163], v[122:125]
	v_mfma_f32_16x16x32_bf16 v[126:129], v[152:155], v[160:163], v[126:129]
	s_waitcnt lgkmcnt(5)
	v_mfma_f32_16x16x32_bf16 v[110:113], v[144:147], v[172:175], v[110:113]
	v_mfma_f32_16x16x32_bf16 v[106:109], v[152:155], v[172:175], v[106:109]
	s_waitcnt lgkmcnt(3)
	v_mfma_f32_16x16x32_bf16 v[92:95], v[144:147], v[196:199], v[92:95]
	v_mfma_f32_16x16x32_bf16 v[88:91], v[152:155], v[196:199], v[88:91]
	s_waitcnt lgkmcnt(1)
	v_mfma_f32_16x16x32_bf16 v[76:79], v[144:147], v[204:207], v[76:79]
	v_mfma_f32_16x16x32_bf16 v[72:75], v[152:155], v[204:207], v[72:75]
	v_mfma_f32_16x16x32_bf16 v[122:125], v[148:151], v[168:171], v[122:125]
	v_mfma_f32_16x16x32_bf16 v[126:129], v[156:159], v[168:171], v[126:129]
	v_mfma_f32_16x16x32_bf16 v[110:113], v[148:151], v[176:179], v[110:113]
	v_mfma_f32_16x16x32_bf16 v[106:109], v[156:159], v[176:179], v[106:109]
	v_mfma_f32_16x16x32_bf16 v[92:95], v[148:151], v[200:203], v[92:95]
	v_mfma_f32_16x16x32_bf16 v[88:91], v[156:159], v[200:203], v[88:91]
	s_waitcnt lgkmcnt(0)
	v_mfma_f32_16x16x32_bf16 v[76:79], v[148:151], v[208:211], v[76:79]
	v_mfma_f32_16x16x32_bf16 v[72:75], v[156:159], v[208:211], v[72:75]
	s_setprio 0
	s_barrier
	s_add_i32 s6, 0, 0x1c000
	s_add_i32 s7, s8, s68
	v_add_u32_e32 v182, s6, v142
	v_lshl_add_u64 v[164:165], v[164:165], 0, s[28:29]
	s_mov_b32 m0, s7
	ds_read_b128 v[212:215], v182
	ds_read_b128 v[216:219], v182 offset:1024
	ds_read_b128 v[220:223], v182 offset:2048
	ds_read_b128 v[224:227], v182 offset:3072
	global_load_lds_dwordx4 v[164:165], off
	v_lshl_add_u64 v[164:165], v[180:181], 0, s[28:29]
	s_add_i32 m0, s7, 0x2000
	s_nop 0
	global_load_lds_dwordx4 v[164:165], off
	s_barrier
; #define PG8_STAGE(bufoff, gbase, voff) do { _Pragma("unroll") for (int _i = 0; _i < 2; ++_i) \
;         __builtin_amdgcn_global_load_lds((const unsigned*)((const char*)(gbase) + (voff)[_i]), (LAS unsigned*)(lds + (bufoff) + ldsw + _i * 8192), 16, 0, 0); } while (0)
; #define PG8_LDA(dst, b, h) do { _Pragma("unroll") for (int m = 0; m < 4; ++m) _Pragma("unroll") for (int k = 0; k < 2; ++k) dst[m][k] = *(const LAS bf16x8*)(lds + PG8_SA(b, h) + aoff + m * 2048 + k * 1024); } while (0)
; #define PG8_MMA(ai, bj, At, Bt) do { __builtin_amdgcn_s_setprio(1); _Pragma("unroll") for (int m = 0; m < 4; ++m) _Pragma("unroll") for (int n = 0; n < 2; ++n) _Pragma("unroll") for (int k = 0; k < 2; ++k) \
;         acc[ai][bj][m][n] = __builtin_amdgcn_mfma_f32_16x16x32_bf16(Bt[n][k], At[m][k], acc[ai][bj][m][n], 0, 0, 0); __builtin_amdgcn_s_setprio(0); } while (0)
; #define PG8_WAIT_V(n) asm volatile("s_waitcnt vmcnt(" #n ")" ::: "memory")
; #define PG8_WAIT_L(n) asm volatile("s_waitcnt lgkmcnt(" #n ")" ::: "memory")
; #define PG8_BAR __builtin_amdgcn_s_barrier()
; #define PG8_SCHED __builtin_amdgcn_sched_barrier(0)
; template <class Epi, class Sched>
; DI void gemm_phase(LAS unsigned char* lds, const Gemm g, const Sched& S, const Epi& E) {
;     ...
;             PG8_BAR; PG8_WAIT_L(0); PG8_MMA(0, 1, At, B1); PG8_BAR;
;             PG8_LDA(At, 1, 1); PG8_STAGE(PG8_SA(1, 0), a3, voffA);
;             PG8_BAR; PG8_WAIT_L(0); PG8_MMA(1, 0, At, B0); PG8_BAR; PG8_SCHED;
;             PG8_STAGE(PG8_SB(1, 1), b3 + hstepB, voffB);
;             PG8_WAIT_V(6); PG8_BAR; PG8_MMA(1, 1, At, B1); PG8_BAR;
	s_setprio 1
	s_waitcnt lgkmcnt(3)
	v_mfma_f32_16x16x32_bf16 v[118:121], v[212:215], v[160:163], v[118:121]
	s_waitcnt lgkmcnt(1)
	v_mfma_f32_16x16x32_bf16 v[114:117], v[220:223], v[160:163], v[114:117]
	v_mfma_f32_16x16x32_bf16 v[102:105], v[212:215], v[172:175], v[102:105]
	v_mfma_f32_16x16x32_bf16 v[98:101], v[220:223], v[172:175], v[98:101]
	v_mfma_f32_16x16x32_bf16 v[84:87], v[212:215], v[196:199], v[84:87]
	v_mfma_f32_16x16x32_bf16 v[80:83], v[220:223], v[196:199], v[80:83]
	v_mfma_f32_16x16x32_bf16 v[68:71], v[212:215], v[204:207], v[68:71]
	v_mfma_f32_16x16x32_bf16 v[64:67], v[220:223], v[204:207], v[64:67]
	v_mfma_f32_16x16x32_bf16 v[118:121], v[216:219], v[168:171], v[118:121]
	s_waitcnt lgkmcnt(0)
	v_mfma_f32_16x16x32_bf16 v[114:117], v[224:227], v[168:171], v[114:117]
	v_mfma_f32_16x16x32_bf16 v[102:105], v[216:219], v[176:179], v[102:105]
	v_mfma_f32_16x16x32_bf16 v[98:101], v[224:227], v[176:179], v[98:101]
	v_mfma_f32_16x16x32_bf16 v[84:87], v[216:219], v[200:203], v[84:87]
	v_mfma_f32_16x16x32_bf16 v[80:83], v[224:227], v[200:203], v[80:83]
	v_mfma_f32_16x16x32_bf16 v[68:71], v[216:219], v[208:211], v[68:71]
	v_mfma_f32_16x16x32_bf16 v[64:67], v[224:227], v[208:211], v[64:67]
	s_setprio 0
	s_mov_b32 m0, s78
	v_lshl_add_u64 v[164:165], v[228:229], 0, s[28:29]
	s_barrier
	ds_read_b128 v[160:163], v143 offset:49152
	ds_read_b128 v[168:171], v143 offset:50176
	ds_read_b128 v[172:175], v143 offset:51200
	ds_read_b128 v[176:179], v143 offset:52224
	ds_read_b128 v[196:199], v143 offset:53248
	ds_read_b128 v[200:203], v143 offset:54272
	ds_read_b128 v[204:207], v143 offset:55296
	ds_read_b128 v[208:211], v143 offset:56320
	global_load_lds_dwordx4 v[164:165], off
	v_lshl_add_u64 v[164:165], v[230:231], 0, s[28:29]
	s_mov_b32 m0, s80
	s_nop 0
	global_load_lds_dwordx4 v[164:165], off
	s_barrier
	s_setprio 1
	s_waitcnt lgkmcnt(7)
	v_mfma_f32_16x16x32_bf16 v[60:63], v[144:147], v[160:163], v[60:63]
	v_mfma_f32_16x16x32_bf16 v[56:59], v[152:155], v[160:163], v[56:59]
	s_waitcnt lgkmcnt(5)
	v_mfma_f32_16x16x32_bf16 v[44:47], v[144:147], v[172:175], v[44:47]
	v_mfma_f32_16x16x32_bf16 v[40:43], v[152:155], v[172:175], v[40:43]
	s_waitcnt lgkmcnt(3)
	v_mfma_f32_16x16x32_bf16 v[28:31], v[144:147], v[196:199], v[28:31]
	v_mfma_f32_16x16x32_bf16 v[24:27], v[152:155], v[196:199], v[24:27]
	s_waitcnt lgkmcnt(1)
	v_mfma_f32_16x16x32_bf16 v[12:15], v[144:147], v[204:207], v[12:15]
	v_mfma_f32_16x16x32_bf16 v[8:11], v[152:155], v[204:207], v[8:11]
	v_mfma_f32_16x16x32_bf16 v[60:63], v[148:151], v[168:171], v[60:63]
	v_mfma_f32_16x16x32_bf16 v[56:59], v[156:159], v[168:171], v[56:59]
	v_mfma_f32_16x16x32_bf16 v[44:47], v[148:151], v[176:179], v[44:47]
	v_mfma_f32_16x16x32_bf16 v[40:43], v[156:159], v[176:179], v[40:43]
	v_mfma_f32_16x16x32_bf16 v[28:31], v[148:151], v[200:203], v[28:31]
	v_mfma_f32_16x16x32_bf16 v[24:27], v[156:159], v[200:203], v[24:27]
	s_waitcnt lgkmcnt(0)
	v_mfma_f32_16x16x32_bf16 v[12:15], v[148:151], v[208:211], v[12:15]
	v_mfma_f32_16x16x32_bf16 v[8:11], v[156:159], v[208:211], v[8:11]
	s_setprio 0
	s_barrier
	s_add_i32 s6, s6, s68
	v_lshl_add_u64 v[144:145], v[232:233], 0, s[28:29]
	s_mov_b32 m0, s6
	s_nop 0
	global_load_lds_dwordx4 v[144:145], off
	v_lshl_add_u64 v[144:145], v[234:235], 0, s[28:29]
	s_add_i32 m0, s6, 0x2000
	s_nop 0
	global_load_lds_dwordx4 v[144:145], off
	s_waitcnt vmcnt(6)
	s_barrier
	s_setprio 1
	v_mfma_f32_16x16x32_bf16 v[52:55], v[212:215], v[160:163], v[52:55]
	v_mfma_f32_16x16x32_bf16 v[48:51], v[220:223], v[160:163], v[48:51]
	v_mfma_f32_16x16x32_bf16 v[36:39], v[212:215], v[172:175], v[36:39]
	v_mfma_f32_16x16x32_bf16 v[32:35], v[220:223], v[172:175], v[32:35]
	v_mfma_f32_16x16x32_bf16 v[20:23], v[212:215], v[196:199], v[20:23]
	v_mfma_f32_16x16x32_bf16 v[16:19], v[220:223], v[196:199], v[16:19]
	v_mfma_f32_16x16x32_bf16 v[4:7], v[212:215], v[204:207], v[4:7]
	v_mfma_f32_16x16x32_bf16 v[0:3], v[220:223], v[204:207], v[0:3]
	v_mfma_f32_16x16x32_bf16 v[52:55], v[216:219], v[168:171], v[52:55]
	v_mfma_f32_16x16x32_bf16 v[48:51], v[224:227], v[168:171], v[48:51]
	v_mfma_f32_16x16x32_bf16 v[36:39], v[216:219], v[176:179], v[36:39]
	v_mfma_f32_16x16x32_bf16 v[32:35], v[224:227], v[176:179], v[32:35]
	v_mfma_f32_16x16x32_bf16 v[20:23], v[216:219], v[200:203], v[20:23]
	v_mfma_f32_16x16x32_bf16 v[16:19], v[224:227], v[200:203], v[16:19]
	v_mfma_f32_16x16x32_bf16 v[4:7], v[216:219], v[208:211], v[4:7]
	v_mfma_f32_16x16x32_bf16 v[0:3], v[224:227], v[208:211], v[0:3]
	s_setprio 0
	s_add_u32 s85, s85, 0x100
	s_addc_u32 s86, s86, 0
	s_add_u32 s54, s54, 0x100
	s_addc_u32 s55, s55, 0
	s_cmp_ge_i32 s56, s75
	s_mov_b32 s6, s56
	s_barrier
	s_cbranch_scc0 .LBB0_982
	s_branch .LBB0_969
